# rowscale loads batched + cache-roll copy moved from epilogues into K-loop trips (1 store + 1 load per trip)
# speedup vs baseline: 1.0428x; 1.0428x over previous
.LBB0_128:
	s_or_b64 exec, exec, s[0:1]
	s_barrier
	s_load_dword s0, s[80:81], 0x90
	s_cmpk_lt_i32 s73, 0xc0
	s_cselect_b64 s[2:3], -1, 0
	s_mul_i32 s1, s77, s76
	v_writelane_b32 v255, s2, 4
	s_cmpk_lt_i32 s73, 0x100
	s_waitcnt lgkmcnt(0)
	s_mul_i32 s77, s1, s0
	v_writelane_b32 v255, s3, 5
	s_cselect_b64 s[0:1], -1, 0
	v_writelane_b32 v255, s0, 6
	s_cmp_lt_i32 s73, 64
	s_mov_b32 s85, 0
	v_writelane_b32 v255, s1, 7
	s_cselect_b64 s[0:1], -1, 0
	v_writelane_b32 v255, s0, 8
	s_mov_b64 s[12:13], -1
	s_movk_i32 s74, 0x61
	v_writelane_b32 v255, s1, 9
	s_lshl_b32 s0, s73, 1
	s_cmpk_lt_i32 s0, 0x200
	v_writelane_b32 v255, s0, 10
	s_cselect_b64 s[0:1], -1, 0
	v_writelane_b32 v255, s0, 11
	s_lshl_b32 s70, s76, 9
	s_lshl_b32 s71, s76, 12
	v_writelane_b32 v255, s1, 12
	s_lshl_b32 s0, s76, 1
	v_writelane_b32 v255, s0, 13
	s_and_b32 s0, s73, 7
	v_writelane_b32 v255, s0, 14
	s_and_b32 s0, s73, -8
	v_writelane_b32 v255, s0, 15
	s_lshl_b32 s0, s73, 5
	v_writelane_b32 v255, s0, 16
	s_lshl_b32 s0, s73, 12
	v_writelane_b32 v255, s0, 17
	s_add_i32 s0, 0, 0x27ff0
	v_writelane_b32 v255, s0, 18
	s_add_i32 s0, 0, 0x27ff4
	v_writelane_b32 v255, s0, 19
	s_add_i32 s0, 0, 0x12700
	v_writelane_b32 v255, s0, 20
	s_add_i32 s0, 0, 0x1ce0
	v_writelane_b32 v255, s0, 21
	s_add_i32 s0, 0, 0x3de0
	v_writelane_b32 v255, s0, 22
	v_writelane_b32 v255, s80, 23
	s_lshl_b32 s94, s76, 5
	s_movk_i32 s75, 0x2000
	v_writelane_b32 v255, s81, 24
	v_writelane_b32 v255, s68, 25
	v_mov_b32_e32 v189, 0
	s_mov_b64 s[86:87], 0x80000
	v_writelane_b32 v255, s69, 26
	v_writelane_b32 v255, s77, 27
	v_writelane_b32 v255, s70, 28
	v_writelane_b32 v255, s71, 29
	s_mov_b64 s[88:89], 0x80
	v_mov_b32_e32 v233, 0x358637bd
	s_mov_b32 s96, 0x800000
	s_movk_i32 s97, 0x7ff
	s_movk_i32 s82, 0x1000
	s_movk_i32 s83, 0x3ff
	v_mov_b32_e32 v241, 0x1000
	v_mov_b32_e32 v253, 0x2000
	v_mov_b32_e32 v242, 1
	s_movk_i32 s95, 0x210
	s_movk_i32 s72, 0xffd
	s_movk_i32 s78, 0xfff
	v_mov_b64_e32 v[190:191], 0xff
	v_mov_b64_e32 v[192:193], 0x100
	v_mbcnt_hi_u32_b32 v238, -1, v1
	v_mov_b32_e32 v239, 0xff800000
	s_mov_b64 s[92:93], 0x40000
	s_mov_b32 s30, s85
	v_writelane_b32 v255, s73, 30
	s_cmpk_lt_u32 s73, 0x80
	s_cselect_b32 s0, 32, 40
	s_mov_b32 s3, 0x8194000
	s_cselect_b32 s2, s3, 0x1c194000
	s_add_u32 s0, s80, s0
	s_addc_u32 s1, s81, 0
	s_load_dwordx2 s[98:99], s[0:1], 0x0
	s_load_dwordx2 s[100:101], s[80:81], 0x78
	s_lshl_b32 s0, s73, 21
	s_and_b32 s0, s0, 0xf000000
	s_and_b32 s1, s73, 7
	s_mul_i32 s1, s1, 0x1ff000
	s_add_u32 s0, s0, s1
	s_waitcnt lgkmcnt(0)
	s_add_u32 s98, s98, s0
	s_addc_u32 s99, s99, 0
	s_add_u32 s98, s98, 0x8000
	s_addc_u32 s99, s99, 0
	s_add_u32 s100, s100, s2
	s_addc_u32 s101, s101, 0
	s_add_u32 s100, s100, s0
	s_addc_u32 s101, s101, 0
	v_writelane_b32 v255, s98, 49
	v_writelane_b32 v255, s99, 50
	v_writelane_b32 v255, s100, 51
	v_writelane_b32 v255, s101, 52
	s_branch .LBB0_131

.LBB0_131:
	s_mov_b64 s[0:1], s[80:81]
	s_mov_b32 s31, s76
	s_mov_b32 s44, s73
	s_cmp_eq_u32 s31, s31
	s_mov_b64 s[18:19], 0
	s_mov_b64 s[16:17], 0
	s_cbranch_scc1 .LBB0_133
	s_and_b32 s4, s44, 7
	s_cmpk_lt_u32 s44, 0x80
	s_cselect_b32 s2, 32, 40
	s_mov_b32 s3, 0x8194000
	s_cselect_b32 s6, s3, 0x1c194000
	s_add_u32 s2, s0, s2
	s_addc_u32 s3, s1, 0
	s_load_dwordx2 s[2:3], s[2:3], 0x0
	s_lshl_b32 s5, s44, 21
	s_and_b32 s7, s5, 0xf000000
	s_mul_i32 s8, s4, 0x1ff000
	s_load_dwordx2 s[4:5], s[0:1], 0x78
	s_waitcnt lgkmcnt(0)
	s_add_u32 s2, s2, s7
	s_addc_u32 s3, s3, 0
	s_add_u32 s2, s2, s8
	s_addc_u32 s3, s3, 0
	s_add_u32 s16, s2, 0x8000
	s_addc_u32 s17, s3, 0
	s_add_u32 s2, s4, s6
	s_addc_u32 s3, s5, 0
	s_add_u32 s2, s2, s7
	s_addc_u32 s3, s3, 0
	s_add_u32 s18, s2, s8
	s_addc_u32 s19, s3, 0

.LBB0_142:
	v_mov_b64_e32 v[0:1], 0x300
	s_ashr_i32 s37, s36, 31
	v_cmp_lt_i64_e32 vcc, s[0:1], v[0:1]
	s_lshl_b64 s[0:1], s[36:37], 20
	s_add_u32 s38, s14, s0
	s_addc_u32 s39, s15, s1
	s_and_b64 s[0:1], vcc, exec
	s_cselect_b32 s0, s39, s11
	s_cselect_b32 s1, s38, s10
	s_ashr_i32 s29, s28, 31
	s_lshl_b64 s[40:41], s[28:29], 20
	s_add_u32 s40, s22, s40
	s_addc_u32 s41, s23, s41
	s_and_b64 s[42:43], vcc, exec
	s_cselect_b32 s7, s41, s3
	s_cselect_b32 s9, s40, s2
	s_add_u32 s29, s2, 0x100
	s_addc_u32 s33, s3, 0
	s_add_u32 s10, s10, 0x80080
	v_mov_b32_e32 v0, 0
	s_addc_u32 s11, s11, 0
	s_mov_b32 s37, -2
	v_mov_b32_e32 v1, v0
	v_mov_b32_e32 v2, v0
	v_mov_b32_e32 v3, v0
	v_mov_b32_e32 v4, v0
	v_mov_b32_e32 v5, v0
	v_mov_b32_e32 v6, v0
	v_mov_b32_e32 v7, v0
	v_mov_b32_e32 v44, v0
	v_mov_b32_e32 v45, v0
	v_mov_b32_e32 v46, v0
	v_mov_b32_e32 v47, v0
	s_waitcnt vmcnt(0)
	v_mov_b32_e32 v48, v0
	v_mov_b32_e32 v49, v0
	v_mov_b32_e32 v50, v0
	v_mov_b32_e32 v51, v0
	v_mov_b32_e32 v60, v0
	v_mov_b32_e32 v61, v0
	v_mov_b32_e32 v62, v0
	v_mov_b32_e32 v63, v0
	v_mov_b32_e32 v64, v0
	v_mov_b32_e32 v65, v0
	v_mov_b32_e32 v66, v0
	v_mov_b32_e32 v67, v0
	v_mov_b32_e32 v76, v0
	v_mov_b32_e32 v77, v0
	v_mov_b32_e32 v78, v0
	v_mov_b32_e32 v79, v0
	v_mov_b32_e32 v80, v0
	v_mov_b32_e32 v81, v0
	v_mov_b32_e32 v82, v0
	v_mov_b32_e32 v83, v0
	v_mov_b32_e32 v8, v0
	v_mov_b32_e32 v9, v0
	v_mov_b32_e32 v10, v0
	v_mov_b32_e32 v11, v0
	v_mov_b32_e32 v16, v0
	v_mov_b32_e32 v17, v0
	v_mov_b32_e32 v18, v0
	v_mov_b32_e32 v19, v0
	v_mov_b32_e32 v52, v0
	v_mov_b32_e32 v53, v0
	v_mov_b32_e32 v54, v0
	v_mov_b32_e32 v55, v0
	v_mov_b32_e32 v56, v0
	v_mov_b32_e32 v57, v0
	v_mov_b32_e32 v58, v0
	v_mov_b32_e32 v59, v0
	v_mov_b32_e32 v68, v0
	v_mov_b32_e32 v69, v0
	v_mov_b32_e32 v70, v0
	v_mov_b32_e32 v71, v0
	v_mov_b32_e32 v72, v0
	v_mov_b32_e32 v73, v0
	v_mov_b32_e32 v74, v0
	v_mov_b32_e32 v75, v0
	v_mov_b32_e32 v84, v0
	v_mov_b32_e32 v85, v0
	v_mov_b32_e32 v86, v0
	v_mov_b32_e32 v87, v0
	v_mov_b32_e32 v88, v0
	v_mov_b32_e32 v89, v0
	v_mov_b32_e32 v90, v0
	v_mov_b32_e32 v91, v0
	v_mov_b32_e32 v92, v0
	v_mov_b32_e32 v93, v0
	v_mov_b32_e32 v94, v0
	v_mov_b32_e32 v95, v0
	v_mov_b32_e32 v96, v0
	v_mov_b32_e32 v97, v0
	v_mov_b32_e32 v98, v0
	v_mov_b32_e32 v99, v0
	v_mov_b32_e32 v112, v0
	v_mov_b32_e32 v113, v0
	v_mov_b32_e32 v114, v0
	v_mov_b32_e32 v115, v0
	v_mov_b32_e32 v116, v0
	v_mov_b32_e32 v117, v0
	v_mov_b32_e32 v118, v0
	v_mov_b32_e32 v119, v0
	v_mov_b32_e32 v128, v0
	v_mov_b32_e32 v129, v0
	v_mov_b32_e32 v130, v0
	v_mov_b32_e32 v131, v0
	v_mov_b32_e32 v132, v0
	v_mov_b32_e32 v133, v0
	v_mov_b32_e32 v134, v0
	v_mov_b32_e32 v135, v0
	v_mov_b32_e32 v144, v0
	v_mov_b32_e32 v145, v0
	v_mov_b32_e32 v146, v0
	v_mov_b32_e32 v147, v0
	v_mov_b32_e32 v148, v0
	v_mov_b32_e32 v149, v0
	v_mov_b32_e32 v150, v0
	v_mov_b32_e32 v151, v0
	v_mov_b32_e32 v104, v0
	v_mov_b32_e32 v105, v0
	v_mov_b32_e32 v106, v0
	v_mov_b32_e32 v107, v0
	v_mov_b32_e32 v108, v0
	v_mov_b32_e32 v109, v0
	v_mov_b32_e32 v110, v0
	v_mov_b32_e32 v111, v0
	v_mov_b32_e32 v120, v0
	v_mov_b32_e32 v121, v0
	v_mov_b32_e32 v122, v0
	v_mov_b32_e32 v123, v0
	v_mov_b32_e32 v124, v0
	v_mov_b32_e32 v125, v0
	v_mov_b32_e32 v126, v0
	v_mov_b32_e32 v127, v0
	v_mov_b32_e32 v136, v0
	v_mov_b32_e32 v137, v0
	v_mov_b32_e32 v138, v0
	v_mov_b32_e32 v139, v0
	v_mov_b32_e32 v140, v0
	v_mov_b32_e32 v141, v0
	v_mov_b32_e32 v142, v0
	v_mov_b32_e32 v143, v0
	v_mov_b32_e32 v152, v0
	v_mov_b32_e32 v153, v0
	v_mov_b32_e32 v154, v0
	v_mov_b32_e32 v155, v0
	v_mov_b32_e32 v156, v0
	v_mov_b32_e32 v157, v0
	v_mov_b32_e32 v158, v0
	v_mov_b32_e32 v159, v0
	s_mul_i32 s100, s56, 0x1e00
	v_add_u32_e32 v246, s100, v232
	v_readlane_b32 s98, v255, 49
	v_readlane_b32 s99, v255, 50
	v_readlane_b32 s100, v255, 51
	v_readlane_b32 s101, v255, 52
.LBB0_143:
	s_cmp_eq_u32 s37, -2
	s_cbranch_scc1 .Lkcp_skip_143
	global_store_dwordx4 v247, v[248:251], s[100:101] nt
.Lkcp_skip_143:
	s_add_u32 s2, s10, 0xfff80080
	s_addc_u32 s3, s11, -1
	s_add_i32 s57, 0, 0x10000
	v_add_u32_e32 v28, s57, v217
	ds_read_b128 v[12:15], v28
	ds_read_b128 v[20:23], v28 offset:1024
	ds_read_b128 v[24:27], v28 offset:2048
	ds_read_b128 v[28:31], v28 offset:3072
	s_cmp_eq_u32 s37, 28
	s_cselect_b32 s43, s0, s3
	s_cselect_b32 s42, s1, s2
	s_cselect_b32 s3, s7, s33
	s_cselect_b32 s2, s9, s29
	v_lshl_add_u64 v[194:195], s[10:11], 0, v[170:171]
	s_add_i32 m0, s47, 0xc000
	ds_read_b128 v[32:35], v220
	ds_read_b128 v[36:39], v220 offset:1024
	ds_read_b128 v[40:43], v220 offset:2048
	ds_read_b128 v[100:103], v220 offset:3072
	ds_read_b128 v[172:175], v220 offset:4096
	ds_read_b128 v[176:179], v220 offset:5120
	ds_read_b128 v[180:183], v220 offset:6144
	ds_read_b128 v[184:187], v220 offset:7168
	global_load_lds_dwordx4 v[194:195], off
	v_lshl_add_u64 v[194:195], s[10:11], 0, v[168:169]
	s_add_i32 m0, s47, 0xe000
	s_nop 0
	global_load_lds_dwordx4 v[194:195], off
	s_waitcnt lgkmcnt(8)
	s_barrier
	s_waitcnt lgkmcnt(0)
	s_setprio 1
	s_waitcnt lgkmcnt(0)
	v_mfma_f32_16x16x32_bf16 v[156:159], v[12:15], v[32:35], v[156:159]
	v_mfma_f32_16x16x32_bf16 v[152:155], v[24:27], v[32:35], v[152:155]
	v_mfma_f32_16x16x32_bf16 v[140:143], v[12:15], v[40:43], v[140:143]
	v_mfma_f32_16x16x32_bf16 v[136:139], v[24:27], v[40:43], v[136:139]
	v_mfma_f32_16x16x32_bf16 v[124:127], v[12:15], v[172:175], v[124:127]
	v_mfma_f32_16x16x32_bf16 v[120:123], v[24:27], v[172:175], v[120:123]
	v_mfma_f32_16x16x32_bf16 v[108:111], v[12:15], v[180:183], v[108:111]
	v_mfma_f32_16x16x32_bf16 v[104:107], v[24:27], v[180:183], v[104:107]
	v_mfma_f32_16x16x32_bf16 v[156:159], v[20:23], v[36:39], v[156:159]
	v_mfma_f32_16x16x32_bf16 v[152:155], v[28:31], v[36:39], v[152:155]
	v_mfma_f32_16x16x32_bf16 v[140:143], v[20:23], v[100:103], v[140:143]
	v_mfma_f32_16x16x32_bf16 v[136:139], v[28:31], v[100:103], v[136:139]
	v_mfma_f32_16x16x32_bf16 v[124:127], v[20:23], v[176:179], v[124:127]
	v_mfma_f32_16x16x32_bf16 v[120:123], v[28:31], v[176:179], v[120:123]
	v_mfma_f32_16x16x32_bf16 v[108:111], v[20:23], v[184:187], v[108:111]
	v_mfma_f32_16x16x32_bf16 v[104:107], v[28:31], v[184:187], v[104:107]
	s_setprio 0
	s_barrier
	s_add_i32 s60, 0, 0x14000
	s_add_i32 s57, s57, s46
	v_add_u32_e32 v188, s60, v217
	v_lshl_add_u64 v[214:215], s[2:3], 0, v[162:163]
	s_mov_b32 m0, s57
	ds_read_b128 v[194:197], v188
	ds_read_b128 v[198:201], v188 offset:1024
	ds_read_b128 v[202:205], v188 offset:2048
	ds_read_b128 v[206:209], v188 offset:3072
	global_load_lds_dwordx4 v[214:215], off
	v_lshl_add_u64 v[226:227], s[2:3], 0, v[166:167]
	s_add_i32 m0, s57, 0x2000
	s_nop 0
	global_load_lds_dwordx4 v[226:227], off
	v_min_u32_e32 v247, 0x1feff, v246
	v_lshlrev_b32_e32 v247, 4, v247
	v_add_u32_e32 v246, 0x200, v246
	global_load_dwordx4 v[248:251], v247, s[98:99] nt
	s_barrier
	s_waitcnt lgkmcnt(0)
	s_setprio 1
	s_waitcnt lgkmcnt(0)
	v_mfma_f32_16x16x32_bf16 v[148:151], v[194:197], v[32:35], v[148:151]
	v_mfma_f32_16x16x32_bf16 v[32:35], v[202:205], v[32:35], v[144:147]
	v_mfma_f32_16x16x32_bf16 v[148:151], v[198:201], v[36:39], v[148:151]
	v_mfma_f32_16x16x32_bf16 v[32:35], v[206:209], v[36:39], v[32:35]
	v_mfma_f32_16x16x32_bf16 v[36:39], v[194:197], v[40:43], v[132:135]
	v_mfma_f32_16x16x32_bf16 v[40:43], v[202:205], v[40:43], v[128:131]
	v_mfma_f32_16x16x32_bf16 v[112:115], v[202:205], v[172:175], v[112:115]
	v_mfma_f32_16x16x32_bf16 v[96:99], v[194:197], v[180:183], v[96:99]
	v_mfma_f32_16x16x32_bf16 v[92:95], v[202:205], v[180:183], v[92:95]
	v_mfma_f32_16x16x32_bf16 v[36:39], v[198:201], v[100:103], v[36:39]
	v_mfma_f32_16x16x32_bf16 v[40:43], v[206:209], v[100:103], v[40:43]
	v_mfma_f32_16x16x32_bf16 v[100:103], v[194:197], v[172:175], v[116:119]
	v_mfma_f32_16x16x32_bf16 v[112:115], v[206:209], v[176:179], v[112:115]
	v_mfma_f32_16x16x32_bf16 v[96:99], v[198:201], v[184:187], v[96:99]
	v_mfma_f32_16x16x32_bf16 v[92:95], v[206:209], v[184:187], v[92:95]
	v_mfma_f32_16x16x32_bf16 v[100:103], v[198:201], v[176:179], v[100:103]
	s_setprio 0
	s_mov_b32 m0, s47
	v_lshl_add_u64 v[228:229], s[42:43], 0, v[160:161]
	s_barrier
	ds_read_b128 v[116:119], v220 offset:16384
	ds_read_b128 v[128:131], v220 offset:17408
	ds_read_b128 v[132:135], v220 offset:18432
	ds_read_b128 v[144:147], v220 offset:19456
	ds_read_b128 v[172:175], v220 offset:20480
	ds_read_b128 v[176:179], v220 offset:21504
	ds_read_b128 v[180:183], v220 offset:22528
	ds_read_b128 v[184:187], v220 offset:23552
	global_load_lds_dwordx4 v[228:229], off
	v_lshl_add_u64 v[230:231], s[42:43], 0, v[164:165]
	s_mov_b32 m0, s48
	s_nop 0
	global_load_lds_dwordx4 v[230:231], off
	s_barrier
	s_waitcnt lgkmcnt(0)
	s_setprio 1
	s_waitcnt lgkmcnt(0)
	v_mfma_f32_16x16x32_bf16 v[88:91], v[12:15], v[116:119], v[88:91]
	v_mfma_f32_16x16x32_bf16 v[84:87], v[24:27], v[116:119], v[84:87]
	v_mfma_f32_16x16x32_bf16 v[72:75], v[12:15], v[132:135], v[72:75]
	v_mfma_f32_16x16x32_bf16 v[68:71], v[24:27], v[132:135], v[68:71]
	v_mfma_f32_16x16x32_bf16 v[56:59], v[12:15], v[172:175], v[56:59]
	v_mfma_f32_16x16x32_bf16 v[52:55], v[24:27], v[172:175], v[52:55]
	v_mfma_f32_16x16x32_bf16 v[8:11], v[24:27], v[180:183], v[8:11]
	v_mfma_f32_16x16x32_bf16 v[88:91], v[20:23], v[128:131], v[88:91]
	v_mfma_f32_16x16x32_bf16 v[84:87], v[28:31], v[128:131], v[84:87]
	v_mfma_f32_16x16x32_bf16 v[72:75], v[20:23], v[144:147], v[72:75]
	v_mfma_f32_16x16x32_bf16 v[68:71], v[28:31], v[144:147], v[68:71]
	v_mfma_f32_16x16x32_bf16 v[56:59], v[20:23], v[176:179], v[56:59]
	v_mfma_f32_16x16x32_bf16 v[52:55], v[28:31], v[176:179], v[52:55]
	v_mfma_f32_16x16x32_bf16 v[12:15], v[12:15], v[180:183], v[16:19]
	v_mfma_f32_16x16x32_bf16 v[8:11], v[28:31], v[184:187], v[8:11]
	v_mfma_f32_16x16x32_bf16 v[12:15], v[20:23], v[184:187], v[12:15]
	s_setprio 0
	s_barrier
	s_add_u32 s58, s2, 0x80000
	s_addc_u32 s59, s3, 0
	s_add_i32 s57, s60, s46
	v_lshl_add_u64 v[16:17], s[58:59], 0, v[162:163]
	s_mov_b32 m0, s57
	s_nop 0
	global_load_lds_dwordx4 v[16:17], off
	v_lshl_add_u64 v[16:17], s[58:59], 0, v[166:167]
	s_add_i32 m0, s57, 0x2000
	s_nop 0
	global_load_lds_dwordx4 v[16:17], off
	s_waitcnt vmcnt(7)
	s_barrier
	s_setprio 1
	v_mfma_f32_16x16x32_bf16 v[16:19], v[194:197], v[116:119], v[80:83]
	v_mfma_f32_16x16x32_bf16 v[20:23], v[198:201], v[128:131], v[16:19]
	v_mfma_f32_16x16x32_bf16 v[16:19], v[202:205], v[116:119], v[76:79]
	v_mfma_f32_16x16x32_bf16 v[24:27], v[206:209], v[128:131], v[16:19]
	v_mfma_f32_16x16x32_bf16 v[16:19], v[194:197], v[132:135], v[64:67]
	v_mfma_f32_16x16x32_bf16 v[28:31], v[198:201], v[144:147], v[16:19]
	v_mfma_f32_16x16x32_bf16 v[16:19], v[202:205], v[132:135], v[60:63]
	v_mfma_f32_16x16x32_bf16 v[60:63], v[206:209], v[144:147], v[16:19]
	v_mfma_f32_16x16x32_bf16 v[16:19], v[194:197], v[172:175], v[48:51]
	v_mfma_f32_16x16x32_bf16 v[48:51], v[198:201], v[176:179], v[16:19]
	v_mfma_f32_16x16x32_bf16 v[16:19], v[202:205], v[172:175], v[44:47]
	v_mfma_f32_16x16x32_bf16 v[4:7], v[194:197], v[180:183], v[4:7]
	v_mfma_f32_16x16x32_bf16 v[0:3], v[202:205], v[180:183], v[0:3]
	v_mfma_f32_16x16x32_bf16 v[44:47], v[206:209], v[176:179], v[16:19]
	v_mfma_f32_16x16x32_bf16 v[4:7], v[198:201], v[184:187], v[4:7]
	v_mfma_f32_16x16x32_bf16 v[0:3], v[206:209], v[184:187], v[0:3]
	s_setprio 0
	s_add_i32 s57, 0, 0x18000
	v_add_u32_e32 v80, s57, v217
	s_barrier
	ds_read_b128 v[16:19], v80
	ds_read_b128 v[64:67], v80 offset:1024
	ds_read_b128 v[76:79], v80 offset:2048
	ds_read_b128 v[80:83], v80 offset:3072
	s_add_u32 s42, s42, 0x80000
	s_addc_u32 s43, s43, 0
	s_mov_b32 m0, s49
	v_lshl_add_u64 v[132:133], s[42:43], 0, v[160:161]
	ds_read_b128 v[116:119], v220 offset:32768
	ds_read_b128 v[128:131], v220 offset:33792
	ds_read_b128 v[172:175], v220 offset:34816
	ds_read_b128 v[176:179], v220 offset:35840
	ds_read_b128 v[180:183], v220 offset:36864
	ds_read_b128 v[184:187], v220 offset:37888
	ds_read_b128 v[194:197], v220 offset:38912
	ds_read_b128 v[198:201], v220 offset:39936
	global_load_lds_dwordx4 v[132:133], off
	v_lshl_add_u64 v[132:133], s[42:43], 0, v[164:165]
	s_mov_b32 m0, s50
	s_nop 0
	global_load_lds_dwordx4 v[132:133], off
	s_waitcnt lgkmcnt(8)
	s_barrier
	s_waitcnt lgkmcnt(0)
	s_setprio 1
	s_waitcnt lgkmcnt(0)
	v_mfma_f32_16x16x32_bf16 v[132:135], v[16:19], v[116:119], v[156:159]
	v_mfma_f32_16x16x32_bf16 v[156:159], v[64:67], v[128:131], v[132:135]
	v_mfma_f32_16x16x32_bf16 v[132:135], v[76:79], v[116:119], v[152:155]
	v_mfma_f32_16x16x32_bf16 v[152:155], v[80:83], v[128:131], v[132:135]
	v_mfma_f32_16x16x32_bf16 v[132:135], v[16:19], v[172:175], v[140:143]
	v_mfma_f32_16x16x32_bf16 v[140:143], v[64:67], v[176:179], v[132:135]
	v_mfma_f32_16x16x32_bf16 v[132:135], v[76:79], v[172:175], v[136:139]
	v_mfma_f32_16x16x32_bf16 v[124:127], v[16:19], v[180:183], v[124:127]
	v_mfma_f32_16x16x32_bf16 v[120:123], v[76:79], v[180:183], v[120:123]
	v_mfma_f32_16x16x32_bf16 v[108:111], v[16:19], v[194:197], v[108:111]
	v_mfma_f32_16x16x32_bf16 v[104:107], v[76:79], v[194:197], v[104:107]
	v_mfma_f32_16x16x32_bf16 v[136:139], v[80:83], v[176:179], v[132:135]
	v_mfma_f32_16x16x32_bf16 v[124:127], v[64:67], v[184:187], v[124:127]
	v_mfma_f32_16x16x32_bf16 v[120:123], v[80:83], v[184:187], v[120:123]
	v_mfma_f32_16x16x32_bf16 v[108:111], v[64:67], v[198:201], v[108:111]
	v_mfma_f32_16x16x32_bf16 v[104:107], v[80:83], v[198:201], v[104:107]
	s_setprio 0
	s_barrier
	s_add_i32 s42, 0, 0x1c000
	v_add_u32_e32 v132, s42, v217
	s_add_i32 s43, s57, s46
	ds_read_b128 v[202:205], v132
	ds_read_b128 v[206:209], v132 offset:1024
	ds_read_b128 v[210:213], v132 offset:2048
	ds_read_b128 v[222:225], v132 offset:3072
	v_lshl_add_u64 v[132:133], v[214:215], 0, s[88:89]
	s_mov_b32 m0, s43
	s_nop 0
	global_load_lds_dwordx4 v[132:133], off
	v_lshl_add_u64 v[132:133], v[226:227], 0, s[88:89]
	s_add_i32 m0, s43, 0x2000
	s_nop 0
	global_load_lds_dwordx4 v[132:133], off
	s_barrier
	s_waitcnt lgkmcnt(0)
	s_setprio 1
	s_waitcnt lgkmcnt(0)
	v_mfma_f32_16x16x32_bf16 v[32:35], v[210:213], v[116:119], v[32:35]
	v_mfma_f32_16x16x32_bf16 v[132:135], v[202:205], v[116:119], v[148:151]
	v_mfma_f32_16x16x32_bf16 v[144:147], v[222:225], v[128:131], v[32:35]
	v_mfma_f32_16x16x32_bf16 v[32:35], v[202:205], v[172:175], v[36:39]
	v_mfma_f32_16x16x32_bf16 v[148:151], v[206:209], v[128:131], v[132:135]
	v_mfma_f32_16x16x32_bf16 v[132:135], v[206:209], v[176:179], v[32:35]
	v_mfma_f32_16x16x32_bf16 v[32:35], v[210:213], v[172:175], v[40:43]
	v_mfma_f32_16x16x32_bf16 v[128:131], v[222:225], v[176:179], v[32:35]
	v_mfma_f32_16x16x32_bf16 v[32:35], v[202:205], v[180:183], v[100:103]
	v_mfma_f32_16x16x32_bf16 v[116:119], v[206:209], v[184:187], v[32:35]
	v_mfma_f32_16x16x32_bf16 v[32:35], v[210:213], v[180:183], v[112:115]
	v_mfma_f32_16x16x32_bf16 v[112:115], v[222:225], v[184:187], v[32:35]
	v_mfma_f32_16x16x32_bf16 v[32:35], v[202:205], v[194:197], v[96:99]
	v_mfma_f32_16x16x32_bf16 v[96:99], v[206:209], v[198:201], v[32:35]
	v_mfma_f32_16x16x32_bf16 v[32:35], v[210:213], v[194:197], v[92:95]
	v_mfma_f32_16x16x32_bf16 v[92:95], v[222:225], v[198:201], v[32:35]
	s_setprio 0
	s_mov_b32 m0, s51
	v_lshl_add_u64 v[194:195], v[228:229], 0, s[88:89]
	s_barrier
	s_nop 2
	ds_read_b128 v[32:35], v220 offset:49152
	ds_read_b128 v[36:39], v220 offset:50176
	ds_read_b128 v[40:43], v220 offset:51200
	ds_read_b128 v[100:103], v220 offset:52224
	ds_read_b128 v[172:175], v220 offset:53248
	ds_read_b128 v[176:179], v220 offset:54272
	ds_read_b128 v[180:183], v220 offset:55296
	ds_read_b128 v[184:187], v220 offset:56320
	global_load_lds_dwordx4 v[194:195], off
	v_lshl_add_u64 v[194:195], v[230:231], 0, s[88:89]
	s_mov_b32 m0, s52
	s_nop 0
	global_load_lds_dwordx4 v[194:195], off
	s_barrier
	s_waitcnt lgkmcnt(0)
	s_setprio 1
	s_waitcnt lgkmcnt(0)
	v_mfma_f32_16x16x32_bf16 v[88:91], v[16:19], v[32:35], v[88:91]
	v_mfma_f32_16x16x32_bf16 v[84:87], v[76:79], v[32:35], v[84:87]
	v_mfma_f32_16x16x32_bf16 v[72:75], v[16:19], v[40:43], v[72:75]
	v_mfma_f32_16x16x32_bf16 v[68:71], v[76:79], v[40:43], v[68:71]
	v_mfma_f32_16x16x32_bf16 v[56:59], v[16:19], v[172:175], v[56:59]
	v_mfma_f32_16x16x32_bf16 v[52:55], v[76:79], v[172:175], v[52:55]
	v_mfma_f32_16x16x32_bf16 v[12:15], v[16:19], v[180:183], v[12:15]
	v_mfma_f32_16x16x32_bf16 v[8:11], v[76:79], v[180:183], v[8:11]
	v_mfma_f32_16x16x32_bf16 v[88:91], v[64:67], v[36:39], v[88:91]
	v_mfma_f32_16x16x32_bf16 v[84:87], v[80:83], v[36:39], v[84:87]
	v_mfma_f32_16x16x32_bf16 v[72:75], v[64:67], v[100:103], v[72:75]
	v_mfma_f32_16x16x32_bf16 v[68:71], v[80:83], v[100:103], v[68:71]
	v_mfma_f32_16x16x32_bf16 v[56:59], v[64:67], v[176:179], v[56:59]
	v_mfma_f32_16x16x32_bf16 v[52:55], v[80:83], v[176:179], v[52:55]
	v_mfma_f32_16x16x32_bf16 v[16:19], v[64:67], v[184:187], v[12:15]
	v_mfma_f32_16x16x32_bf16 v[8:11], v[80:83], v[184:187], v[8:11]
	s_setprio 0
	s_barrier
	s_add_u32 s2, s2, 0x80080
	s_addc_u32 s3, s3, 0
	s_add_i32 s42, s42, s46
	v_lshl_add_u64 v[12:13], s[2:3], 0, v[162:163]
	s_mov_b32 m0, s42
	s_nop 0
	global_load_lds_dwordx4 v[12:13], off
	v_lshl_add_u64 v[12:13], s[2:3], 0, v[166:167]
	s_add_i32 m0, s42, 0x2000
	s_nop 0
	global_load_lds_dwordx4 v[12:13], off
	s_waitcnt vmcnt(6)
	s_barrier
	s_setprio 1
	v_mfma_f32_16x16x32_bf16 v[12:15], v[202:205], v[32:35], v[20:23]
	v_mfma_f32_16x16x32_bf16 v[80:83], v[206:209], v[36:39], v[12:15]
	v_mfma_f32_16x16x32_bf16 v[12:15], v[210:213], v[32:35], v[24:27]
	v_mfma_f32_16x16x32_bf16 v[76:79], v[222:225], v[36:39], v[12:15]
	v_mfma_f32_16x16x32_bf16 v[12:15], v[202:205], v[40:43], v[28:31]
	v_mfma_f32_16x16x32_bf16 v[64:67], v[206:209], v[100:103], v[12:15]
	v_mfma_f32_16x16x32_bf16 v[12:15], v[210:213], v[40:43], v[60:63]
	v_mfma_f32_16x16x32_bf16 v[60:63], v[222:225], v[100:103], v[12:15]
	v_mfma_f32_16x16x32_bf16 v[12:15], v[202:205], v[172:175], v[48:51]
	v_mfma_f32_16x16x32_bf16 v[48:51], v[206:209], v[176:179], v[12:15]
	v_mfma_f32_16x16x32_bf16 v[12:15], v[210:213], v[172:175], v[44:47]
	v_mfma_f32_16x16x32_bf16 v[4:7], v[202:205], v[180:183], v[4:7]
	v_mfma_f32_16x16x32_bf16 v[0:3], v[210:213], v[180:183], v[0:3]
	v_mfma_f32_16x16x32_bf16 v[44:47], v[222:225], v[176:179], v[12:15]
	v_mfma_f32_16x16x32_bf16 v[4:7], v[206:209], v[184:187], v[4:7]
	v_mfma_f32_16x16x32_bf16 v[0:3], v[222:225], v[184:187], v[0:3]
	s_setprio 0
	s_add_i32 s37, s37, 2
	s_add_u32 s29, s29, 0x100
	s_addc_u32 s33, s33, 0
	s_add_u32 s10, s10, 0x100
	s_addc_u32 s11, s11, 0
	s_cmp_gt_u32 s37, 29
	s_barrier
	s_cbranch_scc0 .LBB0_143
	v_lshl_add_u32 v176, s6, 8, v216
	v_ashrrev_i32_e32 v177, 31, v176
	v_lshl_add_u64 v[12:13], v[176:177], 2, s[24:25]
	global_load_dword v212, v[12:13], off
	global_load_dword v210, v[12:13], off offset:64
	global_load_dword v208, v[12:13], off offset:128
	global_load_dword v206, v[12:13], off offset:192
	global_load_dword v182, v[12:13], off offset:512
	global_load_dword v180, v[12:13], off offset:576
	global_load_dword v178, v[12:13], off offset:640
	global_load_dword v172, v[12:13], off offset:704
	s_mul_i32 s0, s56, 0x1e00
	v_add_u32_e32 v173, s0, v219
	v_min_i32_e32 v204, 0x1feff, v173
	v_min_i32_e32 v202, 0x1fcff, v173
	v_min_i32_e32 v200, 0x1faff, v173
	v_min_i32_e32 v198, 0x1f8ff, v173
	v_min_i32_e32 v196, 0x1f6ff, v173
	v_min_i32_e32 v194, 0x1f4ff, v173
	v_min_i32_e32 v186, 0x1f2ff, v173
	v_min_i32_e32 v184, 0x1f0ff, v173
	v_ashrrev_i32_e32 v205, 31, v204
	v_ashrrev_i32_e32 v203, 31, v202
	v_ashrrev_i32_e32 v201, 31, v200
	v_ashrrev_i32_e32 v199, 31, v198
	v_ashrrev_i32_e32 v197, 31, v196
	v_ashrrev_i32_e32 v195, 31, v194
	v_ashrrev_i32_e32 v187, 31, v186
	v_ashrrev_i32_e32 v185, 31, v184
	s_waitcnt vmcnt(0)
	v_fmamk_f32 v14, v212, 0x3a000000, v233
	v_cmp_gt_f32_e32 vcc, s96, v14
	v_mul_f32_e32 v15, 0x4b800000, v14
	s_nop 0
	v_cndmask_b32_e32 v14, v14, v15, vcc
	v_rsq_f32_e32 v14, v14
	s_nop 0
	v_mul_f32_e32 v15, 0x45800000, v14
	v_cndmask_b32_e32 v212, v14, v15, vcc
	v_fmamk_f32 v14, v210, 0x3a000000, v233
	v_cmp_gt_f32_e32 vcc, s96, v14
	v_mul_f32_e32 v15, 0x4b800000, v14
	s_nop 0
	v_cndmask_b32_e32 v14, v14, v15, vcc
	v_rsq_f32_e32 v14, v14
	s_nop 0
	v_mul_f32_e32 v15, 0x45800000, v14
	v_cndmask_b32_e32 v210, v14, v15, vcc
	v_fmamk_f32 v14, v208, 0x3a000000, v233
	v_cmp_gt_f32_e32 vcc, s96, v14
	v_mul_f32_e32 v15, 0x4b800000, v14
	s_nop 0
	v_cndmask_b32_e32 v14, v14, v15, vcc
	v_rsq_f32_e32 v14, v14
	s_nop 0
	v_mul_f32_e32 v15, 0x45800000, v14
	v_cndmask_b32_e32 v208, v14, v15, vcc
	v_fmamk_f32 v14, v206, 0x3a000000, v233
	v_cmp_gt_f32_e32 vcc, s96, v14
	v_mul_f32_e32 v15, 0x4b800000, v14
	s_nop 0
	v_cndmask_b32_e32 v14, v14, v15, vcc
	v_rsq_f32_e32 v14, v14
	s_nop 0
	v_mul_f32_e32 v15, 0x45800000, v14
	v_cndmask_b32_e32 v206, v14, v15, vcc
	v_fmamk_f32 v14, v182, 0x3a000000, v233
	v_cmp_gt_f32_e32 vcc, s96, v14
	v_mul_f32_e32 v15, 0x4b800000, v14
	s_nop 0
	v_cndmask_b32_e32 v14, v14, v15, vcc
	v_rsq_f32_e32 v14, v14
	s_nop 0
	v_mul_f32_e32 v15, 0x45800000, v14
	v_cndmask_b32_e32 v182, v14, v15, vcc
	v_fmamk_f32 v14, v180, 0x3a000000, v233
	v_cmp_gt_f32_e32 vcc, s96, v14
	v_mul_f32_e32 v15, 0x4b800000, v14
	s_nop 0
	v_cndmask_b32_e32 v14, v14, v15, vcc
	v_rsq_f32_e32 v14, v14
	s_nop 0
	v_mul_f32_e32 v15, 0x45800000, v14
	v_cndmask_b32_e32 v180, v14, v15, vcc
	v_fmamk_f32 v14, v178, 0x3a000000, v233
	v_cmp_gt_f32_e32 vcc, s96, v14
	v_mul_f32_e32 v15, 0x4b800000, v14
	s_nop 0
	v_cndmask_b32_e32 v14, v14, v15, vcc
	v_rsq_f32_e32 v14, v14
	s_nop 0
	v_mul_f32_e32 v15, 0x45800000, v14
	v_cndmask_b32_e32 v178, v14, v15, vcc
	v_fmamk_f32 v14, v172, 0x3a000000, v233
	v_cmp_gt_f32_e32 vcc, s96, v14
	v_mul_f32_e32 v15, 0x4b800000, v14
	s_nop 0
	v_cndmask_b32_e32 v14, v14, v15, vcc
	v_rsq_f32_e32 v14, v14
	s_nop 0
	v_mul_f32_e32 v15, 0x45800000, v14
	v_cndmask_b32_e32 v172, v14, v15, vcc
	v_cndmask_b32_e64 v12, 0, 1, s[26:27]
	v_cmp_ne_u32_e64 s[6:7], 1, v12
	s_andn2_b64 vcc, exec, s[26:27]
	s_cbranch_vccnz .LBB0_146
	v_lshl_add_u64 v[14:15], v[202:203], 4, s[16:17]
	v_lshl_add_u64 v[12:13], v[204:205], 4, s[16:17]
	v_add_co_u32_e32 v14, vcc, 0x2000, v14
	v_lshl_add_u64 v[20:21], v[186:187], 4, s[16:17]
	s_nop 0
	v_addc_co_u32_e32 v15, vcc, 0, v15, vcc
	global_load_dwordx4 v[40:43], v[12:13], off nt
	global_load_dwordx4 v[28:31], v[14:15], off nt
	v_lshl_add_u64 v[12:13], v[200:201], 4, s[16:17]
	v_add_co_u32_e32 v12, vcc, 0x4000, v12
	v_lshl_add_u64 v[14:15], v[198:199], 4, s[16:17]
	s_nop 0
	v_addc_co_u32_e32 v13, vcc, 0, v13, vcc
	v_add_co_u32_e32 v14, vcc, 0x6000, v14
	v_lshl_add_u64 v[22:23], v[184:185], 4, s[16:17]
	s_nop 0
	v_addc_co_u32_e32 v15, vcc, 0, v15, vcc
	global_load_dwordx4 v[36:39], v[12:13], off nt
	global_load_dwordx4 v[24:27], v[14:15], off nt
	v_lshl_add_u64 v[12:13], v[196:197], 4, s[16:17]
	v_add_co_u32_e32 v12, vcc, 0x8000, v12
	v_lshl_add_u64 v[14:15], v[194:195], 4, s[16:17]
	s_nop 0
	v_addc_co_u32_e32 v13, vcc, 0, v13, vcc
	v_add_co_u32_e32 v14, vcc, 0xa000, v14
	s_nop 1
	v_addc_co_u32_e32 v15, vcc, 0, v15, vcc
	v_add_co_u32_e32 v20, vcc, 0xc000, v20
	global_load_dwordx4 v[32:35], v[12:13], off nt
	s_nop 0
	global_load_dwordx4 v[12:15], v[14:15], off nt
	v_addc_co_u32_e32 v21, vcc, 0, v21, vcc
	v_add_co_u32_e32 v100, vcc, 0xe000, v22
	s_nop 1
	v_addc_co_u32_e32 v101, vcc, 0, v23, vcc
	global_load_dwordx4 v[20:23], v[20:21], off nt
	s_nop 0
	global_load_dwordx4 v[100:103], v[100:101], off nt
	s_branch .LBB0_147

.LBB0_489:
	s_or_b64 exec, exec, s[6:7]
	s_mov_b64 s[26:27], s[80:81]
	s_waitcnt lgkmcnt(0)
	s_barrier
	s_load_dwordx2 s[16:17], s[26:27], 0x80
	s_mov_b32 s31, s73
	s_mov_b32 s50, s76
	s_mov_b64 s[24:25], 0
	s_cmp_eq_u32 s50, s50
	s_mov_b64 s[22:23], 0
	s_cbranch_scc1 .LBB0_491
	s_and_b32 s2, s31, 7
	s_cmpk_lt_u32 s31, 0x80
	s_cselect_b32 s0, 32, 40
	s_mov_b32 s1, 0x8194000
	s_cselect_b32 s6, s1, 0x1c194000
	s_add_u32 s0, s26, s0
	s_addc_u32 s1, s27, 0
	s_load_dwordx2 s[0:1], s[0:1], 0x0
	s_lshl_b32 s3, s31, 21
	s_and_b32 s7, s3, 0xf000000
	s_mul_i32 s8, s2, 0x1ff000
	s_load_dwordx2 s[2:3], s[26:27], 0x78
	s_waitcnt lgkmcnt(0)
	s_add_u32 s0, s0, s7
	s_addc_u32 s1, s1, 0
	s_add_u32 s0, s0, s8
	s_addc_u32 s1, s1, 0
	s_add_u32 s22, s0, 0x8000
	s_addc_u32 s23, s1, 0
	s_add_u32 s0, s2, s6
	s_addc_u32 s1, s3, 0
	s_add_u32 s0, s0, s7
	s_addc_u32 s1, s1, 0
	s_add_u32 s24, s0, s8
	s_addc_u32 s25, s1, 0

.LBB0_509:
	s_ashr_i32 s37, s36, 31
	v_cmp_lt_i64_e32 vcc, s[0:1], v[192:193]
	s_lshl_b64 s[0:1], s[36:37], 20
	s_add_u32 s38, s20, s0
	s_addc_u32 s39, s21, s1
	s_and_b64 s[0:1], vcc, exec
	s_cselect_b32 s0, s39, s11
	s_cselect_b32 s1, s38, s10
	s_ashr_i32 s29, s28, 31
	s_lshl_b64 s[40:41], s[28:29], 20
	s_add_u32 s40, s18, s40
	s_addc_u32 s41, s19, s41
	s_and_b64 s[46:47], vcc, exec
	s_cselect_b32 s29, s41, s3
	s_cselect_b32 s33, s40, s2
	s_add_u32 s37, s2, 0x100
	s_addc_u32 s60, s3, 0
	s_add_u32 s10, s10, 0x80080
	v_mov_b32_e32 v0, 0
	s_addc_u32 s11, s11, 0
	s_mov_b32 s61, -2
	s_waitcnt lgkmcnt(0)
	v_mov_b32_e32 v1, v0
	v_mov_b32_e32 v2, v0
	v_mov_b32_e32 v3, v0
	v_mov_b32_e32 v4, v0
	v_mov_b32_e32 v5, v0
	v_mov_b32_e32 v6, v0
	v_mov_b32_e32 v7, v0
	v_mov_b32_e32 v16, v0
	v_mov_b32_e32 v17, v0
	v_mov_b32_e32 v18, v0
	v_mov_b32_e32 v19, v0
	v_mov_b32_e32 v20, v0
	v_mov_b32_e32 v21, v0
	v_mov_b32_e32 v22, v0
	v_mov_b32_e32 v23, v0
	v_mov_b32_e32 v32, v0
	v_mov_b32_e32 v33, v0
	v_mov_b32_e32 v34, v0
	v_mov_b32_e32 v35, v0
	v_mov_b32_e32 v36, v0
	v_mov_b32_e32 v37, v0
	v_mov_b32_e32 v38, v0
	v_mov_b32_e32 v39, v0
	v_mov_b32_e32 v48, v0
	v_mov_b32_e32 v49, v0
	v_mov_b32_e32 v50, v0
	v_mov_b32_e32 v51, v0
	v_mov_b32_e32 v52, v0
	v_mov_b32_e32 v53, v0
	v_mov_b32_e32 v54, v0
	v_mov_b32_e32 v55, v0
	v_mov_b32_e32 v8, v0
	v_mov_b32_e32 v9, v0
	v_mov_b32_e32 v10, v0
	v_mov_b32_e32 v11, v0
	v_mov_b32_e32 v12, v0
	v_mov_b32_e32 v13, v0
	v_mov_b32_e32 v14, v0
	v_mov_b32_e32 v15, v0
	v_mov_b32_e32 v24, v0
	v_mov_b32_e32 v25, v0
	v_mov_b32_e32 v26, v0
	v_mov_b32_e32 v27, v0
	v_mov_b32_e32 v28, v0
	v_mov_b32_e32 v29, v0
	v_mov_b32_e32 v30, v0
	v_mov_b32_e32 v31, v0
	v_mov_b32_e32 v40, v0
	v_mov_b32_e32 v41, v0
	v_mov_b32_e32 v42, v0
	v_mov_b32_e32 v43, v0
	v_mov_b32_e32 v44, v0
	v_mov_b32_e32 v45, v0
	v_mov_b32_e32 v46, v0
	v_mov_b32_e32 v47, v0
	v_mov_b32_e32 v56, v0
	v_mov_b32_e32 v57, v0
	v_mov_b32_e32 v58, v0
	v_mov_b32_e32 v59, v0
	v_mov_b32_e32 v60, v0
	v_mov_b32_e32 v61, v0
	v_mov_b32_e32 v62, v0
	v_mov_b32_e32 v63, v0
	v_mov_b32_e32 v92, v0
	v_mov_b32_e32 v93, v0
	v_mov_b32_e32 v94, v0
	v_mov_b32_e32 v95, v0
	v_mov_b32_e32 v96, v0
	v_mov_b32_e32 v97, v0
	v_mov_b32_e32 v98, v0
	v_mov_b32_e32 v99, v0
	v_mov_b32_e32 v108, v0
	v_mov_b32_e32 v109, v0
	v_mov_b32_e32 v110, v0
	v_mov_b32_e32 v111, v0
	v_mov_b32_e32 v112, v0
	v_mov_b32_e32 v113, v0
	v_mov_b32_e32 v114, v0
	v_mov_b32_e32 v115, v0
	v_mov_b32_e32 v124, v0
	v_mov_b32_e32 v125, v0
	v_mov_b32_e32 v126, v0
	v_mov_b32_e32 v127, v0
	v_mov_b32_e32 v128, v0
	v_mov_b32_e32 v129, v0
	v_mov_b32_e32 v130, v0
	v_mov_b32_e32 v131, v0
	v_mov_b32_e32 v144, v0
	v_mov_b32_e32 v145, v0
	v_mov_b32_e32 v146, v0
	v_mov_b32_e32 v147, v0
	v_mov_b32_e32 v148, v0
	v_mov_b32_e32 v149, v0
	v_mov_b32_e32 v150, v0
	v_mov_b32_e32 v151, v0
	v_mov_b32_e32 v100, v0
	v_mov_b32_e32 v101, v0
	v_mov_b32_e32 v102, v0
	v_mov_b32_e32 v103, v0
	v_mov_b32_e32 v104, v0
	v_mov_b32_e32 v105, v0
	v_mov_b32_e32 v106, v0
	v_mov_b32_e32 v107, v0
	v_mov_b32_e32 v116, v0
	v_mov_b32_e32 v117, v0
	v_mov_b32_e32 v118, v0
	v_mov_b32_e32 v119, v0
	v_mov_b32_e32 v120, v0
	v_mov_b32_e32 v121, v0
	v_mov_b32_e32 v122, v0
	v_mov_b32_e32 v123, v0
	v_mov_b32_e32 v132, v0
	v_mov_b32_e32 v133, v0
	v_mov_b32_e32 v134, v0
	v_mov_b32_e32 v135, v0
	v_mov_b32_e32 v136, v0
	v_mov_b32_e32 v137, v0
	v_mov_b32_e32 v138, v0
	v_mov_b32_e32 v139, v0
	v_mov_b32_e32 v152, v0
	v_mov_b32_e32 v153, v0
	v_mov_b32_e32 v154, v0
	v_mov_b32_e32 v155, v0
	v_mov_b32_e32 v156, v0
	v_mov_b32_e32 v157, v0
	v_mov_b32_e32 v158, v0
	v_mov_b32_e32 v159, v0
	s_mul_i32 s100, s59, 0x1e00
	v_add_u32_e32 v246, s100, v232
	v_readlane_b32 s98, v255, 49
	v_readlane_b32 s99, v255, 50
	v_readlane_b32 s100, v255, 51
	v_readlane_b32 s101, v255, 52
.LBB0_510:
	s_cmp_eq_u32 s61, -2
	s_cbranch_scc1 .Lkcp_skip_510
	global_store_dwordx4 v247, v[248:251], s[100:101] nt
.Lkcp_skip_510:
	s_add_u32 s2, s10, 0xfff80080
	s_addc_u32 s3, s11, -1
	s_add_i32 s62, 0, 0x10000
	v_add_u32_e32 v76, s62, v241
	ds_read_b128 v[64:67], v76
	ds_read_b128 v[68:71], v76 offset:1024
	ds_read_b128 v[72:75], v76 offset:2048
	ds_read_b128 v[76:79], v76 offset:3072
	s_cmp_eq_u32 s61, 28
	s_cselect_b32 s47, s0, s3
	s_cselect_b32 s46, s1, s2
	s_cselect_b32 s3, s29, s60
	s_cselect_b32 s2, s33, s37
	v_lshl_add_u64 v[176:177], s[10:11], 0, v[198:199]
	s_add_i32 m0, s43, 0xc000
	ds_read_b128 v[80:83], v244
	ds_read_b128 v[84:87], v244 offset:1024
	ds_read_b128 v[88:91], v244 offset:2048
	ds_read_b128 v[140:143], v244 offset:3072
	ds_read_b128 v[160:163], v244 offset:4096
	ds_read_b128 v[164:167], v244 offset:5120
	ds_read_b128 v[168:171], v244 offset:6144
	ds_read_b128 v[172:175], v244 offset:7168
	global_load_lds_dwordx4 v[176:177], off
	v_lshl_add_u64 v[176:177], s[10:11], 0, v[196:197]
	s_add_i32 m0, s43, 0xe000
	s_nop 0
	global_load_lds_dwordx4 v[176:177], off
	s_waitcnt lgkmcnt(8)
	s_barrier
	s_waitcnt lgkmcnt(0)
	s_setprio 1
	s_waitcnt lgkmcnt(0)
	v_mfma_f32_16x16x32_bf16 v[156:159], v[64:67], v[80:83], v[156:159]
	v_mfma_f32_16x16x32_bf16 v[152:155], v[72:75], v[80:83], v[152:155]
	v_mfma_f32_16x16x32_bf16 v[136:139], v[64:67], v[88:91], v[136:139]
	v_mfma_f32_16x16x32_bf16 v[132:135], v[72:75], v[88:91], v[132:135]
	v_mfma_f32_16x16x32_bf16 v[120:123], v[64:67], v[160:163], v[120:123]
	v_mfma_f32_16x16x32_bf16 v[116:119], v[72:75], v[160:163], v[116:119]
	v_mfma_f32_16x16x32_bf16 v[104:107], v[64:67], v[168:171], v[104:107]
	v_mfma_f32_16x16x32_bf16 v[100:103], v[72:75], v[168:171], v[100:103]
	v_mfma_f32_16x16x32_bf16 v[156:159], v[68:71], v[84:87], v[156:159]
	v_mfma_f32_16x16x32_bf16 v[152:155], v[76:79], v[84:87], v[152:155]
	v_mfma_f32_16x16x32_bf16 v[136:139], v[68:71], v[140:143], v[136:139]
	v_mfma_f32_16x16x32_bf16 v[132:135], v[76:79], v[140:143], v[132:135]
	v_mfma_f32_16x16x32_bf16 v[120:123], v[68:71], v[164:167], v[120:123]
	v_mfma_f32_16x16x32_bf16 v[116:119], v[76:79], v[164:167], v[116:119]
	v_mfma_f32_16x16x32_bf16 v[104:107], v[68:71], v[172:175], v[104:107]
	v_mfma_f32_16x16x32_bf16 v[100:103], v[76:79], v[172:175], v[100:103]
	s_setprio 0
	s_barrier
	s_add_i32 s64, 0, 0x14000
	s_add_i32 s62, s62, s49
	v_add_u32_e32 v204, s64, v241
	v_lshl_add_u64 v[212:213], s[2:3], 0, v[188:189]
	s_mov_b32 m0, s62
	ds_read_b128 v[176:179], v204
	ds_read_b128 v[180:183], v204 offset:1024
	ds_read_b128 v[200:203], v204 offset:2048
	ds_read_b128 v[204:207], v204 offset:3072
	global_load_lds_dwordx4 v[212:213], off
	v_lshl_add_u64 v[214:215], s[2:3], 0, v[194:195]
	s_add_i32 m0, s62, 0x2000
	s_nop 0
	global_load_lds_dwordx4 v[214:215], off
	v_min_u32_e32 v247, 0x1feff, v246
	v_lshlrev_b32_e32 v247, 4, v247
	v_add_u32_e32 v246, 0x200, v246
	global_load_dwordx4 v[248:251], v247, s[98:99] nt
	s_barrier
	s_waitcnt lgkmcnt(0)
	s_setprio 1
	s_waitcnt lgkmcnt(0)
	v_mfma_f32_16x16x32_bf16 v[148:151], v[176:179], v[80:83], v[148:151]
	v_mfma_f32_16x16x32_bf16 v[80:83], v[200:203], v[80:83], v[144:147]
	v_mfma_f32_16x16x32_bf16 v[112:115], v[176:179], v[160:163], v[112:115]
	v_mfma_f32_16x16x32_bf16 v[108:111], v[200:203], v[160:163], v[108:111]
	v_mfma_f32_16x16x32_bf16 v[96:99], v[176:179], v[168:171], v[96:99]
	v_mfma_f32_16x16x32_bf16 v[92:95], v[200:203], v[168:171], v[92:95]
	v_mfma_f32_16x16x32_bf16 v[148:151], v[180:183], v[84:87], v[148:151]
	v_mfma_f32_16x16x32_bf16 v[80:83], v[204:207], v[84:87], v[80:83]
	v_mfma_f32_16x16x32_bf16 v[84:87], v[176:179], v[88:91], v[128:131]
	v_mfma_f32_16x16x32_bf16 v[88:91], v[200:203], v[88:91], v[124:127]
	v_mfma_f32_16x16x32_bf16 v[112:115], v[180:183], v[164:167], v[112:115]
	v_mfma_f32_16x16x32_bf16 v[108:111], v[204:207], v[164:167], v[108:111]
	v_mfma_f32_16x16x32_bf16 v[96:99], v[180:183], v[172:175], v[96:99]
	v_mfma_f32_16x16x32_bf16 v[92:95], v[204:207], v[172:175], v[92:95]
	v_mfma_f32_16x16x32_bf16 v[84:87], v[180:183], v[140:143], v[84:87]
	v_mfma_f32_16x16x32_bf16 v[88:91], v[204:207], v[140:143], v[88:91]
	s_setprio 0
	s_mov_b32 m0, s43
	v_lshl_add_u64 v[216:217], s[46:47], 0, v[184:185]
	s_barrier
	ds_read_b128 v[124:127], v244 offset:16384
	ds_read_b128 v[128:131], v244 offset:17408
	ds_read_b128 v[140:143], v244 offset:18432
	ds_read_b128 v[144:147], v244 offset:19456
	ds_read_b128 v[160:163], v244 offset:20480
	ds_read_b128 v[164:167], v244 offset:21504
	ds_read_b128 v[168:171], v244 offset:22528
	ds_read_b128 v[172:175], v244 offset:23552
	global_load_lds_dwordx4 v[216:217], off
	v_lshl_add_u64 v[218:219], s[46:47], 0, v[186:187]
	s_mov_b32 m0, s45
	s_nop 0
	global_load_lds_dwordx4 v[218:219], off
	s_barrier
	s_waitcnt lgkmcnt(0)
	s_setprio 1
	s_waitcnt lgkmcnt(0)
	v_mfma_f32_16x16x32_bf16 v[60:63], v[64:67], v[124:127], v[60:63]
	v_mfma_f32_16x16x32_bf16 v[56:59], v[72:75], v[124:127], v[56:59]
	v_mfma_f32_16x16x32_bf16 v[44:47], v[64:67], v[140:143], v[44:47]
	v_mfma_f32_16x16x32_bf16 v[40:43], v[72:75], v[140:143], v[40:43]
	v_mfma_f32_16x16x32_bf16 v[28:31], v[64:67], v[160:163], v[28:31]
	v_mfma_f32_16x16x32_bf16 v[24:27], v[72:75], v[160:163], v[24:27]
	v_mfma_f32_16x16x32_bf16 v[12:15], v[64:67], v[168:171], v[12:15]
	v_mfma_f32_16x16x32_bf16 v[8:11], v[72:75], v[168:171], v[8:11]
	v_mfma_f32_16x16x32_bf16 v[60:63], v[68:71], v[128:131], v[60:63]
	v_mfma_f32_16x16x32_bf16 v[56:59], v[76:79], v[128:131], v[56:59]
	v_mfma_f32_16x16x32_bf16 v[44:47], v[68:71], v[144:147], v[44:47]
	v_mfma_f32_16x16x32_bf16 v[40:43], v[76:79], v[144:147], v[40:43]
	v_mfma_f32_16x16x32_bf16 v[28:31], v[68:71], v[164:167], v[28:31]
	v_mfma_f32_16x16x32_bf16 v[24:27], v[76:79], v[164:167], v[24:27]
	v_mfma_f32_16x16x32_bf16 v[12:15], v[68:71], v[172:175], v[12:15]
	v_mfma_f32_16x16x32_bf16 v[8:11], v[76:79], v[172:175], v[8:11]
	s_setprio 0
	s_barrier
	s_add_u32 s62, s2, 0x80000
	s_addc_u32 s63, s3, 0
	s_add_i32 s64, s64, s49
	v_lshl_add_u64 v[64:65], s[62:63], 0, v[188:189]
	s_mov_b32 m0, s64
	s_nop 0
	global_load_lds_dwordx4 v[64:65], off
	v_lshl_add_u64 v[64:65], s[62:63], 0, v[194:195]
	s_add_i32 m0, s64, 0x2000
	s_nop 0
	global_load_lds_dwordx4 v[64:65], off
	s_waitcnt vmcnt(7)
	s_barrier
	s_setprio 1
	v_mfma_f32_16x16x32_bf16 v[52:55], v[176:179], v[124:127], v[52:55]
	v_mfma_f32_16x16x32_bf16 v[48:51], v[200:203], v[124:127], v[48:51]
	v_mfma_f32_16x16x32_bf16 v[36:39], v[176:179], v[140:143], v[36:39]
	v_mfma_f32_16x16x32_bf16 v[32:35], v[200:203], v[140:143], v[32:35]
	v_mfma_f32_16x16x32_bf16 v[20:23], v[176:179], v[160:163], v[20:23]
	v_mfma_f32_16x16x32_bf16 v[16:19], v[200:203], v[160:163], v[16:19]
	v_mfma_f32_16x16x32_bf16 v[4:7], v[176:179], v[168:171], v[4:7]
	v_mfma_f32_16x16x32_bf16 v[0:3], v[200:203], v[168:171], v[0:3]
	v_mfma_f32_16x16x32_bf16 v[52:55], v[180:183], v[128:131], v[52:55]
	v_mfma_f32_16x16x32_bf16 v[48:51], v[204:207], v[128:131], v[48:51]
	v_mfma_f32_16x16x32_bf16 v[36:39], v[180:183], v[144:147], v[36:39]
	v_mfma_f32_16x16x32_bf16 v[32:35], v[204:207], v[144:147], v[32:35]
	v_mfma_f32_16x16x32_bf16 v[20:23], v[180:183], v[164:167], v[20:23]
	v_mfma_f32_16x16x32_bf16 v[16:19], v[204:207], v[164:167], v[16:19]
	v_mfma_f32_16x16x32_bf16 v[4:7], v[180:183], v[172:175], v[4:7]
	v_mfma_f32_16x16x32_bf16 v[0:3], v[204:207], v[172:175], v[0:3]
	s_setprio 0
	s_add_i32 s62, 0, 0x18000
	v_add_u32_e32 v76, s62, v241
	s_barrier
	ds_read_b128 v[64:67], v76
	ds_read_b128 v[68:71], v76 offset:1024
	ds_read_b128 v[72:75], v76 offset:2048
	ds_read_b128 v[76:79], v76 offset:3072
	s_add_u32 s46, s46, 0x80000
	s_addc_u32 s47, s47, 0
	s_mov_b32 m0, s52
	v_lshl_add_u64 v[144:145], s[46:47], 0, v[184:185]
	ds_read_b128 v[124:127], v244 offset:32768
	ds_read_b128 v[128:131], v244 offset:33792
	ds_read_b128 v[140:143], v244 offset:34816
	ds_read_b128 v[160:163], v244 offset:35840
	ds_read_b128 v[164:167], v244 offset:36864
	ds_read_b128 v[168:171], v244 offset:37888
	ds_read_b128 v[172:175], v244 offset:38912
	ds_read_b128 v[176:179], v244 offset:39936
	global_load_lds_dwordx4 v[144:145], off
	v_lshl_add_u64 v[144:145], s[46:47], 0, v[186:187]
	s_mov_b32 m0, s53
	s_nop 0
	global_load_lds_dwordx4 v[144:145], off
	s_waitcnt lgkmcnt(8)
	s_barrier
	s_waitcnt lgkmcnt(0)
	s_setprio 1
	s_waitcnt lgkmcnt(0)
	v_mfma_f32_16x16x32_bf16 v[144:147], v[64:67], v[124:127], v[156:159]
	v_mfma_f32_16x16x32_bf16 v[156:159], v[68:71], v[128:131], v[144:147]
	v_mfma_f32_16x16x32_bf16 v[144:147], v[72:75], v[124:127], v[152:155]
	v_mfma_f32_16x16x32_bf16 v[136:139], v[64:67], v[140:143], v[136:139]
	v_mfma_f32_16x16x32_bf16 v[132:135], v[72:75], v[140:143], v[132:135]
	v_mfma_f32_16x16x32_bf16 v[120:123], v[64:67], v[164:167], v[120:123]
	v_mfma_f32_16x16x32_bf16 v[116:119], v[72:75], v[164:167], v[116:119]
	v_mfma_f32_16x16x32_bf16 v[104:107], v[64:67], v[172:175], v[104:107]
	v_mfma_f32_16x16x32_bf16 v[100:103], v[72:75], v[172:175], v[100:103]
	v_mfma_f32_16x16x32_bf16 v[152:155], v[76:79], v[128:131], v[144:147]
	v_mfma_f32_16x16x32_bf16 v[136:139], v[68:71], v[160:163], v[136:139]
	v_mfma_f32_16x16x32_bf16 v[132:135], v[76:79], v[160:163], v[132:135]
	v_mfma_f32_16x16x32_bf16 v[120:123], v[68:71], v[168:171], v[120:123]
	v_mfma_f32_16x16x32_bf16 v[116:119], v[76:79], v[168:171], v[116:119]
	v_mfma_f32_16x16x32_bf16 v[104:107], v[68:71], v[176:179], v[104:107]
	v_mfma_f32_16x16x32_bf16 v[100:103], v[76:79], v[176:179], v[100:103]
	s_setprio 0
	s_barrier
	s_add_i32 s46, 0, 0x1c000
	v_add_u32_e32 v144, s46, v241
	s_add_i32 s47, s62, s49
	ds_read_b128 v[180:183], v144
	ds_read_b128 v[200:203], v144 offset:1024
	ds_read_b128 v[204:207], v144 offset:2048
	ds_read_b128 v[208:211], v144 offset:3072
	v_lshl_add_u64 v[144:145], v[212:213], 0, s[88:89]
	s_mov_b32 m0, s47
	s_nop 0
	global_load_lds_dwordx4 v[144:145], off
	v_lshl_add_u64 v[144:145], v[214:215], 0, s[88:89]
	s_add_i32 m0, s47, 0x2000
	s_nop 0
	global_load_lds_dwordx4 v[144:145], off
	s_barrier
	s_waitcnt lgkmcnt(0)
	s_setprio 1
	s_waitcnt lgkmcnt(0)
	v_mfma_f32_16x16x32_bf16 v[144:147], v[180:183], v[124:127], v[148:151]
	v_mfma_f32_16x16x32_bf16 v[80:83], v[204:207], v[124:127], v[80:83]
	v_mfma_f32_16x16x32_bf16 v[148:151], v[200:203], v[128:131], v[144:147]
	v_mfma_f32_16x16x32_bf16 v[144:147], v[208:211], v[128:131], v[80:83]
	v_mfma_f32_16x16x32_bf16 v[80:83], v[180:183], v[140:143], v[84:87]
	v_mfma_f32_16x16x32_bf16 v[128:131], v[200:203], v[160:163], v[80:83]
	v_mfma_f32_16x16x32_bf16 v[80:83], v[204:207], v[140:143], v[88:91]
	v_mfma_f32_16x16x32_bf16 v[124:127], v[208:211], v[160:163], v[80:83]
	v_mfma_f32_16x16x32_bf16 v[80:83], v[180:183], v[164:167], v[112:115]
	v_mfma_f32_16x16x32_bf16 v[112:115], v[200:203], v[168:171], v[80:83]
	v_mfma_f32_16x16x32_bf16 v[80:83], v[204:207], v[164:167], v[108:111]
	v_mfma_f32_16x16x32_bf16 v[108:111], v[208:211], v[168:171], v[80:83]
	v_mfma_f32_16x16x32_bf16 v[80:83], v[180:183], v[172:175], v[96:99]
	v_mfma_f32_16x16x32_bf16 v[96:99], v[200:203], v[176:179], v[80:83]
	v_mfma_f32_16x16x32_bf16 v[80:83], v[204:207], v[172:175], v[92:95]
	v_mfma_f32_16x16x32_bf16 v[92:95], v[208:211], v[176:179], v[80:83]
	s_setprio 0
	s_mov_b32 m0, s54
	v_lshl_add_u64 v[176:177], v[216:217], 0, s[88:89]
	s_barrier
	s_nop 2
	ds_read_b128 v[80:83], v244 offset:49152
	ds_read_b128 v[84:87], v244 offset:50176
	ds_read_b128 v[88:91], v244 offset:51200
	ds_read_b128 v[140:143], v244 offset:52224
	ds_read_b128 v[160:163], v244 offset:53248
	ds_read_b128 v[164:167], v244 offset:54272
	ds_read_b128 v[168:171], v244 offset:55296
	ds_read_b128 v[172:175], v244 offset:56320
	global_load_lds_dwordx4 v[176:177], off
	v_lshl_add_u64 v[176:177], v[218:219], 0, s[88:89]
	s_mov_b32 m0, s55
	s_nop 0
	global_load_lds_dwordx4 v[176:177], off
	s_barrier
	s_waitcnt lgkmcnt(0)
	s_setprio 1
	s_waitcnt lgkmcnt(0)
	v_mfma_f32_16x16x32_bf16 v[60:63], v[64:67], v[80:83], v[60:63]
	v_mfma_f32_16x16x32_bf16 v[56:59], v[72:75], v[80:83], v[56:59]
	v_mfma_f32_16x16x32_bf16 v[44:47], v[64:67], v[88:91], v[44:47]
	v_mfma_f32_16x16x32_bf16 v[40:43], v[72:75], v[88:91], v[40:43]
	v_mfma_f32_16x16x32_bf16 v[28:31], v[64:67], v[160:163], v[28:31]
	v_mfma_f32_16x16x32_bf16 v[24:27], v[72:75], v[160:163], v[24:27]
	v_mfma_f32_16x16x32_bf16 v[12:15], v[64:67], v[168:171], v[12:15]
	v_mfma_f32_16x16x32_bf16 v[8:11], v[72:75], v[168:171], v[8:11]
	v_mfma_f32_16x16x32_bf16 v[60:63], v[68:71], v[84:87], v[60:63]
	v_mfma_f32_16x16x32_bf16 v[56:59], v[76:79], v[84:87], v[56:59]
	v_mfma_f32_16x16x32_bf16 v[44:47], v[68:71], v[140:143], v[44:47]
	v_mfma_f32_16x16x32_bf16 v[40:43], v[76:79], v[140:143], v[40:43]
	v_mfma_f32_16x16x32_bf16 v[28:31], v[68:71], v[164:167], v[28:31]
	v_mfma_f32_16x16x32_bf16 v[24:27], v[76:79], v[164:167], v[24:27]
	v_mfma_f32_16x16x32_bf16 v[12:15], v[68:71], v[172:175], v[12:15]
	v_mfma_f32_16x16x32_bf16 v[8:11], v[76:79], v[172:175], v[8:11]
	s_setprio 0
	s_barrier
	s_add_u32 s2, s2, 0x80080
	s_addc_u32 s3, s3, 0
	s_add_i32 s46, s46, s49
	v_lshl_add_u64 v[64:65], s[2:3], 0, v[188:189]
	s_mov_b32 m0, s46
	s_nop 0
	global_load_lds_dwordx4 v[64:65], off
	v_lshl_add_u64 v[64:65], s[2:3], 0, v[194:195]
	s_add_i32 m0, s46, 0x2000
	s_nop 0
	global_load_lds_dwordx4 v[64:65], off
	s_waitcnt vmcnt(6)
	s_barrier
	s_setprio 1
	v_mfma_f32_16x16x32_bf16 v[52:55], v[180:183], v[80:83], v[52:55]
	v_mfma_f32_16x16x32_bf16 v[48:51], v[204:207], v[80:83], v[48:51]
	v_mfma_f32_16x16x32_bf16 v[36:39], v[180:183], v[88:91], v[36:39]
	v_mfma_f32_16x16x32_bf16 v[32:35], v[204:207], v[88:91], v[32:35]
	v_mfma_f32_16x16x32_bf16 v[20:23], v[180:183], v[160:163], v[20:23]
	v_mfma_f32_16x16x32_bf16 v[16:19], v[204:207], v[160:163], v[16:19]
	v_mfma_f32_16x16x32_bf16 v[4:7], v[180:183], v[168:171], v[4:7]
	v_mfma_f32_16x16x32_bf16 v[0:3], v[204:207], v[168:171], v[0:3]
	v_mfma_f32_16x16x32_bf16 v[52:55], v[200:203], v[84:87], v[52:55]
	v_mfma_f32_16x16x32_bf16 v[48:51], v[208:211], v[84:87], v[48:51]
	v_mfma_f32_16x16x32_bf16 v[36:39], v[200:203], v[140:143], v[36:39]
	v_mfma_f32_16x16x32_bf16 v[32:35], v[208:211], v[140:143], v[32:35]
	v_mfma_f32_16x16x32_bf16 v[20:23], v[200:203], v[164:167], v[20:23]
	v_mfma_f32_16x16x32_bf16 v[16:19], v[208:211], v[164:167], v[16:19]
	v_mfma_f32_16x16x32_bf16 v[4:7], v[200:203], v[172:175], v[4:7]
	v_mfma_f32_16x16x32_bf16 v[0:3], v[208:211], v[172:175], v[0:3]
	s_setprio 0
	s_add_i32 s61, s61, 2
	s_add_u32 s37, s37, 0x100
	s_addc_u32 s60, s60, 0
	s_add_u32 s10, s10, 0x100
	s_addc_u32 s11, s11, 0
	s_cmp_gt_u32 s61, 29
	s_barrier
	s_cbranch_scc0 .LBB0_510
	v_mov_b32_e32 v64, 1.0
	v_mov_b32_e32 v65, 1.0
	v_mov_b32_e32 v66, 1.0
	v_mov_b32_e32 v67, 1.0
	v_mov_b32_e32 v68, 1.0
	v_mov_b32_e32 v69, 1.0
	v_mov_b32_e32 v70, 1.0
	v_mov_b32_e32 v71, 1.0
	s_mul_i32 s0, s59, 0x1e00
	v_add_u32_e32 v245, s0, v243
	v_cndmask_b32_e64 v64, 0, 1, s[14:15]
	v_min_i32_e32 v218, 0x1feff, v245
	v_min_i32_e32 v216, 0x1fcff, v245
	v_min_i32_e32 v214, 0x1faff, v245
	v_min_i32_e32 v210, 0x1f8ff, v245
	v_min_i32_e32 v208, 0x1f6ff, v245
	v_min_i32_e32 v204, 0x1f4ff, v245
	v_min_i32_e32 v202, 0x1f2ff, v245
	v_min_i32_e32 v200, 0x1f0ff, v245
	v_cmp_ne_u32_e64 s[10:11], 1, v64
	s_andn2_b64 vcc, exec, s[14:15]
	v_ashrrev_i32_e32 v219, 31, v218
	v_ashrrev_i32_e32 v217, 31, v216
	v_ashrrev_i32_e32 v215, 31, v214
	v_ashrrev_i32_e32 v211, 31, v210
	v_ashrrev_i32_e32 v209, 31, v208
	v_ashrrev_i32_e32 v205, 31, v204
	v_ashrrev_i32_e32 v203, 31, v202
	v_ashrrev_i32_e32 v201, 31, v200
	s_cbranch_vccnz .LBB0_513
	v_lshl_add_u64 v[66:67], v[216:217], 4, s[22:23]
	v_lshl_add_u64 v[64:65], v[218:219], 4, s[22:23]
	v_add_co_u32_e32 v66, vcc, 0x2000, v66
	v_lshl_add_u64 v[68:69], v[202:203], 4, s[22:23]
	s_nop 0
	v_addc_co_u32_e32 v67, vcc, 0, v67, vcc
	global_load_dwordx4 v[88:91], v[64:65], off nt
	global_load_dwordx4 v[76:79], v[66:67], off nt
	v_lshl_add_u64 v[64:65], v[214:215], 4, s[22:23]
	v_add_co_u32_e32 v64, vcc, 0x4000, v64
	v_lshl_add_u64 v[66:67], v[210:211], 4, s[22:23]
	s_nop 0
	v_addc_co_u32_e32 v65, vcc, 0, v65, vcc
	v_add_co_u32_e32 v66, vcc, 0x6000, v66
	v_lshl_add_u64 v[70:71], v[200:201], 4, s[22:23]
	s_nop 0
	v_addc_co_u32_e32 v67, vcc, 0, v67, vcc
	global_load_dwordx4 v[84:87], v[64:65], off nt
	global_load_dwordx4 v[72:75], v[66:67], off nt
	v_lshl_add_u64 v[64:65], v[208:209], 4, s[22:23]
	v_add_co_u32_e32 v64, vcc, 0x8000, v64
	v_lshl_add_u64 v[66:67], v[204:205], 4, s[22:23]
	s_nop 0
	v_addc_co_u32_e32 v65, vcc, 0, v65, vcc
	v_add_co_u32_e32 v66, vcc, 0xa000, v66
	s_nop 1
	v_addc_co_u32_e32 v67, vcc, 0, v67, vcc
	v_add_co_u32_e32 v68, vcc, 0xc000, v68
	global_load_dwordx4 v[80:83], v[64:65], off nt
	s_nop 0
	global_load_dwordx4 v[64:67], v[66:67], off nt
	v_addc_co_u32_e32 v69, vcc, 0, v69, vcc
	v_add_co_u32_e32 v140, vcc, 0xe000, v70
	s_nop 1
	v_addc_co_u32_e32 v141, vcc, 0, v71, vcc
	global_load_dwordx4 v[68:71], v[68:69], off nt
	s_nop 0
	global_load_dwordx4 v[140:143], v[140:141], off nt
	s_branch .LBB0_514

.LBB0_562:
	s_ashr_i32 s39, s38, 31
	v_cmp_lt_i64_e64 s[8:9], s[0:1], v[192:193]
	s_lshl_b64 s[0:1], s[38:39], 20
	s_add_u32 s40, s20, s0
	s_addc_u32 s41, s21, s1
	s_and_b64 s[0:1], s[8:9], exec
	s_cselect_b32 s0, s41, s11
	s_cselect_b32 s1, s40, s10
	s_ashr_i32 s37, s36, 31
	s_lshl_b64 s[42:43], s[36:37], 20
	s_add_u32 s42, s18, s42
	s_addc_u32 s43, s19, s43
	s_and_b64 s[48:49], s[8:9], exec
	s_cselect_b32 s33, s43, s3
	s_cselect_b32 s37, s42, s2
	s_add_u32 s39, s2, 0x100
	s_addc_u32 s61, s3, 0
	s_add_u32 s2, s10, 0x80080
	s_addc_u32 s3, s11, 0
	s_mov_b32 s62, -2
	s_waitcnt vmcnt(0)
	s_mul_i32 s100, s51, 0x1e00
	v_add_u32_e32 v246, s100, v232
	v_readlane_b32 s98, v255, 49
	v_readlane_b32 s99, v255, 50
	v_readlane_b32 s100, v255, 51
	v_readlane_b32 s101, v255, 52
.LBB0_563:
	s_cmp_eq_u32 s62, -2
	s_cbranch_scc1 .Lkcp_skip_563
	global_store_dwordx4 v247, v[248:251], s[100:101] nt
.Lkcp_skip_563:
	s_add_u32 s10, s2, 0xfff80080
	s_addc_u32 s11, s3, -1
	s_add_i32 s63, 0, 0x10000
	v_add_u32_e32 v140, s63, v197
	ds_read_b128 v[128:131], v140
	ds_read_b128 v[132:135], v140 offset:1024
	ds_read_b128 v[136:139], v140 offset:2048
	ds_read_b128 v[140:143], v140 offset:3072
	s_cmp_eq_u32 s62, 28
	s_cselect_b32 s49, s0, s11
	s_cselect_b32 s48, s1, s10
	s_cselect_b32 s11, s33, s61
	s_cselect_b32 s10, s37, s39
	v_lshl_add_u64 v[186:187], s[2:3], 0, v[168:169]
	s_add_i32 m0, s45, 0xc000
	ds_read_b128 v[144:147], v200
	ds_read_b128 v[148:151], v200 offset:1024
	ds_read_b128 v[152:155], v200 offset:2048
	ds_read_b128 v[156:159], v200 offset:3072
	ds_read_b128 v[170:173], v200 offset:4096
	ds_read_b128 v[174:177], v200 offset:5120
	ds_read_b128 v[178:181], v200 offset:6144
	ds_read_b128 v[182:185], v200 offset:7168
	global_load_lds_dwordx4 v[186:187], off
	v_lshl_add_u64 v[186:187], s[2:3], 0, v[166:167]
	s_add_i32 m0, s45, 0xe000
	s_nop 0
	global_load_lds_dwordx4 v[186:187], off
	s_waitcnt lgkmcnt(8)
	s_barrier
	s_waitcnt lgkmcnt(0)
	s_setprio 1
	s_waitcnt lgkmcnt(0)
	v_mfma_f32_16x16x32_bf16 v[124:127], v[128:131], v[144:147], v[124:127]
	v_mfma_f32_16x16x32_bf16 v[120:123], v[136:139], v[144:147], v[120:123]
	v_mfma_f32_16x16x32_bf16 v[108:111], v[128:131], v[152:155], v[108:111]
	v_mfma_f32_16x16x32_bf16 v[104:107], v[136:139], v[152:155], v[104:107]
	v_mfma_f32_16x16x32_bf16 v[92:95], v[128:131], v[170:173], v[92:95]
	v_mfma_f32_16x16x32_bf16 v[88:91], v[136:139], v[170:173], v[88:91]
	v_mfma_f32_16x16x32_bf16 v[76:79], v[128:131], v[178:181], v[76:79]
	v_mfma_f32_16x16x32_bf16 v[72:75], v[136:139], v[178:181], v[72:75]
	v_mfma_f32_16x16x32_bf16 v[124:127], v[132:135], v[148:151], v[124:127]
	v_mfma_f32_16x16x32_bf16 v[120:123], v[140:143], v[148:151], v[120:123]
	v_mfma_f32_16x16x32_bf16 v[108:111], v[132:135], v[156:159], v[108:111]
	v_mfma_f32_16x16x32_bf16 v[104:107], v[140:143], v[156:159], v[104:107]
	v_mfma_f32_16x16x32_bf16 v[92:95], v[132:135], v[174:177], v[92:95]
	v_mfma_f32_16x16x32_bf16 v[88:91], v[140:143], v[174:177], v[88:91]
	v_mfma_f32_16x16x32_bf16 v[76:79], v[132:135], v[182:185], v[76:79]
	v_mfma_f32_16x16x32_bf16 v[72:75], v[140:143], v[182:185], v[72:75]
	s_setprio 0
	s_barrier
	s_add_i32 s66, 0, 0x14000
	v_add_u32_e32 v186, s66, v197
	s_add_i32 s63, s63, s53
	ds_read_b128 v[202:205], v186
	ds_read_b128 v[206:209], v186 offset:1024
	ds_read_b128 v[210:213], v186 offset:2048
	ds_read_b128 v[214:217], v186 offset:3072
	v_lshl_add_u64 v[186:187], s[10:11], 0, v[188:189]
	s_mov_b32 m0, s63
	v_lshl_add_u64 v[194:195], s[10:11], 0, v[164:165]
	global_load_lds_dwordx4 v[186:187], off
	s_add_i32 m0, s63, 0x2000
	s_nop 0
	global_load_lds_dwordx4 v[194:195], off
	v_min_u32_e32 v247, 0x1feff, v246
	v_lshlrev_b32_e32 v247, 4, v247
	v_add_u32_e32 v246, 0x200, v246
	global_load_dwordx4 v[248:251], v247, s[98:99] nt
	s_barrier
	s_waitcnt lgkmcnt(0)
	s_setprio 1
	s_waitcnt lgkmcnt(0)
	v_mfma_f32_16x16x32_bf16 v[116:119], v[202:205], v[144:147], v[116:119]
	v_mfma_f32_16x16x32_bf16 v[112:115], v[210:213], v[144:147], v[112:115]
	v_mfma_f32_16x16x32_bf16 v[100:103], v[202:205], v[152:155], v[100:103]
	v_mfma_f32_16x16x32_bf16 v[96:99], v[210:213], v[152:155], v[96:99]
	v_mfma_f32_16x16x32_bf16 v[84:87], v[202:205], v[170:173], v[84:87]
	v_mfma_f32_16x16x32_bf16 v[80:83], v[210:213], v[170:173], v[80:83]
	v_mfma_f32_16x16x32_bf16 v[68:71], v[202:205], v[178:181], v[68:71]
	v_mfma_f32_16x16x32_bf16 v[64:67], v[210:213], v[178:181], v[64:67]
	v_mfma_f32_16x16x32_bf16 v[116:119], v[206:209], v[148:151], v[116:119]
	v_mfma_f32_16x16x32_bf16 v[112:115], v[214:217], v[148:151], v[112:115]
	v_mfma_f32_16x16x32_bf16 v[100:103], v[206:209], v[156:159], v[100:103]
	v_mfma_f32_16x16x32_bf16 v[96:99], v[214:217], v[156:159], v[96:99]
	v_mfma_f32_16x16x32_bf16 v[84:87], v[206:209], v[174:177], v[84:87]
	v_mfma_f32_16x16x32_bf16 v[80:83], v[214:217], v[174:177], v[80:83]
	v_mfma_f32_16x16x32_bf16 v[68:71], v[206:209], v[182:185], v[68:71]
	v_mfma_f32_16x16x32_bf16 v[64:67], v[214:217], v[182:185], v[64:67]
	s_setprio 0
	s_mov_b32 m0, s45
	v_lshl_add_u64 v[218:219], s[48:49], 0, v[160:161]
	s_barrier
	ds_read_b128 v[144:147], v200 offset:16384
	ds_read_b128 v[148:151], v200 offset:17408
	ds_read_b128 v[152:155], v200 offset:18432
	ds_read_b128 v[156:159], v200 offset:19456
	ds_read_b128 v[170:173], v200 offset:20480
	ds_read_b128 v[174:177], v200 offset:21504
	ds_read_b128 v[178:181], v200 offset:22528
	ds_read_b128 v[182:185], v200 offset:23552
	global_load_lds_dwordx4 v[218:219], off
	v_lshl_add_u64 v[220:221], s[48:49], 0, v[162:163]
	s_mov_b32 m0, s47
	s_nop 0
	global_load_lds_dwordx4 v[220:221], off
	s_barrier
	s_waitcnt lgkmcnt(0)
	s_setprio 1
	s_waitcnt lgkmcnt(0)
	v_mfma_f32_16x16x32_bf16 v[60:63], v[128:131], v[144:147], v[60:63]
	v_mfma_f32_16x16x32_bf16 v[56:59], v[136:139], v[144:147], v[56:59]
	v_mfma_f32_16x16x32_bf16 v[44:47], v[128:131], v[152:155], v[44:47]
	v_mfma_f32_16x16x32_bf16 v[40:43], v[136:139], v[152:155], v[40:43]
	v_mfma_f32_16x16x32_bf16 v[28:31], v[128:131], v[170:173], v[28:31]
	v_mfma_f32_16x16x32_bf16 v[24:27], v[136:139], v[170:173], v[24:27]
	v_mfma_f32_16x16x32_bf16 v[12:15], v[128:131], v[178:181], v[12:15]
	v_mfma_f32_16x16x32_bf16 v[8:11], v[136:139], v[178:181], v[8:11]
	v_mfma_f32_16x16x32_bf16 v[60:63], v[132:135], v[148:151], v[60:63]
	v_mfma_f32_16x16x32_bf16 v[56:59], v[140:143], v[148:151], v[56:59]
	v_mfma_f32_16x16x32_bf16 v[44:47], v[132:135], v[156:159], v[44:47]
	v_mfma_f32_16x16x32_bf16 v[40:43], v[140:143], v[156:159], v[40:43]
	v_mfma_f32_16x16x32_bf16 v[28:31], v[132:135], v[174:177], v[28:31]
	v_mfma_f32_16x16x32_bf16 v[24:27], v[140:143], v[174:177], v[24:27]
	v_mfma_f32_16x16x32_bf16 v[12:15], v[132:135], v[182:185], v[12:15]
	v_mfma_f32_16x16x32_bf16 v[8:11], v[140:143], v[182:185], v[8:11]
	s_setprio 0
	s_barrier
	s_add_u32 s64, s10, 0x80000
	s_addc_u32 s65, s11, 0
	s_add_i32 s63, s66, s53
	v_lshl_add_u64 v[128:129], s[64:65], 0, v[188:189]
	s_mov_b32 m0, s63
	s_nop 0
	global_load_lds_dwordx4 v[128:129], off
	v_lshl_add_u64 v[128:129], s[64:65], 0, v[164:165]
	s_add_i32 m0, s63, 0x2000
	s_nop 0
	global_load_lds_dwordx4 v[128:129], off
	s_waitcnt vmcnt(7)
	s_barrier
	s_setprio 1
	v_mfma_f32_16x16x32_bf16 v[52:55], v[202:205], v[144:147], v[52:55]
	v_mfma_f32_16x16x32_bf16 v[48:51], v[210:213], v[144:147], v[48:51]
	v_mfma_f32_16x16x32_bf16 v[36:39], v[202:205], v[152:155], v[36:39]
	v_mfma_f32_16x16x32_bf16 v[32:35], v[210:213], v[152:155], v[32:35]
	v_mfma_f32_16x16x32_bf16 v[20:23], v[202:205], v[170:173], v[20:23]
	v_mfma_f32_16x16x32_bf16 v[16:19], v[210:213], v[170:173], v[16:19]
	v_mfma_f32_16x16x32_bf16 v[4:7], v[202:205], v[178:181], v[4:7]
	v_mfma_f32_16x16x32_bf16 v[0:3], v[210:213], v[178:181], v[0:3]
	v_mfma_f32_16x16x32_bf16 v[52:55], v[206:209], v[148:151], v[52:55]
	v_mfma_f32_16x16x32_bf16 v[48:51], v[214:217], v[148:151], v[48:51]
	v_mfma_f32_16x16x32_bf16 v[36:39], v[206:209], v[156:159], v[36:39]
	v_mfma_f32_16x16x32_bf16 v[32:35], v[214:217], v[156:159], v[32:35]
	v_mfma_f32_16x16x32_bf16 v[20:23], v[206:209], v[174:177], v[20:23]
	v_mfma_f32_16x16x32_bf16 v[16:19], v[214:217], v[174:177], v[16:19]
	v_mfma_f32_16x16x32_bf16 v[4:7], v[206:209], v[182:185], v[4:7]
	v_mfma_f32_16x16x32_bf16 v[0:3], v[214:217], v[182:185], v[0:3]
	s_setprio 0
	s_add_i32 s63, 0, 0x18000
	v_add_u32_e32 v140, s63, v197
	s_barrier
	ds_read_b128 v[128:131], v140
	ds_read_b128 v[132:135], v140 offset:1024
	ds_read_b128 v[136:139], v140 offset:2048
	ds_read_b128 v[140:143], v140 offset:3072
	s_add_u32 s48, s48, 0x80000
	s_addc_u32 s49, s49, 0
	s_mov_b32 m0, s54
	v_lshl_add_u64 v[202:203], s[48:49], 0, v[160:161]
	ds_read_b128 v[144:147], v200 offset:32768
	ds_read_b128 v[148:151], v200 offset:33792
	ds_read_b128 v[152:155], v200 offset:34816
	ds_read_b128 v[156:159], v200 offset:35840
	ds_read_b128 v[170:173], v200 offset:36864
	ds_read_b128 v[174:177], v200 offset:37888
	ds_read_b128 v[178:181], v200 offset:38912
	ds_read_b128 v[182:185], v200 offset:39936
	global_load_lds_dwordx4 v[202:203], off
	v_lshl_add_u64 v[202:203], s[48:49], 0, v[162:163]
	s_mov_b32 m0, s55
	s_nop 0
	global_load_lds_dwordx4 v[202:203], off
	s_waitcnt lgkmcnt(8)
	s_barrier
	s_waitcnt lgkmcnt(0)
	s_setprio 1
	s_waitcnt lgkmcnt(0)
	v_mfma_f32_16x16x32_bf16 v[124:127], v[128:131], v[144:147], v[124:127]
	v_mfma_f32_16x16x32_bf16 v[120:123], v[136:139], v[144:147], v[120:123]
	v_mfma_f32_16x16x32_bf16 v[108:111], v[128:131], v[152:155], v[108:111]
	v_mfma_f32_16x16x32_bf16 v[104:107], v[136:139], v[152:155], v[104:107]
	v_mfma_f32_16x16x32_bf16 v[92:95], v[128:131], v[170:173], v[92:95]
	v_mfma_f32_16x16x32_bf16 v[88:91], v[136:139], v[170:173], v[88:91]
	v_mfma_f32_16x16x32_bf16 v[76:79], v[128:131], v[178:181], v[76:79]
	v_mfma_f32_16x16x32_bf16 v[72:75], v[136:139], v[178:181], v[72:75]
	v_mfma_f32_16x16x32_bf16 v[124:127], v[132:135], v[148:151], v[124:127]
	v_mfma_f32_16x16x32_bf16 v[120:123], v[140:143], v[148:151], v[120:123]
	v_mfma_f32_16x16x32_bf16 v[108:111], v[132:135], v[156:159], v[108:111]
	v_mfma_f32_16x16x32_bf16 v[104:107], v[140:143], v[156:159], v[104:107]
	v_mfma_f32_16x16x32_bf16 v[92:95], v[132:135], v[174:177], v[92:95]
	v_mfma_f32_16x16x32_bf16 v[88:91], v[140:143], v[174:177], v[88:91]
	v_mfma_f32_16x16x32_bf16 v[76:79], v[132:135], v[182:185], v[76:79]
	v_mfma_f32_16x16x32_bf16 v[72:75], v[140:143], v[182:185], v[72:75]
	s_setprio 0
	s_barrier
	s_add_i32 s48, 0, 0x1c000
	s_add_i32 s49, s63, s53
	v_add_u32_e32 v201, s48, v197
	v_lshl_add_u64 v[186:187], v[186:187], 0, s[88:89]
	s_mov_b32 m0, s49
	ds_read_b128 v[202:205], v201
	ds_read_b128 v[206:209], v201 offset:1024
	ds_read_b128 v[210:213], v201 offset:2048
	ds_read_b128 v[214:217], v201 offset:3072
	global_load_lds_dwordx4 v[186:187], off
	v_lshl_add_u64 v[186:187], v[194:195], 0, s[88:89]
	s_add_i32 m0, s49, 0x2000
	s_nop 0
	global_load_lds_dwordx4 v[186:187], off
	s_barrier
	s_waitcnt lgkmcnt(0)
	s_setprio 1
	s_waitcnt lgkmcnt(0)
	v_mfma_f32_16x16x32_bf16 v[116:119], v[202:205], v[144:147], v[116:119]
	v_mfma_f32_16x16x32_bf16 v[112:115], v[210:213], v[144:147], v[112:115]
	v_mfma_f32_16x16x32_bf16 v[100:103], v[202:205], v[152:155], v[100:103]
	v_mfma_f32_16x16x32_bf16 v[96:99], v[210:213], v[152:155], v[96:99]
	v_mfma_f32_16x16x32_bf16 v[84:87], v[202:205], v[170:173], v[84:87]
	v_mfma_f32_16x16x32_bf16 v[80:83], v[210:213], v[170:173], v[80:83]
	v_mfma_f32_16x16x32_bf16 v[68:71], v[202:205], v[178:181], v[68:71]
	v_mfma_f32_16x16x32_bf16 v[64:67], v[210:213], v[178:181], v[64:67]
	v_mfma_f32_16x16x32_bf16 v[116:119], v[206:209], v[148:151], v[116:119]
	v_mfma_f32_16x16x32_bf16 v[112:115], v[214:217], v[148:151], v[112:115]
	v_mfma_f32_16x16x32_bf16 v[100:103], v[206:209], v[156:159], v[100:103]
	v_mfma_f32_16x16x32_bf16 v[96:99], v[214:217], v[156:159], v[96:99]
	v_mfma_f32_16x16x32_bf16 v[84:87], v[206:209], v[174:177], v[84:87]
	v_mfma_f32_16x16x32_bf16 v[80:83], v[214:217], v[174:177], v[80:83]
	v_mfma_f32_16x16x32_bf16 v[68:71], v[206:209], v[182:185], v[68:71]
	v_mfma_f32_16x16x32_bf16 v[64:67], v[214:217], v[182:185], v[64:67]
	s_setprio 0
	s_mov_b32 m0, s56
	v_lshl_add_u64 v[186:187], v[218:219], 0, s[88:89]
	s_barrier
	ds_read_b128 v[144:147], v200 offset:49152
	ds_read_b128 v[148:151], v200 offset:50176
	ds_read_b128 v[152:155], v200 offset:51200
	ds_read_b128 v[156:159], v200 offset:52224
	ds_read_b128 v[170:173], v200 offset:53248
	ds_read_b128 v[174:177], v200 offset:54272
	ds_read_b128 v[178:181], v200 offset:55296
	ds_read_b128 v[182:185], v200 offset:56320
	global_load_lds_dwordx4 v[186:187], off
	v_lshl_add_u64 v[186:187], v[220:221], 0, s[88:89]
	s_mov_b32 m0, s57
	s_nop 0
	global_load_lds_dwordx4 v[186:187], off
	s_barrier
	s_waitcnt lgkmcnt(0)
	s_setprio 1
	s_waitcnt lgkmcnt(0)
	v_mfma_f32_16x16x32_bf16 v[60:63], v[128:131], v[144:147], v[60:63]
	v_mfma_f32_16x16x32_bf16 v[56:59], v[136:139], v[144:147], v[56:59]
	v_mfma_f32_16x16x32_bf16 v[44:47], v[128:131], v[152:155], v[44:47]
	v_mfma_f32_16x16x32_bf16 v[40:43], v[136:139], v[152:155], v[40:43]
	v_mfma_f32_16x16x32_bf16 v[28:31], v[128:131], v[170:173], v[28:31]
	v_mfma_f32_16x16x32_bf16 v[24:27], v[136:139], v[170:173], v[24:27]
	v_mfma_f32_16x16x32_bf16 v[12:15], v[128:131], v[178:181], v[12:15]
	v_mfma_f32_16x16x32_bf16 v[8:11], v[136:139], v[178:181], v[8:11]
	v_mfma_f32_16x16x32_bf16 v[60:63], v[132:135], v[148:151], v[60:63]
	v_mfma_f32_16x16x32_bf16 v[56:59], v[140:143], v[148:151], v[56:59]
	v_mfma_f32_16x16x32_bf16 v[44:47], v[132:135], v[156:159], v[44:47]
	v_mfma_f32_16x16x32_bf16 v[40:43], v[140:143], v[156:159], v[40:43]
	v_mfma_f32_16x16x32_bf16 v[28:31], v[132:135], v[174:177], v[28:31]
	v_mfma_f32_16x16x32_bf16 v[24:27], v[140:143], v[174:177], v[24:27]
	v_mfma_f32_16x16x32_bf16 v[12:15], v[132:135], v[182:185], v[12:15]
	v_mfma_f32_16x16x32_bf16 v[8:11], v[140:143], v[182:185], v[8:11]
	s_setprio 0
	s_barrier
	s_add_u32 s10, s10, 0x80080
	s_addc_u32 s11, s11, 0
	s_add_i32 s48, s48, s53
	v_lshl_add_u64 v[128:129], s[10:11], 0, v[188:189]
	s_mov_b32 m0, s48
	s_nop 0
	global_load_lds_dwordx4 v[128:129], off
	v_lshl_add_u64 v[128:129], s[10:11], 0, v[164:165]
	s_add_i32 m0, s48, 0x2000
	s_nop 0
	global_load_lds_dwordx4 v[128:129], off
	s_waitcnt vmcnt(6)
	s_barrier
	s_setprio 1
	v_mfma_f32_16x16x32_bf16 v[52:55], v[202:205], v[144:147], v[52:55]
	v_mfma_f32_16x16x32_bf16 v[48:51], v[210:213], v[144:147], v[48:51]
	v_mfma_f32_16x16x32_bf16 v[36:39], v[202:205], v[152:155], v[36:39]
	v_mfma_f32_16x16x32_bf16 v[32:35], v[210:213], v[152:155], v[32:35]
	v_mfma_f32_16x16x32_bf16 v[20:23], v[202:205], v[170:173], v[20:23]
	v_mfma_f32_16x16x32_bf16 v[16:19], v[210:213], v[170:173], v[16:19]
	v_mfma_f32_16x16x32_bf16 v[4:7], v[202:205], v[178:181], v[4:7]
	v_mfma_f32_16x16x32_bf16 v[0:3], v[210:213], v[178:181], v[0:3]
	v_mfma_f32_16x16x32_bf16 v[52:55], v[206:209], v[148:151], v[52:55]
	v_mfma_f32_16x16x32_bf16 v[48:51], v[214:217], v[148:151], v[48:51]
	v_mfma_f32_16x16x32_bf16 v[36:39], v[206:209], v[156:159], v[36:39]
	v_mfma_f32_16x16x32_bf16 v[32:35], v[214:217], v[156:159], v[32:35]
	v_mfma_f32_16x16x32_bf16 v[20:23], v[206:209], v[174:177], v[20:23]
	v_mfma_f32_16x16x32_bf16 v[16:19], v[214:217], v[174:177], v[16:19]
	v_mfma_f32_16x16x32_bf16 v[4:7], v[206:209], v[182:185], v[4:7]
	v_mfma_f32_16x16x32_bf16 v[0:3], v[214:217], v[182:185], v[0:3]
	s_setprio 0
	s_add_i32 s62, s62, 2
	s_add_u32 s39, s39, 0x100
	s_addc_u32 s61, s61, 0
	s_add_u32 s2, s2, 0x100
	s_addc_u32 s3, s3, 0
	s_cmp_gt_u32 s62, 29
	s_barrier
	s_cbranch_scc0 .LBB0_563
	v_mov_b32_e32 v128, 1.0
	v_mov_b32_e32 v129, 1.0
	v_mov_b32_e32 v130, 1.0
	v_mov_b32_e32 v131, 1.0
	v_mov_b32_e32 v132, 1.0
	v_mov_b32_e32 v133, 1.0
	v_mov_b32_e32 v134, 1.0
	v_mov_b32_e32 v135, 1.0
	s_mul_i32 s0, s51, 0x1e00
	v_add_u32_e32 v201, s0, v198
	v_cndmask_b32_e64 v128, 0, 1, s[28:29]
	v_min_i32_e32 v194, 0x1feff, v201
	v_min_i32_e32 v186, 0x1fcff, v201
	v_min_i32_e32 v184, 0x1faff, v201
	v_min_i32_e32 v182, 0x1f8ff, v201
	v_min_i32_e32 v180, 0x1f6ff, v201
	v_min_i32_e32 v178, 0x1f4ff, v201
	v_min_i32_e32 v176, 0x1f2ff, v201
	v_min_i32_e32 v174, 0x1f0ff, v201
	v_cmp_ne_u32_e64 s[10:11], 1, v128
	s_andn2_b64 vcc, exec, s[28:29]
	v_ashrrev_i32_e32 v195, 31, v194
	v_ashrrev_i32_e32 v187, 31, v186
	v_ashrrev_i32_e32 v185, 31, v184
	v_ashrrev_i32_e32 v183, 31, v182
	v_ashrrev_i32_e32 v181, 31, v180
	v_ashrrev_i32_e32 v179, 31, v178
	v_ashrrev_i32_e32 v177, 31, v176
	v_ashrrev_i32_e32 v175, 31, v174
	s_cbranch_vccnz .LBB0_566
	v_lshl_add_u64 v[130:131], v[186:187], 4, s[22:23]
	v_lshl_add_u64 v[128:129], v[194:195], 4, s[22:23]
	v_add_co_u32_e32 v130, vcc, 0x2000, v130
	v_lshl_add_u64 v[132:133], v[176:177], 4, s[22:23]
	s_nop 0
	v_addc_co_u32_e32 v131, vcc, 0, v131, vcc
	global_load_dwordx4 v[152:155], v[128:129], off nt
	global_load_dwordx4 v[140:143], v[130:131], off nt
	v_lshl_add_u64 v[128:129], v[184:185], 4, s[22:23]
	v_add_co_u32_e32 v128, vcc, 0x4000, v128
	v_lshl_add_u64 v[130:131], v[182:183], 4, s[22:23]
	s_nop 0
	v_addc_co_u32_e32 v129, vcc, 0, v129, vcc
	v_add_co_u32_e32 v130, vcc, 0x6000, v130
	v_lshl_add_u64 v[134:135], v[174:175], 4, s[22:23]
	s_nop 0
	v_addc_co_u32_e32 v131, vcc, 0, v131, vcc
	global_load_dwordx4 v[148:151], v[128:129], off nt
	global_load_dwordx4 v[136:139], v[130:131], off nt
	v_lshl_add_u64 v[128:129], v[180:181], 4, s[22:23]
	v_add_co_u32_e32 v128, vcc, 0x8000, v128
	v_lshl_add_u64 v[130:131], v[178:179], 4, s[22:23]
	s_nop 0
	v_addc_co_u32_e32 v129, vcc, 0, v129, vcc
	v_add_co_u32_e32 v130, vcc, 0xa000, v130
	s_nop 1
	v_addc_co_u32_e32 v131, vcc, 0, v131, vcc
	v_add_co_u32_e32 v132, vcc, 0xc000, v132
	global_load_dwordx4 v[144:147], v[128:129], off nt
	s_nop 0
	global_load_dwordx4 v[128:131], v[130:131], off nt
	v_addc_co_u32_e32 v133, vcc, 0, v133, vcc
	v_add_co_u32_e32 v156, vcc, 0xe000, v134
	s_nop 1
	v_addc_co_u32_e32 v157, vcc, 0, v135, vcc
	global_load_dwordx4 v[132:135], v[132:133], off nt
	s_nop 0
	global_load_dwordx4 v[156:159], v[156:157], off nt
	s_branch .LBB0_567

.LBB0_650:
	s_or_b64 exec, exec, s[6:7]
	s_mov_b64 s[0:1], s[80:81]
	s_waitcnt lgkmcnt(0)
	s_barrier
	s_load_dwordx2 s[22:23], s[0:1], 0x80
	s_lshl_b32 s84, s30, 22
	s_mov_b32 s65, s76
	s_mov_b32 s66, s73
	s_cmp_lg_u32 s65, s65
	s_mov_b64 s[6:7], -1
	s_cbranch_scc1 .LBB0_652
	s_load_dwordx2 s[2:3], s[0:1], 0x78
	s_mov_b64 s[6:7], 0

.LBB0_671:
	v_mov_b64_e32 v[0:1], 0x400
	s_ashr_i32 s45, s44, 31
	v_cmp_lt_i64_e32 vcc, s[0:1], v[0:1]
	s_lshl_b64 s[0:1], s[44:45], 20
	s_add_u32 s46, s22, s0
	s_addc_u32 s47, s23, s1
	s_and_b64 s[0:1], vcc, exec
	s_cselect_b32 s0, s47, s13
	s_cselect_b32 s1, s46, s12
	s_ashr_i32 s43, s42, 31
	s_lshl_b64 s[14:15], s[42:43], 20
	s_add_u32 s48, s36, s14
	s_addc_u32 s49, s37, s15
	s_and_b64 s[14:15], vcc, exec
	s_cselect_b32 s9, s49, s3
	s_cselect_b32 s11, s48, s2
	s_add_u32 s16, s2, 0x100
	s_addc_u32 s17, s3, 0
	s_add_u32 s12, s12, 0x80080
	v_mov_b32_e32 v0, 0
	s_addc_u32 s13, s13, 0
	s_mov_b32 s18, -2
	v_mov_b32_e32 v1, v0
	v_mov_b32_e32 v2, v0
	v_mov_b32_e32 v3, v0
	v_mov_b32_e32 v4, v0
	v_mov_b32_e32 v5, v0
	v_mov_b32_e32 v6, v0
	v_mov_b32_e32 v7, v0
	v_mov_b32_e32 v44, v0
	v_mov_b32_e32 v45, v0
	v_mov_b32_e32 v46, v0
	v_mov_b32_e32 v47, v0
	v_mov_b32_e32 v48, v0
	v_mov_b32_e32 v49, v0
	v_mov_b32_e32 v50, v0
	v_mov_b32_e32 v51, v0
	v_mov_b32_e32 v60, v0
	v_mov_b32_e32 v61, v0
	v_mov_b32_e32 v62, v0
	v_mov_b32_e32 v63, v0
	v_mov_b32_e32 v64, v0
	v_mov_b32_e32 v65, v0
	v_mov_b32_e32 v66, v0
	v_mov_b32_e32 v67, v0
	v_mov_b32_e32 v76, v0
	v_mov_b32_e32 v77, v0
	v_mov_b32_e32 v78, v0
	v_mov_b32_e32 v79, v0
	v_mov_b32_e32 v80, v0
	v_mov_b32_e32 v81, v0
	v_mov_b32_e32 v82, v0
	v_mov_b32_e32 v83, v0
	v_mov_b32_e32 v8, v0
	v_mov_b32_e32 v9, v0
	v_mov_b32_e32 v10, v0
	v_mov_b32_e32 v11, v0
	v_mov_b32_e32 v12, v0
	v_mov_b32_e32 v13, v0
	v_mov_b32_e32 v14, v0
	v_mov_b32_e32 v15, v0
	v_mov_b32_e32 v52, v0
	v_mov_b32_e32 v53, v0
	v_mov_b32_e32 v54, v0
	v_mov_b32_e32 v55, v0
	v_mov_b32_e32 v56, v0
	v_mov_b32_e32 v57, v0
	v_mov_b32_e32 v58, v0
	v_mov_b32_e32 v59, v0
	v_mov_b32_e32 v68, v0
	v_mov_b32_e32 v69, v0
	v_mov_b32_e32 v70, v0
	v_mov_b32_e32 v71, v0
	v_mov_b32_e32 v72, v0
	v_mov_b32_e32 v73, v0
	v_mov_b32_e32 v74, v0
	v_mov_b32_e32 v75, v0
	v_mov_b32_e32 v84, v0
	v_mov_b32_e32 v85, v0
	v_mov_b32_e32 v86, v0
	v_mov_b32_e32 v87, v0
	v_mov_b32_e32 v88, v0
	v_mov_b32_e32 v89, v0
	v_mov_b32_e32 v90, v0
	v_mov_b32_e32 v91, v0
	v_mov_b32_e32 v92, v0
	v_mov_b32_e32 v93, v0
	v_mov_b32_e32 v94, v0
	v_mov_b32_e32 v95, v0
	v_mov_b32_e32 v96, v0
	v_mov_b32_e32 v97, v0
	v_mov_b32_e32 v98, v0
	v_mov_b32_e32 v99, v0
	v_mov_b32_e32 v112, v0
	v_mov_b32_e32 v113, v0
	v_mov_b32_e32 v114, v0
	v_mov_b32_e32 v115, v0
	v_mov_b32_e32 v116, v0
	v_mov_b32_e32 v117, v0
	v_mov_b32_e32 v118, v0
	v_mov_b32_e32 v119, v0
	v_mov_b32_e32 v128, v0
	v_mov_b32_e32 v129, v0
	v_mov_b32_e32 v130, v0
	v_mov_b32_e32 v131, v0
	v_mov_b32_e32 v132, v0
	v_mov_b32_e32 v133, v0
	v_mov_b32_e32 v134, v0
	v_mov_b32_e32 v135, v0
	v_mov_b32_e32 v144, v0
	v_mov_b32_e32 v145, v0
	v_mov_b32_e32 v146, v0
	v_mov_b32_e32 v147, v0
	v_mov_b32_e32 v148, v0
	v_mov_b32_e32 v149, v0
	v_mov_b32_e32 v150, v0
	v_mov_b32_e32 v151, v0
	v_mov_b32_e32 v100, v0
	v_mov_b32_e32 v101, v0
	v_mov_b32_e32 v102, v0
	v_mov_b32_e32 v103, v0
	v_mov_b32_e32 v104, v0
	v_mov_b32_e32 v105, v0
	v_mov_b32_e32 v106, v0
	v_mov_b32_e32 v107, v0
	v_mov_b32_e32 v120, v0
	v_mov_b32_e32 v121, v0
	v_mov_b32_e32 v122, v0
	v_mov_b32_e32 v123, v0
	v_mov_b32_e32 v124, v0
	v_mov_b32_e32 v125, v0
	v_mov_b32_e32 v126, v0
	v_mov_b32_e32 v127, v0
	v_mov_b32_e32 v136, v0
	v_mov_b32_e32 v137, v0
	v_mov_b32_e32 v138, v0
	v_mov_b32_e32 v139, v0
	v_mov_b32_e32 v140, v0
	v_mov_b32_e32 v141, v0
	v_mov_b32_e32 v142, v0
	v_mov_b32_e32 v143, v0
	v_mov_b32_e32 v152, v0
	v_mov_b32_e32 v153, v0
	v_mov_b32_e32 v154, v0
	v_mov_b32_e32 v155, v0
	v_mov_b32_e32 v156, v0
	v_mov_b32_e32 v157, v0
	v_mov_b32_e32 v158, v0
	v_mov_b32_e32 v159, v0
	s_mul_i32 s100, s75, 0x1e00
	v_add_u32_e32 v246, s100, v232
	v_readlane_b32 s98, v255, 49
	v_readlane_b32 s99, v255, 50
	v_readlane_b32 s100, v255, 51
	v_readlane_b32 s101, v255, 52
.LBB0_672:
	s_cmp_eq_u32 s18, -2
	s_cbranch_scc1 .Lkcp_skip_672
	global_store_dwordx4 v247, v[248:251], s[100:101] nt
.Lkcp_skip_672:
	s_add_u32 s2, s12, 0xfff80080
	s_addc_u32 s3, s13, -1
	s_add_i32 s19, 0, 0x10000
	v_add_u32_e32 v28, s19, v228
	ds_read_b128 v[16:19], v28
	ds_read_b128 v[20:23], v28 offset:1024
	ds_read_b128 v[24:27], v28 offset:2048
	ds_read_b128 v[28:31], v28 offset:3072
	s_cmp_eq_u32 s18, 28
	s_cselect_b32 s15, s0, s3
	s_cselect_b32 s14, s1, s2
	s_cselect_b32 s3, s9, s17
	s_cselect_b32 s2, s11, s16
	v_lshl_add_u64 v[160:161], s[12:13], 0, v[174:175]
	s_add_i32 m0, s69, 0xc000
	ds_read_b128 v[32:35], v231
	ds_read_b128 v[36:39], v231 offset:1024
	ds_read_b128 v[40:43], v231 offset:2048
	ds_read_b128 v[108:111], v231 offset:3072
	ds_read_b128 v[176:179], v231 offset:4096
	ds_read_b128 v[180:183], v231 offset:5120
	ds_read_b128 v[184:187], v231 offset:6144
	ds_read_b128 v[194:197], v231 offset:7168
	global_load_lds_dwordx4 v[160:161], off
	v_lshl_add_u64 v[160:161], s[12:13], 0, v[172:173]
	s_add_i32 m0, s69, 0xe000
	s_nop 0
	global_load_lds_dwordx4 v[160:161], off
	s_waitcnt lgkmcnt(8)
	s_barrier
	s_waitcnt lgkmcnt(0)
	s_setprio 1
	s_waitcnt lgkmcnt(0)
	v_mfma_f32_16x16x32_bf16 v[156:159], v[16:19], v[32:35], v[156:159]
	v_mfma_f32_16x16x32_bf16 v[152:155], v[24:27], v[32:35], v[152:155]
	v_mfma_f32_16x16x32_bf16 v[140:143], v[16:19], v[40:43], v[140:143]
	v_mfma_f32_16x16x32_bf16 v[136:139], v[24:27], v[40:43], v[136:139]
	v_mfma_f32_16x16x32_bf16 v[124:127], v[16:19], v[176:179], v[124:127]
	v_mfma_f32_16x16x32_bf16 v[120:123], v[24:27], v[176:179], v[120:123]
	v_mfma_f32_16x16x32_bf16 v[104:107], v[16:19], v[184:187], v[104:107]
	v_mfma_f32_16x16x32_bf16 v[100:103], v[24:27], v[184:187], v[100:103]
	v_mfma_f32_16x16x32_bf16 v[156:159], v[20:23], v[36:39], v[156:159]
	v_mfma_f32_16x16x32_bf16 v[152:155], v[28:31], v[36:39], v[152:155]
	v_mfma_f32_16x16x32_bf16 v[140:143], v[20:23], v[108:111], v[140:143]
	v_mfma_f32_16x16x32_bf16 v[136:139], v[28:31], v[108:111], v[136:139]
	v_mfma_f32_16x16x32_bf16 v[124:127], v[20:23], v[180:183], v[124:127]
	v_mfma_f32_16x16x32_bf16 v[120:123], v[28:31], v[180:183], v[120:123]
	v_mfma_f32_16x16x32_bf16 v[104:107], v[20:23], v[194:197], v[104:107]
	v_mfma_f32_16x16x32_bf16 v[100:103], v[28:31], v[194:197], v[100:103]
	s_setprio 0
	s_barrier
	s_add_i32 s33, 0, 0x14000
	v_add_u32_e32 v160, s33, v228
	s_add_i32 s19, s19, s68
	ds_read_b128 v[198:201], v160
	ds_read_b128 v[202:205], v160 offset:1024
	ds_read_b128 v[206:209], v160 offset:2048
	ds_read_b128 v[210:213], v160 offset:3072
	v_lshl_add_u64 v[160:161], s[2:3], 0, v[164:165]
	s_mov_b32 m0, s19
	v_lshl_add_u64 v[222:223], s[2:3], 0, v[168:169]
	global_load_lds_dwordx4 v[160:161], off
	s_add_i32 m0, s19, 0x2000
	s_nop 0
	global_load_lds_dwordx4 v[222:223], off
	v_min_u32_e32 v247, 0x1feff, v246
	v_lshlrev_b32_e32 v247, 4, v247
	v_add_u32_e32 v246, 0x200, v246
	global_load_dwordx4 v[248:251], v247, s[98:99] nt
	s_barrier
	s_waitcnt lgkmcnt(0)
	s_setprio 1
	s_waitcnt lgkmcnt(0)
	v_mfma_f32_16x16x32_bf16 v[148:151], v[198:201], v[32:35], v[148:151]
	v_mfma_f32_16x16x32_bf16 v[32:35], v[206:209], v[32:35], v[144:147]
	v_mfma_f32_16x16x32_bf16 v[148:151], v[202:205], v[36:39], v[148:151]
	v_mfma_f32_16x16x32_bf16 v[32:35], v[210:213], v[36:39], v[32:35]
	v_mfma_f32_16x16x32_bf16 v[36:39], v[198:201], v[40:43], v[132:135]
	v_mfma_f32_16x16x32_bf16 v[40:43], v[206:209], v[40:43], v[128:131]
	v_mfma_f32_16x16x32_bf16 v[112:115], v[206:209], v[176:179], v[112:115]
	v_mfma_f32_16x16x32_bf16 v[96:99], v[198:201], v[184:187], v[96:99]
	v_mfma_f32_16x16x32_bf16 v[92:95], v[206:209], v[184:187], v[92:95]
	v_mfma_f32_16x16x32_bf16 v[36:39], v[202:205], v[108:111], v[36:39]
	v_mfma_f32_16x16x32_bf16 v[40:43], v[210:213], v[108:111], v[40:43]
	v_mfma_f32_16x16x32_bf16 v[108:111], v[198:201], v[176:179], v[116:119]
	v_mfma_f32_16x16x32_bf16 v[112:115], v[210:213], v[180:183], v[112:115]
	v_mfma_f32_16x16x32_bf16 v[96:99], v[202:205], v[194:197], v[96:99]
	v_mfma_f32_16x16x32_bf16 v[92:95], v[210:213], v[194:197], v[92:95]
	v_mfma_f32_16x16x32_bf16 v[108:111], v[202:205], v[180:183], v[108:111]
	s_setprio 0
	s_mov_b32 m0, s69
	v_lshl_add_u64 v[224:225], s[14:15], 0, v[162:163]
	s_barrier
	ds_read_b128 v[116:119], v231 offset:16384
	ds_read_b128 v[128:131], v231 offset:17408
	ds_read_b128 v[132:135], v231 offset:18432
	ds_read_b128 v[144:147], v231 offset:19456
	ds_read_b128 v[176:179], v231 offset:20480
	ds_read_b128 v[180:183], v231 offset:21504
	ds_read_b128 v[184:187], v231 offset:22528
	ds_read_b128 v[194:197], v231 offset:23552
	global_load_lds_dwordx4 v[224:225], off
	v_lshl_add_u64 v[226:227], s[14:15], 0, v[166:167]
	s_mov_b32 m0, s70
	s_nop 0
	global_load_lds_dwordx4 v[226:227], off
	s_barrier
	s_waitcnt lgkmcnt(0)
	s_setprio 1
	s_waitcnt lgkmcnt(0)
	v_mfma_f32_16x16x32_bf16 v[88:91], v[16:19], v[116:119], v[88:91]
	v_mfma_f32_16x16x32_bf16 v[84:87], v[24:27], v[116:119], v[84:87]
	v_mfma_f32_16x16x32_bf16 v[72:75], v[16:19], v[132:135], v[72:75]
	v_mfma_f32_16x16x32_bf16 v[68:71], v[24:27], v[132:135], v[68:71]
	v_mfma_f32_16x16x32_bf16 v[56:59], v[16:19], v[176:179], v[56:59]
	v_mfma_f32_16x16x32_bf16 v[52:55], v[24:27], v[176:179], v[52:55]
	v_mfma_f32_16x16x32_bf16 v[12:15], v[16:19], v[184:187], v[12:15]
	v_mfma_f32_16x16x32_bf16 v[8:11], v[24:27], v[184:187], v[8:11]
	v_mfma_f32_16x16x32_bf16 v[88:91], v[20:23], v[128:131], v[88:91]
	v_mfma_f32_16x16x32_bf16 v[84:87], v[28:31], v[128:131], v[84:87]
	v_mfma_f32_16x16x32_bf16 v[72:75], v[20:23], v[144:147], v[72:75]
	v_mfma_f32_16x16x32_bf16 v[68:71], v[28:31], v[144:147], v[68:71]
	v_mfma_f32_16x16x32_bf16 v[56:59], v[20:23], v[180:183], v[56:59]
	v_mfma_f32_16x16x32_bf16 v[52:55], v[28:31], v[180:183], v[52:55]
	v_mfma_f32_16x16x32_bf16 v[12:15], v[20:23], v[194:197], v[12:15]
	v_mfma_f32_16x16x32_bf16 v[8:11], v[28:31], v[194:197], v[8:11]
	s_setprio 0
	s_barrier
	s_add_u32 s20, s2, 0x80000
	s_addc_u32 s21, s3, 0
	s_add_i32 s19, s33, s68
	v_lshl_add_u64 v[16:17], s[20:21], 0, v[164:165]
	s_mov_b32 m0, s19
	s_nop 0
	global_load_lds_dwordx4 v[16:17], off
	v_lshl_add_u64 v[16:17], s[20:21], 0, v[168:169]
	s_add_i32 m0, s19, 0x2000
	s_nop 0
	global_load_lds_dwordx4 v[16:17], off
	s_waitcnt vmcnt(7)
	s_barrier
	s_setprio 1
	v_mfma_f32_16x16x32_bf16 v[48:51], v[198:201], v[176:179], v[48:51]
	v_mfma_f32_16x16x32_bf16 v[44:47], v[206:209], v[176:179], v[44:47]
	v_mfma_f32_16x16x32_bf16 v[4:7], v[198:201], v[184:187], v[4:7]
	v_mfma_f32_16x16x32_bf16 v[0:3], v[206:209], v[184:187], v[0:3]
	v_mfma_f32_16x16x32_bf16 v[16:19], v[198:201], v[116:119], v[80:83]
	v_mfma_f32_16x16x32_bf16 v[20:23], v[206:209], v[116:119], v[76:79]
	v_mfma_f32_16x16x32_bf16 v[24:27], v[198:201], v[132:135], v[64:67]
	v_mfma_f32_16x16x32_bf16 v[28:31], v[206:209], v[132:135], v[60:63]
	v_mfma_f32_16x16x32_bf16 v[48:51], v[202:205], v[180:183], v[48:51]
	v_mfma_f32_16x16x32_bf16 v[44:47], v[210:213], v[180:183], v[44:47]
	v_mfma_f32_16x16x32_bf16 v[4:7], v[202:205], v[194:197], v[4:7]
	v_mfma_f32_16x16x32_bf16 v[0:3], v[210:213], v[194:197], v[0:3]
	v_mfma_f32_16x16x32_bf16 v[16:19], v[202:205], v[128:131], v[16:19]
	v_mfma_f32_16x16x32_bf16 v[20:23], v[210:213], v[128:131], v[20:23]
	v_mfma_f32_16x16x32_bf16 v[24:27], v[202:205], v[144:147], v[24:27]
	v_mfma_f32_16x16x32_bf16 v[28:31], v[210:213], v[144:147], v[28:31]
	s_setprio 0
	s_add_i32 s19, 0, 0x18000
	v_add_u32_e32 v80, s19, v228
	s_barrier
	ds_read_b128 v[60:63], v80
	ds_read_b128 v[64:67], v80 offset:1024
	ds_read_b128 v[76:79], v80 offset:2048
	ds_read_b128 v[80:83], v80 offset:3072
	s_add_u32 s14, s14, 0x80000
	s_addc_u32 s15, s15, 0
	s_mov_b32 m0, s71
	v_lshl_add_u64 v[132:133], s[14:15], 0, v[162:163]
	ds_read_b128 v[116:119], v231 offset:32768
	ds_read_b128 v[128:131], v231 offset:33792
	ds_read_b128 v[176:179], v231 offset:34816
	ds_read_b128 v[180:183], v231 offset:35840
	ds_read_b128 v[184:187], v231 offset:36864
	ds_read_b128 v[194:197], v231 offset:37888
	ds_read_b128 v[198:201], v231 offset:38912
	ds_read_b128 v[202:205], v231 offset:39936
	global_load_lds_dwordx4 v[132:133], off
	v_lshl_add_u64 v[132:133], s[14:15], 0, v[166:167]
	s_mov_b32 m0, s74
	s_nop 0
	global_load_lds_dwordx4 v[132:133], off
	s_waitcnt lgkmcnt(8)
	s_barrier
	s_waitcnt lgkmcnt(0)
	s_setprio 1
	s_waitcnt lgkmcnt(0)
	v_mfma_f32_16x16x32_bf16 v[132:135], v[60:63], v[116:119], v[156:159]
	v_mfma_f32_16x16x32_bf16 v[156:159], v[64:67], v[128:131], v[132:135]
	v_mfma_f32_16x16x32_bf16 v[132:135], v[76:79], v[116:119], v[152:155]
	v_mfma_f32_16x16x32_bf16 v[152:155], v[80:83], v[128:131], v[132:135]
	v_mfma_f32_16x16x32_bf16 v[132:135], v[60:63], v[176:179], v[140:143]
	v_mfma_f32_16x16x32_bf16 v[140:143], v[64:67], v[180:183], v[132:135]
	v_mfma_f32_16x16x32_bf16 v[132:135], v[76:79], v[176:179], v[136:139]
	v_mfma_f32_16x16x32_bf16 v[124:127], v[60:63], v[184:187], v[124:127]
	v_mfma_f32_16x16x32_bf16 v[120:123], v[76:79], v[184:187], v[120:123]
	v_mfma_f32_16x16x32_bf16 v[104:107], v[60:63], v[198:201], v[104:107]
	v_mfma_f32_16x16x32_bf16 v[100:103], v[76:79], v[198:201], v[100:103]
	v_mfma_f32_16x16x32_bf16 v[136:139], v[80:83], v[180:183], v[132:135]
	v_mfma_f32_16x16x32_bf16 v[124:127], v[64:67], v[194:197], v[124:127]
	v_mfma_f32_16x16x32_bf16 v[120:123], v[80:83], v[194:197], v[120:123]
	v_mfma_f32_16x16x32_bf16 v[104:107], v[64:67], v[202:205], v[104:107]
	v_mfma_f32_16x16x32_bf16 v[100:103], v[80:83], v[202:205], v[100:103]
	s_setprio 0
	s_barrier
	s_add_i32 s14, 0, 0x1c000
	v_add_u32_e32 v132, s14, v228
	s_add_i32 s15, s19, s68
	ds_read_b128 v[206:209], v132
	ds_read_b128 v[210:213], v132 offset:1024
	ds_read_b128 v[214:217], v132 offset:2048
	ds_read_b128 v[218:221], v132 offset:3072
	v_lshl_add_u64 v[132:133], v[160:161], 0, s[88:89]
	s_mov_b32 m0, s15
	s_nop 0
	global_load_lds_dwordx4 v[132:133], off
	v_lshl_add_u64 v[132:133], v[222:223], 0, s[88:89]
	s_add_i32 m0, s15, 0x2000
	s_nop 0
	global_load_lds_dwordx4 v[132:133], off
	s_barrier
	s_waitcnt lgkmcnt(0)
	s_setprio 1
	s_waitcnt lgkmcnt(0)
	v_mfma_f32_16x16x32_bf16 v[32:35], v[214:217], v[116:119], v[32:35]
	v_mfma_f32_16x16x32_bf16 v[132:135], v[206:209], v[116:119], v[148:151]
	v_mfma_f32_16x16x32_bf16 v[144:147], v[218:221], v[128:131], v[32:35]
	v_mfma_f32_16x16x32_bf16 v[32:35], v[206:209], v[176:179], v[36:39]
	v_mfma_f32_16x16x32_bf16 v[148:151], v[210:213], v[128:131], v[132:135]
	v_mfma_f32_16x16x32_bf16 v[132:135], v[210:213], v[180:183], v[32:35]
	v_mfma_f32_16x16x32_bf16 v[32:35], v[214:217], v[176:179], v[40:43]
	v_mfma_f32_16x16x32_bf16 v[128:131], v[218:221], v[180:183], v[32:35]
	v_mfma_f32_16x16x32_bf16 v[32:35], v[206:209], v[184:187], v[108:111]
	v_mfma_f32_16x16x32_bf16 v[116:119], v[210:213], v[194:197], v[32:35]
	v_mfma_f32_16x16x32_bf16 v[32:35], v[214:217], v[184:187], v[112:115]
	v_mfma_f32_16x16x32_bf16 v[112:115], v[218:221], v[194:197], v[32:35]
	v_mfma_f32_16x16x32_bf16 v[32:35], v[206:209], v[198:201], v[96:99]
	v_mfma_f32_16x16x32_bf16 v[96:99], v[210:213], v[202:205], v[32:35]
	v_mfma_f32_16x16x32_bf16 v[32:35], v[214:217], v[198:201], v[92:95]
	v_mfma_f32_16x16x32_bf16 v[92:95], v[218:221], v[202:205], v[32:35]
	s_setprio 0
	s_mov_b32 m0, s79
	v_lshl_add_u64 v[160:161], v[224:225], 0, s[88:89]
	s_barrier
	s_nop 2
	ds_read_b128 v[32:35], v231 offset:49152
	ds_read_b128 v[36:39], v231 offset:50176
	ds_read_b128 v[40:43], v231 offset:51200
	ds_read_b128 v[108:111], v231 offset:52224
	ds_read_b128 v[176:179], v231 offset:53248
	ds_read_b128 v[180:183], v231 offset:54272
	ds_read_b128 v[184:187], v231 offset:55296
	ds_read_b128 v[194:197], v231 offset:56320
	global_load_lds_dwordx4 v[160:161], off
	v_lshl_add_u64 v[160:161], v[226:227], 0, s[88:89]
	s_mov_b32 m0, s80
	s_nop 0
	global_load_lds_dwordx4 v[160:161], off
	s_barrier
	s_waitcnt lgkmcnt(0)
	s_setprio 1
	s_waitcnt lgkmcnt(0)
	v_mfma_f32_16x16x32_bf16 v[88:91], v[60:63], v[32:35], v[88:91]
	v_mfma_f32_16x16x32_bf16 v[84:87], v[76:79], v[32:35], v[84:87]
	v_mfma_f32_16x16x32_bf16 v[72:75], v[60:63], v[40:43], v[72:75]
	v_mfma_f32_16x16x32_bf16 v[68:71], v[76:79], v[40:43], v[68:71]
	v_mfma_f32_16x16x32_bf16 v[56:59], v[60:63], v[176:179], v[56:59]
	v_mfma_f32_16x16x32_bf16 v[52:55], v[76:79], v[176:179], v[52:55]
	v_mfma_f32_16x16x32_bf16 v[12:15], v[60:63], v[184:187], v[12:15]
	v_mfma_f32_16x16x32_bf16 v[8:11], v[76:79], v[184:187], v[8:11]
	v_mfma_f32_16x16x32_bf16 v[88:91], v[64:67], v[36:39], v[88:91]
	v_mfma_f32_16x16x32_bf16 v[84:87], v[80:83], v[36:39], v[84:87]
	v_mfma_f32_16x16x32_bf16 v[72:75], v[64:67], v[108:111], v[72:75]
	v_mfma_f32_16x16x32_bf16 v[68:71], v[80:83], v[108:111], v[68:71]
	v_mfma_f32_16x16x32_bf16 v[56:59], v[64:67], v[180:183], v[56:59]
	v_mfma_f32_16x16x32_bf16 v[52:55], v[80:83], v[180:183], v[52:55]
	v_mfma_f32_16x16x32_bf16 v[12:15], v[64:67], v[194:197], v[12:15]
	v_mfma_f32_16x16x32_bf16 v[8:11], v[80:83], v[194:197], v[8:11]
	s_setprio 0
	s_barrier
	s_add_u32 s2, s2, 0x80080
	s_addc_u32 s3, s3, 0
	s_add_i32 s14, s14, s68
	v_lshl_add_u64 v[60:61], s[2:3], 0, v[164:165]
	s_mov_b32 m0, s14
	s_nop 0
	global_load_lds_dwordx4 v[60:61], off
	v_lshl_add_u64 v[60:61], s[2:3], 0, v[168:169]
	s_add_i32 m0, s14, 0x2000
	s_nop 0
	global_load_lds_dwordx4 v[60:61], off
	s_waitcnt vmcnt(6)
	s_barrier
	s_setprio 1
	v_mfma_f32_16x16x32_bf16 v[16:19], v[206:209], v[32:35], v[16:19]
	v_mfma_f32_16x16x32_bf16 v[80:83], v[210:213], v[36:39], v[16:19]
	v_mfma_f32_16x16x32_bf16 v[16:19], v[214:217], v[32:35], v[20:23]
	v_mfma_f32_16x16x32_bf16 v[76:79], v[218:221], v[36:39], v[16:19]
	v_mfma_f32_16x16x32_bf16 v[16:19], v[206:209], v[40:43], v[24:27]
	v_mfma_f32_16x16x32_bf16 v[64:67], v[210:213], v[108:111], v[16:19]
	v_mfma_f32_16x16x32_bf16 v[16:19], v[214:217], v[40:43], v[28:31]
	v_mfma_f32_16x16x32_bf16 v[60:63], v[218:221], v[108:111], v[16:19]
	v_mfma_f32_16x16x32_bf16 v[16:19], v[206:209], v[176:179], v[48:51]
	v_mfma_f32_16x16x32_bf16 v[48:51], v[210:213], v[180:183], v[16:19]
	v_mfma_f32_16x16x32_bf16 v[16:19], v[214:217], v[176:179], v[44:47]
	v_mfma_f32_16x16x32_bf16 v[4:7], v[206:209], v[184:187], v[4:7]
	v_mfma_f32_16x16x32_bf16 v[0:3], v[214:217], v[184:187], v[0:3]
	v_mfma_f32_16x16x32_bf16 v[44:47], v[218:221], v[180:183], v[16:19]
	v_mfma_f32_16x16x32_bf16 v[4:7], v[210:213], v[194:197], v[4:7]
	v_mfma_f32_16x16x32_bf16 v[0:3], v[218:221], v[194:197], v[0:3]
	s_setprio 0
	s_add_i32 s18, s18, 2
	s_add_u32 s16, s16, 0x100
	s_addc_u32 s17, s17, 0
	s_add_u32 s12, s12, 0x100
	s_addc_u32 s13, s13, 0
	s_cmp_gt_u32 s18, 29
	s_barrier
	s_cbranch_scc0 .LBB0_672
	s_lshl_b32 s14, s8, 8
	s_add_i32 s14, s14, s78
	v_or_b32_e32 v176, s14, v171
	v_ashrrev_i32_e32 v177, 31, v176
	v_lshl_add_u64 v[16:17], v[176:177], 2, s[28:29]
	global_load_dword v220, v[16:17], off
	global_load_dword v216, v[16:17], off offset:64
	global_load_dword v212, v[16:17], off offset:128
	global_load_dword v208, v[16:17], off offset:192
	global_load_dword v184, v[16:17], off offset:512
	global_load_dword v182, v[16:17], off offset:576
	global_load_dword v180, v[16:17], off offset:640
	global_load_dword v178, v[16:17], off offset:704
	v_or_b32_e32 v218, 16, v176
	v_ashrrev_i32_e32 v219, 31, v218
	v_or_b32_e32 v214, 32, v176
	v_ashrrev_i32_e32 v215, 31, v214
	v_or_b32_e32 v210, 48, v176
	v_ashrrev_i32_e32 v211, 31, v210
	s_mul_i32 s0, s75, 0x1e00
	v_add_u32_e32 v179, s0, v230
	v_min_i32_e32 v206, 0x1feff, v179
	v_min_i32_e32 v204, 0x1fcff, v179
	v_min_i32_e32 v202, 0x1faff, v179
	v_min_i32_e32 v200, 0x1f8ff, v179
	v_min_i32_e32 v198, 0x1f6ff, v179
	v_min_i32_e32 v196, 0x1f4ff, v179
	v_min_i32_e32 v194, 0x1f2ff, v179
	v_min_i32_e32 v186, 0x1f0ff, v179
	v_ashrrev_i32_e32 v207, 31, v206
	v_ashrrev_i32_e32 v205, 31, v204
	v_ashrrev_i32_e32 v203, 31, v202
	v_ashrrev_i32_e32 v201, 31, v200
	v_ashrrev_i32_e32 v199, 31, v198
	v_ashrrev_i32_e32 v197, 31, v196
	v_ashrrev_i32_e32 v195, 31, v194
	v_ashrrev_i32_e32 v187, 31, v186
	s_waitcnt vmcnt(0)
	v_fmamk_f32 v18, v220, 0x3a000000, v233
	v_cmp_gt_f32_e32 vcc, s96, v18
	v_mul_f32_e32 v19, 0x4b800000, v18
	s_nop 0
	v_cndmask_b32_e32 v18, v18, v19, vcc
	v_rsq_f32_e32 v18, v18
	s_nop 0
	v_mul_f32_e32 v19, 0x45800000, v18
	v_cndmask_b32_e32 v220, v18, v19, vcc
	v_fmamk_f32 v18, v216, 0x3a000000, v233
	v_cmp_gt_f32_e32 vcc, s96, v18
	v_mul_f32_e32 v19, 0x4b800000, v18
	s_nop 0
	v_cndmask_b32_e32 v18, v18, v19, vcc
	v_rsq_f32_e32 v18, v18
	s_nop 0
	v_mul_f32_e32 v19, 0x45800000, v18
	v_cndmask_b32_e32 v216, v18, v19, vcc
	v_fmamk_f32 v18, v212, 0x3a000000, v233
	v_cmp_gt_f32_e32 vcc, s96, v18
	v_mul_f32_e32 v19, 0x4b800000, v18
	s_nop 0
	v_cndmask_b32_e32 v18, v18, v19, vcc
	v_rsq_f32_e32 v18, v18
	s_nop 0
	v_mul_f32_e32 v19, 0x45800000, v18
	v_cndmask_b32_e32 v212, v18, v19, vcc
	v_fmamk_f32 v18, v208, 0x3a000000, v233
	v_cmp_gt_f32_e32 vcc, s96, v18
	v_mul_f32_e32 v19, 0x4b800000, v18
	s_nop 0
	v_cndmask_b32_e32 v18, v18, v19, vcc
	v_rsq_f32_e32 v18, v18
	s_nop 0
	v_mul_f32_e32 v19, 0x45800000, v18
	v_cndmask_b32_e32 v208, v18, v19, vcc
	v_fmamk_f32 v18, v184, 0x3a000000, v233
	v_cmp_gt_f32_e32 vcc, s96, v18
	v_mul_f32_e32 v19, 0x4b800000, v18
	s_nop 0
	v_cndmask_b32_e32 v18, v18, v19, vcc
	v_rsq_f32_e32 v18, v18
	s_nop 0
	v_mul_f32_e32 v19, 0x45800000, v18
	v_cndmask_b32_e32 v184, v18, v19, vcc
	v_fmamk_f32 v18, v182, 0x3a000000, v233
	v_cmp_gt_f32_e32 vcc, s96, v18
	v_mul_f32_e32 v19, 0x4b800000, v18
	s_nop 0
	v_cndmask_b32_e32 v18, v18, v19, vcc
	v_rsq_f32_e32 v18, v18
	s_nop 0
	v_mul_f32_e32 v19, 0x45800000, v18
	v_cndmask_b32_e32 v182, v18, v19, vcc
	v_fmamk_f32 v18, v180, 0x3a000000, v233
	v_cmp_gt_f32_e32 vcc, s96, v18
	v_mul_f32_e32 v19, 0x4b800000, v18
	s_nop 0
	v_cndmask_b32_e32 v18, v18, v19, vcc
	v_rsq_f32_e32 v18, v18
	s_nop 0
	v_mul_f32_e32 v19, 0x45800000, v18
	v_cndmask_b32_e32 v180, v18, v19, vcc
	v_fmamk_f32 v18, v178, 0x3a000000, v233
	v_cmp_gt_f32_e32 vcc, s96, v18
	v_mul_f32_e32 v19, 0x4b800000, v18
	s_nop 0
	v_cndmask_b32_e32 v18, v18, v19, vcc
	v_rsq_f32_e32 v18, v18
	s_nop 0
	v_mul_f32_e32 v19, 0x45800000, v18
	v_cndmask_b32_e32 v178, v18, v19, vcc
	v_cndmask_b32_e64 v16, 0, 1, s[38:39]
	v_cmp_ne_u32_e64 s[8:9], 1, v16
	s_andn2_b64 vcc, exec, s[38:39]
	s_cbranch_vccnz .LBB0_675
	v_lshl_add_u64 v[18:19], v[204:205], 4, s[26:27]
	v_lshl_add_u64 v[16:17], v[206:207], 4, s[26:27]
	v_add_co_u32_e32 v18, vcc, 0x2000, v18
	v_lshl_add_u64 v[20:21], v[194:195], 4, s[26:27]
	s_nop 0
	v_addc_co_u32_e32 v19, vcc, 0, v19, vcc
	global_load_dwordx4 v[40:43], v[16:17], off nt
	global_load_dwordx4 v[28:31], v[18:19], off nt
	v_lshl_add_u64 v[16:17], v[202:203], 4, s[26:27]
	v_add_co_u32_e32 v16, vcc, 0x4000, v16
	v_lshl_add_u64 v[18:19], v[200:201], 4, s[26:27]
	s_nop 0
	v_addc_co_u32_e32 v17, vcc, 0, v17, vcc
	v_add_co_u32_e32 v18, vcc, 0x6000, v18
	v_lshl_add_u64 v[22:23], v[186:187], 4, s[26:27]
	s_nop 0
	v_addc_co_u32_e32 v19, vcc, 0, v19, vcc
	global_load_dwordx4 v[36:39], v[16:17], off nt
	global_load_dwordx4 v[24:27], v[18:19], off nt
	v_lshl_add_u64 v[16:17], v[198:199], 4, s[26:27]
	v_add_co_u32_e32 v16, vcc, 0x8000, v16
	v_lshl_add_u64 v[18:19], v[196:197], 4, s[26:27]
	s_nop 0
	v_addc_co_u32_e32 v17, vcc, 0, v17, vcc
	v_add_co_u32_e32 v18, vcc, 0xa000, v18
	s_nop 1
	v_addc_co_u32_e32 v19, vcc, 0, v19, vcc
	v_add_co_u32_e32 v20, vcc, 0xc000, v20
	global_load_dwordx4 v[32:35], v[16:17], off nt
	s_nop 0
	global_load_dwordx4 v[16:19], v[18:19], off nt
	v_addc_co_u32_e32 v21, vcc, 0, v21, vcc
	v_add_co_u32_e32 v108, vcc, 0xe000, v22
	s_nop 1
	v_addc_co_u32_e32 v109, vcc, 0, v23, vcc
	global_load_dwordx4 v[20:23], v[20:21], off nt
	s_nop 0
	global_load_dwordx4 v[108:111], v[108:109], off nt
	s_branch .LBB0_676

.LBB0_1258:
	s_or_b64 exec, exec, s[4:5]
	s_mov_b64 s[0:1], s[80:81]
	s_waitcnt lgkmcnt(0)
	s_barrier
	s_load_dwordx2 s[10:11], s[0:1], 0x80
	s_mov_b32 s42, s76
	s_mov_b32 s43, s73
	s_mov_b64 s[18:19], 0
	s_cmp_eq_u32 s42, s42
	s_mov_b64 s[16:17], 0
	s_cbranch_scc1 .LBB0_1260
	s_and_b32 s4, s43, 7
	s_cmpk_lt_u32 s43, 0x80
	s_cselect_b32 s2, 32, 40
	s_mov_b32 s3, 0x8194000
	s_cselect_b32 s5, s3, 0x1c194000
	s_add_u32 s2, s0, s2
	s_addc_u32 s3, s1, 0
	s_load_dwordx2 s[2:3], s[2:3], 0x0
	s_lshl_b32 s6, s43, 21
	s_and_b32 s6, s6, 0xf000000
	s_load_dwordx2 s[0:1], s[0:1], 0x78
	s_mul_i32 s4, s4, 0x1ff000
	s_waitcnt lgkmcnt(0)
	s_add_u32 s2, s2, s6
	s_addc_u32 s3, s3, 0
	s_add_u32 s2, s2, s4
	s_addc_u32 s3, s3, 0
	s_add_u32 s16, s2, 0x8000
	s_addc_u32 s17, s3, 0
	s_add_u32 s0, s0, s5
	s_addc_u32 s1, s1, 0
	s_add_u32 s0, s0, s6
	s_addc_u32 s1, s1, 0
	s_add_u32 s18, s0, s4
	s_addc_u32 s19, s1, 0

.LBB0_1278:
	s_ashr_i32 s29, s28, 31
	v_cmp_lt_i64_e32 vcc, s[0:1], v[192:193]
	s_lshl_b64 s[0:1], s[28:29], 20
	s_add_u32 s30, s14, s0
	s_addc_u32 s31, s15, s1
	s_and_b64 s[0:1], vcc, exec
	s_cselect_b32 s0, s31, s9
	s_cselect_b32 s1, s30, s8
	s_ashr_i32 s27, s26, 31
	s_lshl_b64 s[34:35], s[26:27], 20
	s_add_u32 s34, s12, s34
	s_addc_u32 s35, s13, s35
	s_and_b64 s[40:41], vcc, exec
	s_cselect_b32 s27, s35, s3
	s_cselect_b32 s29, s34, s2
	s_add_u32 s33, s2, 0x100
	s_addc_u32 s55, s3, 0
	s_add_u32 s8, s8, 0x80080
	v_mov_b32_e32 v0, 0
	s_addc_u32 s9, s9, 0
	s_mov_b32 s56, -2
	s_waitcnt lgkmcnt(0)
	v_mov_b32_e32 v1, v0
	v_mov_b32_e32 v2, v0
	v_mov_b32_e32 v3, v0
	v_mov_b32_e32 v4, v0
	v_mov_b32_e32 v5, v0
	v_mov_b32_e32 v6, v0
	v_mov_b32_e32 v7, v0
	v_mov_b32_e32 v16, v0
	v_mov_b32_e32 v17, v0
	v_mov_b32_e32 v18, v0
	v_mov_b32_e32 v19, v0
	v_mov_b32_e32 v20, v0
	v_mov_b32_e32 v21, v0
	v_mov_b32_e32 v22, v0
	v_mov_b32_e32 v23, v0
	v_mov_b32_e32 v32, v0
	v_mov_b32_e32 v33, v0
	v_mov_b32_e32 v34, v0
	v_mov_b32_e32 v35, v0
	v_mov_b32_e32 v36, v0
	v_mov_b32_e32 v37, v0
	v_mov_b32_e32 v38, v0
	v_mov_b32_e32 v39, v0
	v_mov_b32_e32 v48, v0
	v_mov_b32_e32 v49, v0
	v_mov_b32_e32 v50, v0
	v_mov_b32_e32 v51, v0
	v_mov_b32_e32 v52, v0
	v_mov_b32_e32 v53, v0
	v_mov_b32_e32 v54, v0
	v_mov_b32_e32 v55, v0
	v_mov_b32_e32 v8, v0
	v_mov_b32_e32 v9, v0
	v_mov_b32_e32 v10, v0
	v_mov_b32_e32 v11, v0
	v_mov_b32_e32 v12, v0
	v_mov_b32_e32 v13, v0
	v_mov_b32_e32 v14, v0
	v_mov_b32_e32 v15, v0
	v_mov_b32_e32 v24, v0
	v_mov_b32_e32 v25, v0
	v_mov_b32_e32 v26, v0
	v_mov_b32_e32 v27, v0
	v_mov_b32_e32 v28, v0
	v_mov_b32_e32 v29, v0
	v_mov_b32_e32 v30, v0
	v_mov_b32_e32 v31, v0
	v_mov_b32_e32 v40, v0
	v_mov_b32_e32 v41, v0
	v_mov_b32_e32 v42, v0
	v_mov_b32_e32 v43, v0
	v_mov_b32_e32 v44, v0
	v_mov_b32_e32 v45, v0
	v_mov_b32_e32 v46, v0
	v_mov_b32_e32 v47, v0
	v_mov_b32_e32 v56, v0
	v_mov_b32_e32 v57, v0
	v_mov_b32_e32 v58, v0
	v_mov_b32_e32 v59, v0
	v_mov_b32_e32 v60, v0
	v_mov_b32_e32 v61, v0
	v_mov_b32_e32 v62, v0
	v_mov_b32_e32 v63, v0
	v_mov_b32_e32 v92, v0
	v_mov_b32_e32 v93, v0
	v_mov_b32_e32 v94, v0
	v_mov_b32_e32 v95, v0
	v_mov_b32_e32 v96, v0
	v_mov_b32_e32 v97, v0
	v_mov_b32_e32 v98, v0
	v_mov_b32_e32 v99, v0
	v_mov_b32_e32 v108, v0
	v_mov_b32_e32 v109, v0
	v_mov_b32_e32 v110, v0
	v_mov_b32_e32 v111, v0
	v_mov_b32_e32 v112, v0
	v_mov_b32_e32 v113, v0
	v_mov_b32_e32 v114, v0
	v_mov_b32_e32 v115, v0
	v_mov_b32_e32 v124, v0
	v_mov_b32_e32 v125, v0
	v_mov_b32_e32 v126, v0
	v_mov_b32_e32 v127, v0
	v_mov_b32_e32 v128, v0
	v_mov_b32_e32 v129, v0
	v_mov_b32_e32 v130, v0
	v_mov_b32_e32 v131, v0
	v_mov_b32_e32 v140, v0
	v_mov_b32_e32 v141, v0
	v_mov_b32_e32 v142, v0
	v_mov_b32_e32 v143, v0
	v_mov_b32_e32 v144, v0
	v_mov_b32_e32 v145, v0
	v_mov_b32_e32 v146, v0
	v_mov_b32_e32 v147, v0
	v_mov_b32_e32 v100, v0
	v_mov_b32_e32 v101, v0
	v_mov_b32_e32 v102, v0
	v_mov_b32_e32 v103, v0
	v_mov_b32_e32 v104, v0
	v_mov_b32_e32 v105, v0
	v_mov_b32_e32 v106, v0
	v_mov_b32_e32 v107, v0
	v_mov_b32_e32 v116, v0
	v_mov_b32_e32 v117, v0
	v_mov_b32_e32 v118, v0
	v_mov_b32_e32 v119, v0
	v_mov_b32_e32 v120, v0
	v_mov_b32_e32 v121, v0
	v_mov_b32_e32 v122, v0
	v_mov_b32_e32 v123, v0
	v_mov_b32_e32 v132, v0
	v_mov_b32_e32 v133, v0
	v_mov_b32_e32 v134, v0
	v_mov_b32_e32 v135, v0
	v_mov_b32_e32 v136, v0
	v_mov_b32_e32 v137, v0
	v_mov_b32_e32 v138, v0
	v_mov_b32_e32 v139, v0
	v_mov_b32_e32 v152, v0
	v_mov_b32_e32 v153, v0
	v_mov_b32_e32 v154, v0
	v_mov_b32_e32 v155, v0
	v_mov_b32_e32 v156, v0
	v_mov_b32_e32 v157, v0
	v_mov_b32_e32 v158, v0
	v_mov_b32_e32 v159, v0
	s_mul_i32 s100, s54, 0x1e00
	v_add_u32_e32 v246, s100, v232
	v_readlane_b32 s98, v255, 49
	v_readlane_b32 s99, v255, 50
	v_readlane_b32 s100, v255, 51
	v_readlane_b32 s101, v255, 52
.LBB0_1279:
	s_cmp_eq_u32 s56, -2
	s_cbranch_scc1 .Lkcp_skip_1279
	global_store_dwordx4 v247, v[248:251], s[100:101] nt
.Lkcp_skip_1279:
	s_add_u32 s2, s8, 0xfff80080
	s_addc_u32 s3, s9, -1
	s_add_i32 s57, 0, 0x10000
	v_add_u32_e32 v76, s57, v241
	ds_read_b128 v[64:67], v76
	ds_read_b128 v[68:71], v76 offset:1024
	ds_read_b128 v[72:75], v76 offset:2048
	ds_read_b128 v[76:79], v76 offset:3072
	s_cmp_eq_u32 s56, 28
	s_cselect_b32 s41, s0, s3
	s_cselect_b32 s40, s1, s2
	s_cselect_b32 s3, s27, s55
	s_cselect_b32 s2, s29, s33
	v_lshl_add_u64 v[176:177], s[8:9], 0, v[202:203]
	s_add_i32 m0, s37, 0xc000
	ds_read_b128 v[80:83], v244
	ds_read_b128 v[84:87], v244 offset:1024
	ds_read_b128 v[88:91], v244 offset:2048
	ds_read_b128 v[148:151], v244 offset:3072
	ds_read_b128 v[160:163], v244 offset:4096
	ds_read_b128 v[164:167], v244 offset:5120
	ds_read_b128 v[168:171], v244 offset:6144
	ds_read_b128 v[172:175], v244 offset:7168
	global_load_lds_dwordx4 v[176:177], off
	v_lshl_add_u64 v[176:177], s[8:9], 0, v[200:201]
	s_add_i32 m0, s37, 0xe000
	s_nop 0
	global_load_lds_dwordx4 v[176:177], off
	s_waitcnt lgkmcnt(8)
	s_barrier
	s_waitcnt lgkmcnt(0)
	s_setprio 1
	s_waitcnt lgkmcnt(0)
	v_mfma_f32_16x16x32_bf16 v[156:159], v[64:67], v[80:83], v[156:159]
	v_mfma_f32_16x16x32_bf16 v[152:155], v[72:75], v[80:83], v[152:155]
	v_mfma_f32_16x16x32_bf16 v[136:139], v[64:67], v[88:91], v[136:139]
	v_mfma_f32_16x16x32_bf16 v[132:135], v[72:75], v[88:91], v[132:135]
	v_mfma_f32_16x16x32_bf16 v[120:123], v[64:67], v[160:163], v[120:123]
	v_mfma_f32_16x16x32_bf16 v[116:119], v[72:75], v[160:163], v[116:119]
	v_mfma_f32_16x16x32_bf16 v[104:107], v[64:67], v[168:171], v[104:107]
	v_mfma_f32_16x16x32_bf16 v[100:103], v[72:75], v[168:171], v[100:103]
	v_mfma_f32_16x16x32_bf16 v[156:159], v[68:71], v[84:87], v[156:159]
	v_mfma_f32_16x16x32_bf16 v[152:155], v[76:79], v[84:87], v[152:155]
	v_mfma_f32_16x16x32_bf16 v[136:139], v[68:71], v[148:151], v[136:139]
	v_mfma_f32_16x16x32_bf16 v[132:135], v[76:79], v[148:151], v[132:135]
	v_mfma_f32_16x16x32_bf16 v[120:123], v[68:71], v[164:167], v[120:123]
	v_mfma_f32_16x16x32_bf16 v[116:119], v[76:79], v[164:167], v[116:119]
	v_mfma_f32_16x16x32_bf16 v[104:107], v[68:71], v[172:175], v[104:107]
	v_mfma_f32_16x16x32_bf16 v[100:103], v[76:79], v[172:175], v[100:103]
	s_setprio 0
	s_barrier
	s_add_i32 s60, 0, 0x14000
	s_add_i32 s57, s57, s46
	v_add_u32_e32 v204, s60, v241
	v_lshl_add_u64 v[212:213], s[2:3], 0, v[188:189]
	s_mov_b32 m0, s57
	ds_read_b128 v[176:179], v204
	ds_read_b128 v[180:183], v204 offset:1024
	ds_read_b128 v[184:187], v204 offset:2048
	ds_read_b128 v[204:207], v204 offset:3072
	global_load_lds_dwordx4 v[212:213], off
	v_lshl_add_u64 v[214:215], s[2:3], 0, v[198:199]
	s_add_i32 m0, s57, 0x2000
	s_nop 0
	global_load_lds_dwordx4 v[214:215], off
	v_min_u32_e32 v247, 0x1feff, v246
	v_lshlrev_b32_e32 v247, 4, v247
	v_add_u32_e32 v246, 0x200, v246
	global_load_dwordx4 v[248:251], v247, s[98:99] nt
	s_barrier
	s_waitcnt lgkmcnt(0)
	s_setprio 1
	s_waitcnt lgkmcnt(0)
	v_mfma_f32_16x16x32_bf16 v[144:147], v[176:179], v[80:83], v[144:147]
	v_mfma_f32_16x16x32_bf16 v[80:83], v[184:187], v[80:83], v[140:143]
	v_mfma_f32_16x16x32_bf16 v[112:115], v[176:179], v[160:163], v[112:115]
	v_mfma_f32_16x16x32_bf16 v[108:111], v[184:187], v[160:163], v[108:111]
	v_mfma_f32_16x16x32_bf16 v[96:99], v[176:179], v[168:171], v[96:99]
	v_mfma_f32_16x16x32_bf16 v[92:95], v[184:187], v[168:171], v[92:95]
	v_mfma_f32_16x16x32_bf16 v[144:147], v[180:183], v[84:87], v[144:147]
	v_mfma_f32_16x16x32_bf16 v[80:83], v[204:207], v[84:87], v[80:83]
	v_mfma_f32_16x16x32_bf16 v[84:87], v[176:179], v[88:91], v[128:131]
	v_mfma_f32_16x16x32_bf16 v[88:91], v[184:187], v[88:91], v[124:127]
	v_mfma_f32_16x16x32_bf16 v[112:115], v[180:183], v[164:167], v[112:115]
	v_mfma_f32_16x16x32_bf16 v[108:111], v[204:207], v[164:167], v[108:111]
	v_mfma_f32_16x16x32_bf16 v[96:99], v[180:183], v[172:175], v[96:99]
	v_mfma_f32_16x16x32_bf16 v[92:95], v[204:207], v[172:175], v[92:95]
	v_mfma_f32_16x16x32_bf16 v[84:87], v[180:183], v[148:151], v[84:87]
	v_mfma_f32_16x16x32_bf16 v[88:91], v[204:207], v[148:151], v[88:91]
	s_setprio 0
	s_mov_b32 m0, s37
	v_lshl_add_u64 v[216:217], s[40:41], 0, v[194:195]
	s_barrier
	ds_read_b128 v[124:127], v244 offset:16384
	ds_read_b128 v[128:131], v244 offset:17408
	ds_read_b128 v[140:143], v244 offset:18432
	ds_read_b128 v[148:151], v244 offset:19456
	ds_read_b128 v[160:163], v244 offset:20480
	ds_read_b128 v[164:167], v244 offset:21504
	ds_read_b128 v[168:171], v244 offset:22528
	ds_read_b128 v[172:175], v244 offset:23552
	global_load_lds_dwordx4 v[216:217], off
	v_lshl_add_u64 v[218:219], s[40:41], 0, v[196:197]
	s_mov_b32 m0, s39
	s_nop 0
	global_load_lds_dwordx4 v[218:219], off
	s_barrier
	s_waitcnt lgkmcnt(0)
	s_setprio 1
	s_waitcnt lgkmcnt(0)
	v_mfma_f32_16x16x32_bf16 v[60:63], v[64:67], v[124:127], v[60:63]
	v_mfma_f32_16x16x32_bf16 v[56:59], v[72:75], v[124:127], v[56:59]
	v_mfma_f32_16x16x32_bf16 v[44:47], v[64:67], v[140:143], v[44:47]
	v_mfma_f32_16x16x32_bf16 v[40:43], v[72:75], v[140:143], v[40:43]
	v_mfma_f32_16x16x32_bf16 v[28:31], v[64:67], v[160:163], v[28:31]
	v_mfma_f32_16x16x32_bf16 v[24:27], v[72:75], v[160:163], v[24:27]
	v_mfma_f32_16x16x32_bf16 v[12:15], v[64:67], v[168:171], v[12:15]
	v_mfma_f32_16x16x32_bf16 v[8:11], v[72:75], v[168:171], v[8:11]
	v_mfma_f32_16x16x32_bf16 v[60:63], v[68:71], v[128:131], v[60:63]
	v_mfma_f32_16x16x32_bf16 v[56:59], v[76:79], v[128:131], v[56:59]
	v_mfma_f32_16x16x32_bf16 v[44:47], v[68:71], v[148:151], v[44:47]
	v_mfma_f32_16x16x32_bf16 v[40:43], v[76:79], v[148:151], v[40:43]
	v_mfma_f32_16x16x32_bf16 v[28:31], v[68:71], v[164:167], v[28:31]
	v_mfma_f32_16x16x32_bf16 v[24:27], v[76:79], v[164:167], v[24:27]
	v_mfma_f32_16x16x32_bf16 v[12:15], v[68:71], v[172:175], v[12:15]
	v_mfma_f32_16x16x32_bf16 v[8:11], v[76:79], v[172:175], v[8:11]
	s_setprio 0
	s_barrier
	s_add_u32 s58, s2, 0x80000
	s_addc_u32 s59, s3, 0
	s_add_i32 s57, s60, s46
	v_lshl_add_u64 v[64:65], s[58:59], 0, v[188:189]
	s_mov_b32 m0, s57
	s_nop 0
	global_load_lds_dwordx4 v[64:65], off
	v_lshl_add_u64 v[64:65], s[58:59], 0, v[198:199]
	s_add_i32 m0, s57, 0x2000
	s_nop 0
	global_load_lds_dwordx4 v[64:65], off
	s_waitcnt vmcnt(7)
	s_barrier
	s_setprio 1
	v_mfma_f32_16x16x32_bf16 v[52:55], v[176:179], v[124:127], v[52:55]
	v_mfma_f32_16x16x32_bf16 v[48:51], v[184:187], v[124:127], v[48:51]
	v_mfma_f32_16x16x32_bf16 v[36:39], v[176:179], v[140:143], v[36:39]
	v_mfma_f32_16x16x32_bf16 v[32:35], v[184:187], v[140:143], v[32:35]
	v_mfma_f32_16x16x32_bf16 v[20:23], v[176:179], v[160:163], v[20:23]
	v_mfma_f32_16x16x32_bf16 v[16:19], v[184:187], v[160:163], v[16:19]
	v_mfma_f32_16x16x32_bf16 v[4:7], v[176:179], v[168:171], v[4:7]
	v_mfma_f32_16x16x32_bf16 v[0:3], v[184:187], v[168:171], v[0:3]
	v_mfma_f32_16x16x32_bf16 v[52:55], v[180:183], v[128:131], v[52:55]
	v_mfma_f32_16x16x32_bf16 v[48:51], v[204:207], v[128:131], v[48:51]
	v_mfma_f32_16x16x32_bf16 v[36:39], v[180:183], v[148:151], v[36:39]
	v_mfma_f32_16x16x32_bf16 v[32:35], v[204:207], v[148:151], v[32:35]
	v_mfma_f32_16x16x32_bf16 v[20:23], v[180:183], v[164:167], v[20:23]
	v_mfma_f32_16x16x32_bf16 v[16:19], v[204:207], v[164:167], v[16:19]
	v_mfma_f32_16x16x32_bf16 v[4:7], v[180:183], v[172:175], v[4:7]
	v_mfma_f32_16x16x32_bf16 v[0:3], v[204:207], v[172:175], v[0:3]
	s_setprio 0
	s_add_i32 s57, 0, 0x18000
	v_add_u32_e32 v76, s57, v241
	s_barrier
	ds_read_b128 v[64:67], v76
	ds_read_b128 v[68:71], v76 offset:1024
	ds_read_b128 v[72:75], v76 offset:2048
	ds_read_b128 v[76:79], v76 offset:3072
	s_add_u32 s40, s40, 0x80000
	s_addc_u32 s41, s41, 0
	s_mov_b32 m0, s47
	v_lshl_add_u64 v[140:141], s[40:41], 0, v[194:195]
	ds_read_b128 v[124:127], v244 offset:32768
	ds_read_b128 v[128:131], v244 offset:33792
	ds_read_b128 v[148:151], v244 offset:34816
	ds_read_b128 v[160:163], v244 offset:35840
	ds_read_b128 v[164:167], v244 offset:36864
	ds_read_b128 v[168:171], v244 offset:37888
	ds_read_b128 v[172:175], v244 offset:38912
	ds_read_b128 v[176:179], v244 offset:39936
	global_load_lds_dwordx4 v[140:141], off
	v_lshl_add_u64 v[140:141], s[40:41], 0, v[196:197]
	s_mov_b32 m0, s48
	s_nop 0
	global_load_lds_dwordx4 v[140:141], off
	s_waitcnt lgkmcnt(8)
	s_barrier
	s_waitcnt lgkmcnt(0)
	s_setprio 1
	s_waitcnt lgkmcnt(0)
	v_mfma_f32_16x16x32_bf16 v[140:143], v[64:67], v[124:127], v[156:159]
	v_mfma_f32_16x16x32_bf16 v[156:159], v[68:71], v[128:131], v[140:143]
	v_mfma_f32_16x16x32_bf16 v[140:143], v[72:75], v[124:127], v[152:155]
	v_mfma_f32_16x16x32_bf16 v[136:139], v[64:67], v[148:151], v[136:139]
	v_mfma_f32_16x16x32_bf16 v[132:135], v[72:75], v[148:151], v[132:135]
	v_mfma_f32_16x16x32_bf16 v[120:123], v[64:67], v[164:167], v[120:123]
	v_mfma_f32_16x16x32_bf16 v[116:119], v[72:75], v[164:167], v[116:119]
	v_mfma_f32_16x16x32_bf16 v[104:107], v[64:67], v[172:175], v[104:107]
	v_mfma_f32_16x16x32_bf16 v[100:103], v[72:75], v[172:175], v[100:103]
	v_mfma_f32_16x16x32_bf16 v[152:155], v[76:79], v[128:131], v[140:143]
	v_mfma_f32_16x16x32_bf16 v[136:139], v[68:71], v[160:163], v[136:139]
	v_mfma_f32_16x16x32_bf16 v[132:135], v[76:79], v[160:163], v[132:135]
	v_mfma_f32_16x16x32_bf16 v[120:123], v[68:71], v[168:171], v[120:123]
	v_mfma_f32_16x16x32_bf16 v[116:119], v[76:79], v[168:171], v[116:119]
	v_mfma_f32_16x16x32_bf16 v[104:107], v[68:71], v[176:179], v[104:107]
	v_mfma_f32_16x16x32_bf16 v[100:103], v[76:79], v[176:179], v[100:103]
	s_setprio 0
	s_barrier
	s_add_i32 s40, 0, 0x1c000
	v_add_u32_e32 v140, s40, v241
	s_add_i32 s41, s57, s46
	ds_read_b128 v[180:183], v140
	ds_read_b128 v[184:187], v140 offset:1024
	ds_read_b128 v[204:207], v140 offset:2048
	ds_read_b128 v[208:211], v140 offset:3072
	v_lshl_add_u64 v[140:141], v[212:213], 0, s[88:89]
	s_mov_b32 m0, s41
	s_nop 0
	global_load_lds_dwordx4 v[140:141], off
	v_lshl_add_u64 v[140:141], v[214:215], 0, s[88:89]
	s_add_i32 m0, s41, 0x2000
	s_nop 0
	global_load_lds_dwordx4 v[140:141], off
	s_barrier
	s_waitcnt lgkmcnt(0)
	s_setprio 1
	s_waitcnt lgkmcnt(0)
	v_mfma_f32_16x16x32_bf16 v[140:143], v[180:183], v[124:127], v[144:147]
	v_mfma_f32_16x16x32_bf16 v[80:83], v[204:207], v[124:127], v[80:83]
	v_mfma_f32_16x16x32_bf16 v[144:147], v[184:187], v[128:131], v[140:143]
	v_mfma_f32_16x16x32_bf16 v[140:143], v[208:211], v[128:131], v[80:83]
	v_mfma_f32_16x16x32_bf16 v[80:83], v[180:183], v[148:151], v[84:87]
	v_mfma_f32_16x16x32_bf16 v[128:131], v[184:187], v[160:163], v[80:83]
	v_mfma_f32_16x16x32_bf16 v[80:83], v[204:207], v[148:151], v[88:91]
	v_mfma_f32_16x16x32_bf16 v[124:127], v[208:211], v[160:163], v[80:83]
	v_mfma_f32_16x16x32_bf16 v[80:83], v[180:183], v[164:167], v[112:115]
	v_mfma_f32_16x16x32_bf16 v[112:115], v[184:187], v[168:171], v[80:83]
	v_mfma_f32_16x16x32_bf16 v[80:83], v[204:207], v[164:167], v[108:111]
	v_mfma_f32_16x16x32_bf16 v[108:111], v[208:211], v[168:171], v[80:83]
	v_mfma_f32_16x16x32_bf16 v[80:83], v[180:183], v[172:175], v[96:99]
	v_mfma_f32_16x16x32_bf16 v[96:99], v[184:187], v[176:179], v[80:83]
	v_mfma_f32_16x16x32_bf16 v[80:83], v[204:207], v[172:175], v[92:95]
	v_mfma_f32_16x16x32_bf16 v[92:95], v[208:211], v[176:179], v[80:83]
	s_setprio 0
	s_mov_b32 m0, s49
	v_lshl_add_u64 v[176:177], v[216:217], 0, s[88:89]
	s_barrier
	s_nop 2
	ds_read_b128 v[80:83], v244 offset:49152
	ds_read_b128 v[84:87], v244 offset:50176
	ds_read_b128 v[88:91], v244 offset:51200
	ds_read_b128 v[148:151], v244 offset:52224
	ds_read_b128 v[160:163], v244 offset:53248
	ds_read_b128 v[164:167], v244 offset:54272
	ds_read_b128 v[168:171], v244 offset:55296
	ds_read_b128 v[172:175], v244 offset:56320
	global_load_lds_dwordx4 v[176:177], off
	v_lshl_add_u64 v[176:177], v[218:219], 0, s[88:89]
	s_mov_b32 m0, s50
	s_nop 0
	global_load_lds_dwordx4 v[176:177], off
	s_barrier
	s_waitcnt lgkmcnt(0)
	s_setprio 1
	s_waitcnt lgkmcnt(0)
	v_mfma_f32_16x16x32_bf16 v[60:63], v[64:67], v[80:83], v[60:63]
	v_mfma_f32_16x16x32_bf16 v[56:59], v[72:75], v[80:83], v[56:59]
	v_mfma_f32_16x16x32_bf16 v[44:47], v[64:67], v[88:91], v[44:47]
	v_mfma_f32_16x16x32_bf16 v[40:43], v[72:75], v[88:91], v[40:43]
	v_mfma_f32_16x16x32_bf16 v[28:31], v[64:67], v[160:163], v[28:31]
	v_mfma_f32_16x16x32_bf16 v[24:27], v[72:75], v[160:163], v[24:27]
	v_mfma_f32_16x16x32_bf16 v[12:15], v[64:67], v[168:171], v[12:15]
	v_mfma_f32_16x16x32_bf16 v[8:11], v[72:75], v[168:171], v[8:11]
	v_mfma_f32_16x16x32_bf16 v[60:63], v[68:71], v[84:87], v[60:63]
	v_mfma_f32_16x16x32_bf16 v[56:59], v[76:79], v[84:87], v[56:59]
	v_mfma_f32_16x16x32_bf16 v[44:47], v[68:71], v[148:151], v[44:47]
	v_mfma_f32_16x16x32_bf16 v[40:43], v[76:79], v[148:151], v[40:43]
	v_mfma_f32_16x16x32_bf16 v[28:31], v[68:71], v[164:167], v[28:31]
	v_mfma_f32_16x16x32_bf16 v[24:27], v[76:79], v[164:167], v[24:27]
	v_mfma_f32_16x16x32_bf16 v[12:15], v[68:71], v[172:175], v[12:15]
	v_mfma_f32_16x16x32_bf16 v[8:11], v[76:79], v[172:175], v[8:11]
	s_setprio 0
	s_barrier
	s_add_u32 s2, s2, 0x80080
	s_addc_u32 s3, s3, 0
	s_add_i32 s40, s40, s46
	v_lshl_add_u64 v[64:65], s[2:3], 0, v[188:189]
	s_mov_b32 m0, s40
	s_nop 0
	global_load_lds_dwordx4 v[64:65], off
	v_lshl_add_u64 v[64:65], s[2:3], 0, v[198:199]
	s_add_i32 m0, s40, 0x2000
	s_nop 0
	global_load_lds_dwordx4 v[64:65], off
	s_waitcnt vmcnt(6)
	s_barrier
	s_setprio 1
	v_mfma_f32_16x16x32_bf16 v[52:55], v[180:183], v[80:83], v[52:55]
	v_mfma_f32_16x16x32_bf16 v[48:51], v[204:207], v[80:83], v[48:51]
	v_mfma_f32_16x16x32_bf16 v[36:39], v[180:183], v[88:91], v[36:39]
	v_mfma_f32_16x16x32_bf16 v[32:35], v[204:207], v[88:91], v[32:35]
	v_mfma_f32_16x16x32_bf16 v[20:23], v[180:183], v[160:163], v[20:23]
	v_mfma_f32_16x16x32_bf16 v[16:19], v[204:207], v[160:163], v[16:19]
	v_mfma_f32_16x16x32_bf16 v[4:7], v[180:183], v[168:171], v[4:7]
	v_mfma_f32_16x16x32_bf16 v[0:3], v[204:207], v[168:171], v[0:3]
	v_mfma_f32_16x16x32_bf16 v[52:55], v[184:187], v[84:87], v[52:55]
	v_mfma_f32_16x16x32_bf16 v[48:51], v[208:211], v[84:87], v[48:51]
	v_mfma_f32_16x16x32_bf16 v[36:39], v[184:187], v[148:151], v[36:39]
	v_mfma_f32_16x16x32_bf16 v[32:35], v[208:211], v[148:151], v[32:35]
	v_mfma_f32_16x16x32_bf16 v[20:23], v[184:187], v[164:167], v[20:23]
	v_mfma_f32_16x16x32_bf16 v[16:19], v[208:211], v[164:167], v[16:19]
	v_mfma_f32_16x16x32_bf16 v[4:7], v[184:187], v[172:175], v[4:7]
	v_mfma_f32_16x16x32_bf16 v[0:3], v[208:211], v[172:175], v[0:3]
	s_setprio 0
	s_add_i32 s56, s56, 2
	s_add_u32 s33, s33, 0x100
	s_addc_u32 s55, s55, 0
	s_add_u32 s8, s8, 0x100
	s_addc_u32 s9, s9, 0
	s_cmp_gt_u32 s56, 29
	s_barrier
	s_cbranch_scc0 .LBB0_1279
	v_mov_b32_e32 v64, 1.0
	v_mov_b32_e32 v65, 1.0
	v_mov_b32_e32 v66, 1.0
	v_mov_b32_e32 v67, 1.0
	v_mov_b32_e32 v68, 1.0
	v_mov_b32_e32 v69, 1.0
	v_mov_b32_e32 v70, 1.0
	v_mov_b32_e32 v71, 1.0
	s_mul_i32 s0, s54, 0x1e00
	v_add_u32_e32 v247, s0, v243
	v_cndmask_b32_e64 v64, 0, 1, s[24:25]
	v_min_i32_e32 v222, 0x1feff, v247
	v_min_i32_e32 v220, 0x1fcff, v247
	v_min_i32_e32 v218, 0x1faff, v247
	v_min_i32_e32 v214, 0x1f8ff, v247
	v_min_i32_e32 v212, 0x1f6ff, v247
	v_min_i32_e32 v210, 0x1f4ff, v247
	v_min_i32_e32 v208, 0x1f2ff, v247
	v_min_i32_e32 v206, 0x1f0ff, v247
	v_cmp_ne_u32_e64 s[8:9], 1, v64
	s_andn2_b64 vcc, exec, s[24:25]
	v_ashrrev_i32_e32 v223, 31, v222
	v_ashrrev_i32_e32 v221, 31, v220
	v_ashrrev_i32_e32 v219, 31, v218
	v_ashrrev_i32_e32 v215, 31, v214
	v_ashrrev_i32_e32 v213, 31, v212
	v_ashrrev_i32_e32 v211, 31, v210
	v_ashrrev_i32_e32 v209, 31, v208
	v_ashrrev_i32_e32 v207, 31, v206
	s_cbranch_vccnz .LBB0_1282
	v_lshl_add_u64 v[66:67], v[220:221], 4, s[16:17]
	v_lshl_add_u64 v[64:65], v[222:223], 4, s[16:17]
	v_add_co_u32_e32 v66, vcc, 0x2000, v66
	v_lshl_add_u64 v[68:69], v[208:209], 4, s[16:17]
	s_nop 0
	v_addc_co_u32_e32 v67, vcc, 0, v67, vcc
	global_load_dwordx4 v[88:91], v[64:65], off nt
	global_load_dwordx4 v[76:79], v[66:67], off nt
	v_lshl_add_u64 v[64:65], v[218:219], 4, s[16:17]
	v_add_co_u32_e32 v64, vcc, 0x4000, v64
	v_lshl_add_u64 v[66:67], v[214:215], 4, s[16:17]
	s_nop 0
	v_addc_co_u32_e32 v65, vcc, 0, v65, vcc
	v_add_co_u32_e32 v66, vcc, 0x6000, v66
	v_lshl_add_u64 v[70:71], v[206:207], 4, s[16:17]
	s_nop 0
	v_addc_co_u32_e32 v67, vcc, 0, v67, vcc
	global_load_dwordx4 v[84:87], v[64:65], off nt
	global_load_dwordx4 v[72:75], v[66:67], off nt
	v_lshl_add_u64 v[64:65], v[212:213], 4, s[16:17]
	v_add_co_u32_e32 v64, vcc, 0x8000, v64
	v_lshl_add_u64 v[66:67], v[210:211], 4, s[16:17]
	s_nop 0
	v_addc_co_u32_e32 v65, vcc, 0, v65, vcc
	v_add_co_u32_e32 v66, vcc, 0xa000, v66
	s_nop 1
	v_addc_co_u32_e32 v67, vcc, 0, v67, vcc
	v_add_co_u32_e32 v68, vcc, 0xc000, v68
	global_load_dwordx4 v[80:83], v[64:65], off nt
	s_nop 0
	global_load_dwordx4 v[64:67], v[66:67], off nt
	v_addc_co_u32_e32 v69, vcc, 0, v69, vcc
	v_add_co_u32_e32 v148, vcc, 0xe000, v70
	s_nop 1
	v_addc_co_u32_e32 v149, vcc, 0, v71, vcc
	global_load_dwordx4 v[68:71], v[68:69], off nt
	s_nop 0
	global_load_dwordx4 v[148:151], v[148:149], off nt
	s_branch .LBB0_1283

.LBB0_1331:
	s_ashr_i32 s27, s26, 31
	v_cmp_lt_i64_e32 vcc, s[0:1], v[192:193]
	s_lshl_b64 s[0:1], s[26:27], 20
	s_add_u32 s28, s14, s0
	s_addc_u32 s29, s15, s1
	s_and_b64 s[0:1], vcc, exec
	s_cselect_b32 s0, s29, s9
	s_cselect_b32 s1, s28, s8
	s_ashr_i32 s25, s24, 31
	s_lshl_b64 s[30:31], s[24:25], 20
	s_add_u32 s30, s12, s30
	s_addc_u32 s31, s13, s31
	s_and_b64 s[38:39], vcc, exec
	s_cselect_b32 s25, s31, s3
	s_cselect_b32 s27, s30, s2
	s_add_u32 s33, s2, 0x100
	s_addc_u32 s52, s3, 0
	s_add_u32 s8, s8, 0x80080
	v_mov_b32_e32 v0, 0
	s_addc_u32 s9, s9, 0
	s_mov_b32 s53, -2
	s_waitcnt lgkmcnt(0)
	v_mov_b32_e32 v1, v0
	v_mov_b32_e32 v2, v0
	v_mov_b32_e32 v3, v0
	v_mov_b32_e32 v4, v0
	v_mov_b32_e32 v5, v0
	v_mov_b32_e32 v6, v0
	v_mov_b32_e32 v7, v0
	v_mov_b32_e32 v16, v0
	v_mov_b32_e32 v17, v0
	v_mov_b32_e32 v18, v0
	v_mov_b32_e32 v19, v0
	v_mov_b32_e32 v20, v0
	v_mov_b32_e32 v21, v0
	v_mov_b32_e32 v22, v0
	v_mov_b32_e32 v23, v0
	v_mov_b32_e32 v32, v0
	v_mov_b32_e32 v33, v0
	v_mov_b32_e32 v34, v0
	v_mov_b32_e32 v35, v0
	v_mov_b32_e32 v36, v0
	v_mov_b32_e32 v37, v0
	v_mov_b32_e32 v38, v0
	v_mov_b32_e32 v39, v0
	v_mov_b32_e32 v48, v0
	v_mov_b32_e32 v49, v0
	v_mov_b32_e32 v50, v0
	v_mov_b32_e32 v51, v0
	v_mov_b32_e32 v52, v0
	v_mov_b32_e32 v53, v0
	v_mov_b32_e32 v54, v0
	v_mov_b32_e32 v55, v0
	v_mov_b32_e32 v8, v0
	v_mov_b32_e32 v9, v0
	v_mov_b32_e32 v10, v0
	v_mov_b32_e32 v11, v0
	v_mov_b32_e32 v12, v0
	v_mov_b32_e32 v13, v0
	v_mov_b32_e32 v14, v0
	v_mov_b32_e32 v15, v0
	v_mov_b32_e32 v24, v0
	v_mov_b32_e32 v25, v0
	v_mov_b32_e32 v26, v0
	v_mov_b32_e32 v27, v0
	v_mov_b32_e32 v28, v0
	v_mov_b32_e32 v29, v0
	v_mov_b32_e32 v30, v0
	v_mov_b32_e32 v31, v0
	v_mov_b32_e32 v40, v0
	v_mov_b32_e32 v41, v0
	v_mov_b32_e32 v42, v0
	v_mov_b32_e32 v43, v0
	v_mov_b32_e32 v44, v0
	v_mov_b32_e32 v45, v0
	v_mov_b32_e32 v46, v0
	v_mov_b32_e32 v47, v0
	v_mov_b32_e32 v56, v0
	v_mov_b32_e32 v57, v0
	v_mov_b32_e32 v58, v0
	v_mov_b32_e32 v59, v0
	v_mov_b32_e32 v60, v0
	v_mov_b32_e32 v61, v0
	v_mov_b32_e32 v62, v0
	v_mov_b32_e32 v63, v0
	v_mov_b32_e32 v92, v0
	v_mov_b32_e32 v93, v0
	v_mov_b32_e32 v94, v0
	v_mov_b32_e32 v95, v0
	v_mov_b32_e32 v96, v0
	v_mov_b32_e32 v97, v0
	v_mov_b32_e32 v98, v0
	v_mov_b32_e32 v99, v0
	v_mov_b32_e32 v108, v0
	v_mov_b32_e32 v109, v0
	v_mov_b32_e32 v110, v0
	v_mov_b32_e32 v111, v0
	v_mov_b32_e32 v112, v0
	v_mov_b32_e32 v113, v0
	v_mov_b32_e32 v114, v0
	v_mov_b32_e32 v115, v0
	v_mov_b32_e32 v124, v0
	v_mov_b32_e32 v125, v0
	v_mov_b32_e32 v126, v0
	v_mov_b32_e32 v127, v0
	v_mov_b32_e32 v128, v0
	v_mov_b32_e32 v129, v0
	v_mov_b32_e32 v130, v0
	v_mov_b32_e32 v131, v0
	v_mov_b32_e32 v144, v0
	v_mov_b32_e32 v145, v0
	v_mov_b32_e32 v146, v0
	v_mov_b32_e32 v147, v0
	v_mov_b32_e32 v148, v0
	v_mov_b32_e32 v149, v0
	v_mov_b32_e32 v150, v0
	v_mov_b32_e32 v151, v0
	v_mov_b32_e32 v100, v0
	v_mov_b32_e32 v101, v0
	v_mov_b32_e32 v102, v0
	v_mov_b32_e32 v103, v0
	v_mov_b32_e32 v104, v0
	v_mov_b32_e32 v105, v0
	v_mov_b32_e32 v106, v0
	v_mov_b32_e32 v107, v0
	v_mov_b32_e32 v116, v0
	v_mov_b32_e32 v117, v0
	v_mov_b32_e32 v118, v0
	v_mov_b32_e32 v119, v0
	v_mov_b32_e32 v120, v0
	v_mov_b32_e32 v121, v0
	v_mov_b32_e32 v122, v0
	v_mov_b32_e32 v123, v0
	v_mov_b32_e32 v132, v0
	v_mov_b32_e32 v133, v0
	v_mov_b32_e32 v134, v0
	v_mov_b32_e32 v135, v0
	v_mov_b32_e32 v136, v0
	v_mov_b32_e32 v137, v0
	v_mov_b32_e32 v138, v0
	v_mov_b32_e32 v139, v0
	v_mov_b32_e32 v152, v0
	v_mov_b32_e32 v153, v0
	v_mov_b32_e32 v154, v0
	v_mov_b32_e32 v155, v0
	v_mov_b32_e32 v156, v0
	v_mov_b32_e32 v157, v0
	v_mov_b32_e32 v158, v0
	v_mov_b32_e32 v159, v0
	s_mul_i32 s100, s44, 0x1e00
	v_add_u32_e32 v246, s100, v232
	v_readlane_b32 s98, v255, 49
	v_readlane_b32 s99, v255, 50
	v_readlane_b32 s100, v255, 51
	v_readlane_b32 s101, v255, 52
.LBB0_1332:
	s_cmp_eq_u32 s53, -2
	s_cbranch_scc1 .Lkcp_skip_1332
	global_store_dwordx4 v247, v[248:251], s[100:101] nt
.Lkcp_skip_1332:
	s_add_u32 s2, s8, 0xfff80080
	s_addc_u32 s3, s9, -1
	s_add_i32 s54, 0, 0x10000
	v_add_u32_e32 v76, s54, v241
	ds_read_b128 v[64:67], v76
	ds_read_b128 v[68:71], v76 offset:1024
	ds_read_b128 v[72:75], v76 offset:2048
	ds_read_b128 v[76:79], v76 offset:3072
	s_cmp_eq_u32 s53, 28
	s_cselect_b32 s39, s0, s3
	s_cselect_b32 s38, s1, s2
	s_cselect_b32 s3, s25, s52
	s_cselect_b32 s2, s27, s33
	v_lshl_add_u64 v[176:177], s[8:9], 0, v[198:199]
	s_add_i32 m0, s35, 0xc000
	ds_read_b128 v[80:83], v244
	ds_read_b128 v[84:87], v244 offset:1024
	ds_read_b128 v[88:91], v244 offset:2048
	ds_read_b128 v[140:143], v244 offset:3072
	ds_read_b128 v[160:163], v244 offset:4096
	ds_read_b128 v[164:167], v244 offset:5120
	ds_read_b128 v[168:171], v244 offset:6144
	ds_read_b128 v[172:175], v244 offset:7168
	global_load_lds_dwordx4 v[176:177], off
	v_lshl_add_u64 v[176:177], s[8:9], 0, v[196:197]
	s_add_i32 m0, s35, 0xe000
	s_nop 0
	global_load_lds_dwordx4 v[176:177], off
	s_waitcnt lgkmcnt(8)
	s_barrier
	s_waitcnt lgkmcnt(0)
	s_setprio 1
	s_waitcnt lgkmcnt(0)
	v_mfma_f32_16x16x32_bf16 v[156:159], v[64:67], v[80:83], v[156:159]
	v_mfma_f32_16x16x32_bf16 v[152:155], v[72:75], v[80:83], v[152:155]
	v_mfma_f32_16x16x32_bf16 v[136:139], v[64:67], v[88:91], v[136:139]
	v_mfma_f32_16x16x32_bf16 v[132:135], v[72:75], v[88:91], v[132:135]
	v_mfma_f32_16x16x32_bf16 v[120:123], v[64:67], v[160:163], v[120:123]
	v_mfma_f32_16x16x32_bf16 v[116:119], v[72:75], v[160:163], v[116:119]
	v_mfma_f32_16x16x32_bf16 v[104:107], v[64:67], v[168:171], v[104:107]
	v_mfma_f32_16x16x32_bf16 v[100:103], v[72:75], v[168:171], v[100:103]
	v_mfma_f32_16x16x32_bf16 v[156:159], v[68:71], v[84:87], v[156:159]
	v_mfma_f32_16x16x32_bf16 v[152:155], v[76:79], v[84:87], v[152:155]
	v_mfma_f32_16x16x32_bf16 v[136:139], v[68:71], v[140:143], v[136:139]
	v_mfma_f32_16x16x32_bf16 v[132:135], v[76:79], v[140:143], v[132:135]
	v_mfma_f32_16x16x32_bf16 v[120:123], v[68:71], v[164:167], v[120:123]
	v_mfma_f32_16x16x32_bf16 v[116:119], v[76:79], v[164:167], v[116:119]
	v_mfma_f32_16x16x32_bf16 v[104:107], v[68:71], v[172:175], v[104:107]
	v_mfma_f32_16x16x32_bf16 v[100:103], v[76:79], v[172:175], v[100:103]
	s_setprio 0
	s_barrier
	s_add_i32 s56, 0, 0x14000
	s_add_i32 s54, s54, s41
	v_add_u32_e32 v204, s56, v241
	v_lshl_add_u64 v[212:213], s[2:3], 0, v[188:189]
	s_mov_b32 m0, s54
	ds_read_b128 v[176:179], v204
	ds_read_b128 v[180:183], v204 offset:1024
	ds_read_b128 v[200:203], v204 offset:2048
	ds_read_b128 v[204:207], v204 offset:3072
	global_load_lds_dwordx4 v[212:213], off
	v_lshl_add_u64 v[214:215], s[2:3], 0, v[194:195]
	s_add_i32 m0, s54, 0x2000
	s_nop 0
	global_load_lds_dwordx4 v[214:215], off
	v_min_u32_e32 v247, 0x1feff, v246
	v_lshlrev_b32_e32 v247, 4, v247
	v_add_u32_e32 v246, 0x200, v246
	global_load_dwordx4 v[248:251], v247, s[98:99] nt
	s_barrier
	s_waitcnt lgkmcnt(0)
	s_setprio 1
	s_waitcnt lgkmcnt(0)
	v_mfma_f32_16x16x32_bf16 v[148:151], v[176:179], v[80:83], v[148:151]
	v_mfma_f32_16x16x32_bf16 v[80:83], v[200:203], v[80:83], v[144:147]
	v_mfma_f32_16x16x32_bf16 v[112:115], v[176:179], v[160:163], v[112:115]
	v_mfma_f32_16x16x32_bf16 v[108:111], v[200:203], v[160:163], v[108:111]
	v_mfma_f32_16x16x32_bf16 v[96:99], v[176:179], v[168:171], v[96:99]
	v_mfma_f32_16x16x32_bf16 v[92:95], v[200:203], v[168:171], v[92:95]
	v_mfma_f32_16x16x32_bf16 v[148:151], v[180:183], v[84:87], v[148:151]
	v_mfma_f32_16x16x32_bf16 v[80:83], v[204:207], v[84:87], v[80:83]
	v_mfma_f32_16x16x32_bf16 v[84:87], v[176:179], v[88:91], v[128:131]
	v_mfma_f32_16x16x32_bf16 v[88:91], v[200:203], v[88:91], v[124:127]
	v_mfma_f32_16x16x32_bf16 v[112:115], v[180:183], v[164:167], v[112:115]
	v_mfma_f32_16x16x32_bf16 v[108:111], v[204:207], v[164:167], v[108:111]
	v_mfma_f32_16x16x32_bf16 v[96:99], v[180:183], v[172:175], v[96:99]
	v_mfma_f32_16x16x32_bf16 v[92:95], v[204:207], v[172:175], v[92:95]
	v_mfma_f32_16x16x32_bf16 v[84:87], v[180:183], v[140:143], v[84:87]
	v_mfma_f32_16x16x32_bf16 v[88:91], v[204:207], v[140:143], v[88:91]
	s_setprio 0
	s_mov_b32 m0, s35
	v_lshl_add_u64 v[216:217], s[38:39], 0, v[184:185]
	s_barrier
	ds_read_b128 v[124:127], v244 offset:16384
	ds_read_b128 v[128:131], v244 offset:17408
	ds_read_b128 v[140:143], v244 offset:18432
	ds_read_b128 v[144:147], v244 offset:19456
	ds_read_b128 v[160:163], v244 offset:20480
	ds_read_b128 v[164:167], v244 offset:21504
	ds_read_b128 v[168:171], v244 offset:22528
	ds_read_b128 v[172:175], v244 offset:23552
	global_load_lds_dwordx4 v[216:217], off
	v_lshl_add_u64 v[218:219], s[38:39], 0, v[186:187]
	s_mov_b32 m0, s37
	s_nop 0
	global_load_lds_dwordx4 v[218:219], off
	s_barrier
	s_waitcnt lgkmcnt(0)
	s_setprio 1
	s_waitcnt lgkmcnt(0)
	v_mfma_f32_16x16x32_bf16 v[60:63], v[64:67], v[124:127], v[60:63]
	v_mfma_f32_16x16x32_bf16 v[56:59], v[72:75], v[124:127], v[56:59]
	v_mfma_f32_16x16x32_bf16 v[44:47], v[64:67], v[140:143], v[44:47]
	v_mfma_f32_16x16x32_bf16 v[40:43], v[72:75], v[140:143], v[40:43]
	v_mfma_f32_16x16x32_bf16 v[28:31], v[64:67], v[160:163], v[28:31]
	v_mfma_f32_16x16x32_bf16 v[24:27], v[72:75], v[160:163], v[24:27]
	v_mfma_f32_16x16x32_bf16 v[12:15], v[64:67], v[168:171], v[12:15]
	v_mfma_f32_16x16x32_bf16 v[8:11], v[72:75], v[168:171], v[8:11]
	v_mfma_f32_16x16x32_bf16 v[60:63], v[68:71], v[128:131], v[60:63]
	v_mfma_f32_16x16x32_bf16 v[56:59], v[76:79], v[128:131], v[56:59]
	v_mfma_f32_16x16x32_bf16 v[44:47], v[68:71], v[144:147], v[44:47]
	v_mfma_f32_16x16x32_bf16 v[40:43], v[76:79], v[144:147], v[40:43]
	v_mfma_f32_16x16x32_bf16 v[28:31], v[68:71], v[164:167], v[28:31]
	v_mfma_f32_16x16x32_bf16 v[24:27], v[76:79], v[164:167], v[24:27]
	v_mfma_f32_16x16x32_bf16 v[12:15], v[68:71], v[172:175], v[12:15]
	v_mfma_f32_16x16x32_bf16 v[8:11], v[76:79], v[172:175], v[8:11]
	s_setprio 0
	s_barrier
	s_add_u32 s54, s2, 0x80000
	s_addc_u32 s55, s3, 0
	s_add_i32 s56, s56, s41
	v_lshl_add_u64 v[64:65], s[54:55], 0, v[188:189]
	s_mov_b32 m0, s56
	s_nop 0
	global_load_lds_dwordx4 v[64:65], off
	v_lshl_add_u64 v[64:65], s[54:55], 0, v[194:195]
	s_add_i32 m0, s56, 0x2000
	s_nop 0
	global_load_lds_dwordx4 v[64:65], off
	s_waitcnt vmcnt(7)
	s_barrier
	s_setprio 1
	v_mfma_f32_16x16x32_bf16 v[52:55], v[176:179], v[124:127], v[52:55]
	v_mfma_f32_16x16x32_bf16 v[48:51], v[200:203], v[124:127], v[48:51]
	v_mfma_f32_16x16x32_bf16 v[36:39], v[176:179], v[140:143], v[36:39]
	v_mfma_f32_16x16x32_bf16 v[32:35], v[200:203], v[140:143], v[32:35]
	v_mfma_f32_16x16x32_bf16 v[20:23], v[176:179], v[160:163], v[20:23]
	v_mfma_f32_16x16x32_bf16 v[16:19], v[200:203], v[160:163], v[16:19]
	v_mfma_f32_16x16x32_bf16 v[4:7], v[176:179], v[168:171], v[4:7]
	v_mfma_f32_16x16x32_bf16 v[0:3], v[200:203], v[168:171], v[0:3]
	v_mfma_f32_16x16x32_bf16 v[52:55], v[180:183], v[128:131], v[52:55]
	v_mfma_f32_16x16x32_bf16 v[48:51], v[204:207], v[128:131], v[48:51]
	v_mfma_f32_16x16x32_bf16 v[36:39], v[180:183], v[144:147], v[36:39]
	v_mfma_f32_16x16x32_bf16 v[32:35], v[204:207], v[144:147], v[32:35]
	v_mfma_f32_16x16x32_bf16 v[20:23], v[180:183], v[164:167], v[20:23]
	v_mfma_f32_16x16x32_bf16 v[16:19], v[204:207], v[164:167], v[16:19]
	v_mfma_f32_16x16x32_bf16 v[4:7], v[180:183], v[172:175], v[4:7]
	v_mfma_f32_16x16x32_bf16 v[0:3], v[204:207], v[172:175], v[0:3]
	s_setprio 0
	s_add_i32 s54, 0, 0x18000
	v_add_u32_e32 v76, s54, v241
	s_barrier
	ds_read_b128 v[64:67], v76
	ds_read_b128 v[68:71], v76 offset:1024
	ds_read_b128 v[72:75], v76 offset:2048
	ds_read_b128 v[76:79], v76 offset:3072
	s_add_u32 s38, s38, 0x80000
	s_addc_u32 s39, s39, 0
	s_mov_b32 m0, s45
	v_lshl_add_u64 v[144:145], s[38:39], 0, v[184:185]
	ds_read_b128 v[124:127], v244 offset:32768
	ds_read_b128 v[128:131], v244 offset:33792
	ds_read_b128 v[140:143], v244 offset:34816
	ds_read_b128 v[160:163], v244 offset:35840
	ds_read_b128 v[164:167], v244 offset:36864
	ds_read_b128 v[168:171], v244 offset:37888
	ds_read_b128 v[172:175], v244 offset:38912
	ds_read_b128 v[176:179], v244 offset:39936
	global_load_lds_dwordx4 v[144:145], off
	v_lshl_add_u64 v[144:145], s[38:39], 0, v[186:187]
	s_mov_b32 m0, s46
	s_nop 0
	global_load_lds_dwordx4 v[144:145], off
	s_waitcnt lgkmcnt(8)
	s_barrier
	s_waitcnt lgkmcnt(0)
	s_setprio 1
	s_waitcnt lgkmcnt(0)
	v_mfma_f32_16x16x32_bf16 v[144:147], v[64:67], v[124:127], v[156:159]
	v_mfma_f32_16x16x32_bf16 v[156:159], v[68:71], v[128:131], v[144:147]
	v_mfma_f32_16x16x32_bf16 v[144:147], v[72:75], v[124:127], v[152:155]
	v_mfma_f32_16x16x32_bf16 v[136:139], v[64:67], v[140:143], v[136:139]
	v_mfma_f32_16x16x32_bf16 v[132:135], v[72:75], v[140:143], v[132:135]
	v_mfma_f32_16x16x32_bf16 v[120:123], v[64:67], v[164:167], v[120:123]
	v_mfma_f32_16x16x32_bf16 v[116:119], v[72:75], v[164:167], v[116:119]
	v_mfma_f32_16x16x32_bf16 v[104:107], v[64:67], v[172:175], v[104:107]
	v_mfma_f32_16x16x32_bf16 v[100:103], v[72:75], v[172:175], v[100:103]
	v_mfma_f32_16x16x32_bf16 v[152:155], v[76:79], v[128:131], v[144:147]
	v_mfma_f32_16x16x32_bf16 v[136:139], v[68:71], v[160:163], v[136:139]
	v_mfma_f32_16x16x32_bf16 v[132:135], v[76:79], v[160:163], v[132:135]
	v_mfma_f32_16x16x32_bf16 v[120:123], v[68:71], v[168:171], v[120:123]
	v_mfma_f32_16x16x32_bf16 v[116:119], v[76:79], v[168:171], v[116:119]
	v_mfma_f32_16x16x32_bf16 v[104:107], v[68:71], v[176:179], v[104:107]
	v_mfma_f32_16x16x32_bf16 v[100:103], v[76:79], v[176:179], v[100:103]
	s_setprio 0
	s_barrier
	s_add_i32 s38, 0, 0x1c000
	v_add_u32_e32 v144, s38, v241
	s_add_i32 s39, s54, s41
	ds_read_b128 v[180:183], v144
	ds_read_b128 v[200:203], v144 offset:1024
	ds_read_b128 v[204:207], v144 offset:2048
	ds_read_b128 v[208:211], v144 offset:3072
	v_lshl_add_u64 v[144:145], v[212:213], 0, s[88:89]
	s_mov_b32 m0, s39
	s_nop 0
	global_load_lds_dwordx4 v[144:145], off
	v_lshl_add_u64 v[144:145], v[214:215], 0, s[88:89]
	s_add_i32 m0, s39, 0x2000
	s_nop 0
	global_load_lds_dwordx4 v[144:145], off
	s_barrier
	s_waitcnt lgkmcnt(0)
	s_setprio 1
	s_waitcnt lgkmcnt(0)
	v_mfma_f32_16x16x32_bf16 v[144:147], v[180:183], v[124:127], v[148:151]
	v_mfma_f32_16x16x32_bf16 v[80:83], v[204:207], v[124:127], v[80:83]
	v_mfma_f32_16x16x32_bf16 v[148:151], v[200:203], v[128:131], v[144:147]
	v_mfma_f32_16x16x32_bf16 v[144:147], v[208:211], v[128:131], v[80:83]
	v_mfma_f32_16x16x32_bf16 v[80:83], v[180:183], v[140:143], v[84:87]
	v_mfma_f32_16x16x32_bf16 v[128:131], v[200:203], v[160:163], v[80:83]
	v_mfma_f32_16x16x32_bf16 v[80:83], v[204:207], v[140:143], v[88:91]
	v_mfma_f32_16x16x32_bf16 v[124:127], v[208:211], v[160:163], v[80:83]
	v_mfma_f32_16x16x32_bf16 v[80:83], v[180:183], v[164:167], v[112:115]
	v_mfma_f32_16x16x32_bf16 v[112:115], v[200:203], v[168:171], v[80:83]
	v_mfma_f32_16x16x32_bf16 v[80:83], v[204:207], v[164:167], v[108:111]
	v_mfma_f32_16x16x32_bf16 v[108:111], v[208:211], v[168:171], v[80:83]
	v_mfma_f32_16x16x32_bf16 v[80:83], v[180:183], v[172:175], v[96:99]
	v_mfma_f32_16x16x32_bf16 v[96:99], v[200:203], v[176:179], v[80:83]
	v_mfma_f32_16x16x32_bf16 v[80:83], v[204:207], v[172:175], v[92:95]
	v_mfma_f32_16x16x32_bf16 v[92:95], v[208:211], v[176:179], v[80:83]
	s_setprio 0
	s_mov_b32 m0, s47
	v_lshl_add_u64 v[176:177], v[216:217], 0, s[88:89]
	s_barrier
	s_nop 2
	ds_read_b128 v[80:83], v244 offset:49152
	ds_read_b128 v[84:87], v244 offset:50176
	ds_read_b128 v[88:91], v244 offset:51200
	ds_read_b128 v[140:143], v244 offset:52224
	ds_read_b128 v[160:163], v244 offset:53248
	ds_read_b128 v[164:167], v244 offset:54272
	ds_read_b128 v[168:171], v244 offset:55296
	ds_read_b128 v[172:175], v244 offset:56320
	global_load_lds_dwordx4 v[176:177], off
	v_lshl_add_u64 v[176:177], v[218:219], 0, s[88:89]
	s_mov_b32 m0, s48
	s_nop 0
	global_load_lds_dwordx4 v[176:177], off
	s_barrier
	s_waitcnt lgkmcnt(0)
	s_setprio 1
	s_waitcnt lgkmcnt(0)
	v_mfma_f32_16x16x32_bf16 v[60:63], v[64:67], v[80:83], v[60:63]
	v_mfma_f32_16x16x32_bf16 v[56:59], v[72:75], v[80:83], v[56:59]
	v_mfma_f32_16x16x32_bf16 v[44:47], v[64:67], v[88:91], v[44:47]
	v_mfma_f32_16x16x32_bf16 v[40:43], v[72:75], v[88:91], v[40:43]
	v_mfma_f32_16x16x32_bf16 v[28:31], v[64:67], v[160:163], v[28:31]
	v_mfma_f32_16x16x32_bf16 v[24:27], v[72:75], v[160:163], v[24:27]
	v_mfma_f32_16x16x32_bf16 v[12:15], v[64:67], v[168:171], v[12:15]
	v_mfma_f32_16x16x32_bf16 v[8:11], v[72:75], v[168:171], v[8:11]
	v_mfma_f32_16x16x32_bf16 v[60:63], v[68:71], v[84:87], v[60:63]
	v_mfma_f32_16x16x32_bf16 v[56:59], v[76:79], v[84:87], v[56:59]
	v_mfma_f32_16x16x32_bf16 v[44:47], v[68:71], v[140:143], v[44:47]
	v_mfma_f32_16x16x32_bf16 v[40:43], v[76:79], v[140:143], v[40:43]
	v_mfma_f32_16x16x32_bf16 v[28:31], v[68:71], v[164:167], v[28:31]
	v_mfma_f32_16x16x32_bf16 v[24:27], v[76:79], v[164:167], v[24:27]
	v_mfma_f32_16x16x32_bf16 v[12:15], v[68:71], v[172:175], v[12:15]
	v_mfma_f32_16x16x32_bf16 v[8:11], v[76:79], v[172:175], v[8:11]
	s_setprio 0
	s_barrier
	s_add_u32 s2, s2, 0x80080
	s_addc_u32 s3, s3, 0
	s_add_i32 s38, s38, s41
	v_lshl_add_u64 v[64:65], s[2:3], 0, v[188:189]
	s_mov_b32 m0, s38
	s_nop 0
	global_load_lds_dwordx4 v[64:65], off
	v_lshl_add_u64 v[64:65], s[2:3], 0, v[194:195]
	s_add_i32 m0, s38, 0x2000
	s_nop 0
	global_load_lds_dwordx4 v[64:65], off
	s_waitcnt vmcnt(6)
	s_barrier
	s_setprio 1
	v_mfma_f32_16x16x32_bf16 v[52:55], v[180:183], v[80:83], v[52:55]
	v_mfma_f32_16x16x32_bf16 v[48:51], v[204:207], v[80:83], v[48:51]
	v_mfma_f32_16x16x32_bf16 v[36:39], v[180:183], v[88:91], v[36:39]
	v_mfma_f32_16x16x32_bf16 v[32:35], v[204:207], v[88:91], v[32:35]
	v_mfma_f32_16x16x32_bf16 v[20:23], v[180:183], v[160:163], v[20:23]
	v_mfma_f32_16x16x32_bf16 v[16:19], v[204:207], v[160:163], v[16:19]
	v_mfma_f32_16x16x32_bf16 v[4:7], v[180:183], v[168:171], v[4:7]
	v_mfma_f32_16x16x32_bf16 v[0:3], v[204:207], v[168:171], v[0:3]
	v_mfma_f32_16x16x32_bf16 v[52:55], v[200:203], v[84:87], v[52:55]
	v_mfma_f32_16x16x32_bf16 v[48:51], v[208:211], v[84:87], v[48:51]
	v_mfma_f32_16x16x32_bf16 v[36:39], v[200:203], v[140:143], v[36:39]
	v_mfma_f32_16x16x32_bf16 v[32:35], v[208:211], v[140:143], v[32:35]
	v_mfma_f32_16x16x32_bf16 v[20:23], v[200:203], v[164:167], v[20:23]
	v_mfma_f32_16x16x32_bf16 v[16:19], v[208:211], v[164:167], v[16:19]
	v_mfma_f32_16x16x32_bf16 v[4:7], v[200:203], v[172:175], v[4:7]
	v_mfma_f32_16x16x32_bf16 v[0:3], v[208:211], v[172:175], v[0:3]
	s_setprio 0
	s_add_i32 s53, s53, 2
	s_add_u32 s33, s33, 0x100
	s_addc_u32 s52, s52, 0
	s_add_u32 s8, s8, 0x100
	s_addc_u32 s9, s9, 0
	s_cmp_gt_u32 s53, 29
	s_barrier
	s_cbranch_scc0 .LBB0_1332
	v_mov_b32_e32 v64, 1.0
	v_mov_b32_e32 v65, 1.0
	v_mov_b32_e32 v66, 1.0
	v_mov_b32_e32 v67, 1.0
	v_mov_b32_e32 v68, 1.0
	v_mov_b32_e32 v69, 1.0
	v_mov_b32_e32 v70, 1.0
	v_mov_b32_e32 v71, 1.0
	s_mul_i32 s0, s44, 0x1e00
	v_add_u32_e32 v245, s0, v243
	v_cndmask_b32_e64 v64, 0, 1, s[22:23]
	v_min_i32_e32 v218, 0x1feff, v245
	v_min_i32_e32 v216, 0x1fcff, v245
	v_min_i32_e32 v214, 0x1faff, v245
	v_min_i32_e32 v210, 0x1f8ff, v245
	v_min_i32_e32 v208, 0x1f6ff, v245
	v_min_i32_e32 v204, 0x1f4ff, v245
	v_min_i32_e32 v202, 0x1f2ff, v245
	v_min_i32_e32 v200, 0x1f0ff, v245
	v_cmp_ne_u32_e64 s[8:9], 1, v64
	s_andn2_b64 vcc, exec, s[22:23]
	v_ashrrev_i32_e32 v219, 31, v218
	v_ashrrev_i32_e32 v217, 31, v216
	v_ashrrev_i32_e32 v215, 31, v214
	v_ashrrev_i32_e32 v211, 31, v210
	v_ashrrev_i32_e32 v209, 31, v208
	v_ashrrev_i32_e32 v205, 31, v204
	v_ashrrev_i32_e32 v203, 31, v202
	v_ashrrev_i32_e32 v201, 31, v200
	s_cbranch_vccnz .LBB0_1335
	v_lshl_add_u64 v[66:67], v[216:217], 4, s[16:17]
	v_lshl_add_u64 v[64:65], v[218:219], 4, s[16:17]
	v_add_co_u32_e32 v66, vcc, 0x2000, v66
	v_lshl_add_u64 v[68:69], v[202:203], 4, s[16:17]
	s_nop 0
	v_addc_co_u32_e32 v67, vcc, 0, v67, vcc
	global_load_dwordx4 v[88:91], v[64:65], off nt
	global_load_dwordx4 v[76:79], v[66:67], off nt
	v_lshl_add_u64 v[64:65], v[214:215], 4, s[16:17]
	v_add_co_u32_e32 v64, vcc, 0x4000, v64
	v_lshl_add_u64 v[66:67], v[210:211], 4, s[16:17]
	s_nop 0
	v_addc_co_u32_e32 v65, vcc, 0, v65, vcc
	v_add_co_u32_e32 v66, vcc, 0x6000, v66
	v_lshl_add_u64 v[70:71], v[200:201], 4, s[16:17]
	s_nop 0
	v_addc_co_u32_e32 v67, vcc, 0, v67, vcc
	global_load_dwordx4 v[84:87], v[64:65], off nt
	global_load_dwordx4 v[72:75], v[66:67], off nt
	v_lshl_add_u64 v[64:65], v[208:209], 4, s[16:17]
	v_add_co_u32_e32 v64, vcc, 0x8000, v64
	v_lshl_add_u64 v[66:67], v[204:205], 4, s[16:17]
	s_nop 0
	v_addc_co_u32_e32 v65, vcc, 0, v65, vcc
	v_add_co_u32_e32 v66, vcc, 0xa000, v66
	s_nop 1
	v_addc_co_u32_e32 v67, vcc, 0, v67, vcc
	v_add_co_u32_e32 v68, vcc, 0xc000, v68
	global_load_dwordx4 v[80:83], v[64:65], off nt
	s_nop 0
	global_load_dwordx4 v[64:67], v[66:67], off nt
	v_addc_co_u32_e32 v69, vcc, 0, v69, vcc
	v_add_co_u32_e32 v140, vcc, 0xe000, v70
	s_nop 1
	v_addc_co_u32_e32 v141, vcc, 0, v71, vcc
	global_load_dwordx4 v[68:71], v[68:69], off nt
	s_nop 0
	global_load_dwordx4 v[140:143], v[140:141], off nt
	s_branch .LBB0_1336

	.amdhsa_kernel _Z10hybrid_fwd6Params
		.amdhsa_group_segment_fixed_size 0
		.amdhsa_private_segment_fixed_size 0
		.amdhsa_kernarg_size 392
		.amdhsa_user_sgpr_count 2
		.amdhsa_user_sgpr_dispatch_ptr 0
		.amdhsa_user_sgpr_queue_ptr 0
		.amdhsa_user_sgpr_kernarg_segment_ptr 1
		.amdhsa_user_sgpr_dispatch_id 0
		.amdhsa_user_sgpr_kernarg_preload_length 0
		.amdhsa_user_sgpr_kernarg_preload_offset 0
		.amdhsa_user_sgpr_private_segment_size 0
		.amdhsa_uses_dynamic_stack 0
		.amdhsa_enable_private_segment 0
		.amdhsa_system_sgpr_workgroup_id_x 1
		.amdhsa_system_sgpr_workgroup_id_y 0
		.amdhsa_system_sgpr_workgroup_id_z 0
		.amdhsa_system_sgpr_workgroup_info 0
		.amdhsa_system_vgpr_workitem_id 2
		.amdhsa_next_free_vgpr 256
		.amdhsa_next_free_sgpr 102
		.amdhsa_accum_offset 256
		.amdhsa_reserve_vcc 1
		.amdhsa_float_round_mode_32 0
		.amdhsa_float_round_mode_16_64 0
		.amdhsa_float_denorm_mode_32 3
		.amdhsa_float_denorm_mode_16_64 3
		.amdhsa_dx10_clamp 1
		.amdhsa_ieee_mode 1
		.amdhsa_fp16_overflow 0
		.amdhsa_tg_split 0
		.amdhsa_exception_fp_ieee_invalid_op 0
		.amdhsa_exception_fp_denorm_src 0
		.amdhsa_exception_fp_ieee_div_zero 0
		.amdhsa_exception_fp_ieee_overflow 0
		.amdhsa_exception_fp_ieee_underflow 0
		.amdhsa_exception_fp_ieee_inexact 0
		.amdhsa_exception_int_div_zero 0
	.end_amdhsa_kernel

amdhsa.kernels:
  - .agpr_count:     0
    .args:
      - .offset:         0
        .size:           136
        .value_kind:     by_value
      - .offset:         136
        .size:           4
        .value_kind:     hidden_block_count_x
      - .offset:         140
        .size:           4
        .value_kind:     hidden_block_count_y
      - .offset:         144
        .size:           4
        .value_kind:     hidden_block_count_z
      - .offset:         148
        .size:           2
        .value_kind:     hidden_group_size_x
      - .offset:         150
        .size:           2
        .value_kind:     hidden_group_size_y
      - .offset:         152
        .size:           2
        .value_kind:     hidden_group_size_z
      - .offset:         154
        .size:           2
        .value_kind:     hidden_remainder_x
      - .offset:         156
        .size:           2
        .value_kind:     hidden_remainder_y
      - .offset:         158
        .size:           2
        .value_kind:     hidden_remainder_z
      - .offset:         176
        .size:           8
        .value_kind:     hidden_global_offset_x
      - .offset:         184
        .size:           8
        .value_kind:     hidden_global_offset_y
      - .offset:         192
        .size:           8
        .value_kind:     hidden_global_offset_z
      - .offset:         200
        .size:           2
        .value_kind:     hidden_grid_dims
      - .offset:         224
        .size:           8
        .value_kind:     hidden_multigrid_sync_arg
      - .offset:         256
        .size:           4
        .value_kind:     hidden_dynamic_lds_size
    .group_segment_fixed_size: 0
    .kernarg_segment_align: 8
    .kernarg_segment_size: 392
    .language:       OpenCL C
    .language_version:
      - 2
      - 0
    .max_flat_workgroup_size: 512
    .name:           _Z10hybrid_fwd6Params
    .private_segment_fixed_size: 0
    .sgpr_count:     108
    .sgpr_spill_count: 50
    .symbol:         _Z10hybrid_fwd6Params.kd
    .uniform_work_group_size: 1
    .uses_dynamic_stack: false
    .vgpr_count:     256
    .vgpr_spill_count: 0
    .wavefront_size: 64
